# v25 combination + GEMM K-loops: closing barrier of each MFMA block taken 2 MFMAs early with s_setprio 2 for the tail MFMAs
# speedup vs baseline: 1.0101x; 1.0049x over previous
.LBB0_291:
	s_ashr_i32 s5, s4, 31
	s_lshl_b64 s[28:29], s[4:5], 20
	s_add_u32 s28, s14, s28
	s_addc_u32 s29, s15, s29
	s_and_b64 s[34:35], s[22:23], exec
	s_cselect_b32 s5, s29, s37
	s_cselect_b32 s8, s28, s36
	s_ashr_i32 s19, s18, 31
	s_lshl_b64 s[34:35], s[18:19], 20
	v_readlane_b32 s19, v245, 38
	s_add_u32 s34, s19, s34
	v_readlane_b32 s19, v245, 39
	s_addc_u32 s35, s19, s35
	s_and_b64 s[44:45], s[22:23], exec
	s_cselect_b32 s19, s35, s43
	s_cselect_b32 s21, s34, s42
	s_add_u32 s36, s36, 0x80080
	s_addc_u32 s37, s37, 0
	s_add_u32 s41, s42, 0x100
	s_addc_u32 s46, s43, 0
	s_mov_b32 s47, -2
	s_waitcnt vmcnt(0) lgkmcnt(0)
	s_add_u32 s42, s36, 0xfff80080
	s_addc_u32 s43, s37, -1
	s_add_i32 s48, 0, 0x10000
	s_cmp_eq_u32 s47, 28
	s_cselect_b32 s45, s5, s43
	s_cselect_b32 s44, s8, s42
	s_cselect_b32 s43, s19, s46
	s_cselect_b32 s42, s21, s41
	s_add_i32 s50, 0, 0x14000
	v_add_u32_e32 v158, s48, v147
	v_add_u32_e32 v162, s50, v147
	ds_read_b128 v[130:133], v158
	ds_read_b128 v[134:137], v158 offset:1024
	ds_read_b128 v[152:155], v158 offset:2048
	ds_read_b128 v[158:161], v158 offset:3072
	ds_read_b128 v[164:167], v162
	ds_read_b128 v[180:183], v162 offset:1024
	ds_read_b128 v[184:187], v162 offset:2048
	ds_read_b128 v[188:191], v162 offset:3072
	v_lshl_add_u64 v[168:169], s[36:37], 0, v[148:149]
	s_add_i32 m0, s11, 0xc000
	ds_read_b128 v[192:195], v157
	ds_read_b128 v[196:199], v157 offset:1024
	ds_read_b128 v[200:203], v157 offset:2048
	ds_read_b128 v[204:207], v157 offset:3072
	ds_read_b128 v[208:211], v157 offset:4096
	ds_read_b128 v[212:215], v157 offset:5120
	ds_read_b128 v[216:219], v157 offset:6144
	ds_read_b128 v[220:223], v157 offset:7168
	global_load_lds_dwordx4 v[168:169], off
	v_lshl_add_u64 v[168:169], s[36:37], 0, v[150:151]
	s_add_i32 m0, s11, 0xe000
	s_nop 0
	global_load_lds_dwordx4 v[168:169], off
	s_waitcnt vmcnt(8)
	s_waitcnt lgkmcnt(0)
	s_barrier
	s_setprio 1
	s_waitcnt lgkmcnt(0)
	v_mfma_f32_16x16x32_bf16 v[126:129], v[130:133], v[192:195], 0
	v_mfma_f32_16x16x32_bf16 v[122:125], v[152:155], v[192:195], 0
	v_mfma_f32_16x16x32_bf16 v[110:113], v[130:133], v[200:203], 0
	v_mfma_f32_16x16x32_bf16 v[106:109], v[152:155], v[200:203], 0
	v_mfma_f32_16x16x32_bf16 v[94:97], v[130:133], v[208:211], 0
	v_mfma_f32_16x16x32_bf16 v[90:93], v[152:155], v[208:211], 0
	v_mfma_f32_16x16x32_bf16 v[78:81], v[130:133], v[216:219], 0
	v_mfma_f32_16x16x32_bf16 v[74:77], v[152:155], v[216:219], 0
	v_mfma_f32_16x16x32_bf16 v[126:129], v[134:137], v[196:199], v[126:129]
	v_mfma_f32_16x16x32_bf16 v[122:125], v[158:161], v[196:199], v[122:125]
	v_mfma_f32_16x16x32_bf16 v[110:113], v[134:137], v[204:207], v[110:113]
	v_mfma_f32_16x16x32_bf16 v[106:109], v[158:161], v[204:207], v[106:109]
	v_mfma_f32_16x16x32_bf16 v[94:97], v[134:137], v[212:215], v[94:97]
	v_mfma_f32_16x16x32_bf16 v[90:93], v[158:161], v[212:215], v[90:93]
	v_mfma_f32_16x16x32_bf16 v[78:81], v[134:137], v[220:223], v[78:81]
	v_mfma_f32_16x16x32_bf16 v[74:77], v[158:161], v[220:223], v[74:77]
	s_setprio 0
	s_setprio 1
	v_mfma_f32_16x16x32_bf16 v[118:121], v[164:167], v[192:195], 0
	v_mfma_f32_16x16x32_bf16 v[114:117], v[184:187], v[192:195], 0
	v_mfma_f32_16x16x32_bf16 v[102:105], v[164:167], v[200:203], 0
	v_mfma_f32_16x16x32_bf16 v[98:101], v[184:187], v[200:203], 0
	v_mfma_f32_16x16x32_bf16 v[86:89], v[164:167], v[208:211], 0
	v_mfma_f32_16x16x32_bf16 v[82:85], v[184:187], v[208:211], 0
	v_mfma_f32_16x16x32_bf16 v[70:73], v[164:167], v[216:219], 0
	v_mfma_f32_16x16x32_bf16 v[66:69], v[184:187], v[216:219], 0
	v_mfma_f32_16x16x32_bf16 v[118:121], v[180:183], v[196:199], v[118:121]
	v_mfma_f32_16x16x32_bf16 v[114:117], v[188:191], v[196:199], v[114:117]
	v_mfma_f32_16x16x32_bf16 v[102:105], v[180:183], v[204:207], v[102:105]
	v_mfma_f32_16x16x32_bf16 v[98:101], v[188:191], v[204:207], v[98:101]
	v_mfma_f32_16x16x32_bf16 v[86:89], v[180:183], v[212:215], v[86:89]
	v_mfma_f32_16x16x32_bf16 v[82:85], v[188:191], v[212:215], v[82:85]
	s_setprio 2
	s_barrier
	v_mfma_f32_16x16x32_bf16 v[70:73], v[180:183], v[220:223], v[70:73]
	v_mfma_f32_16x16x32_bf16 v[66:69], v[188:191], v[220:223], v[66:69]
	s_setprio 0
	s_add_i32 s48, s48, s9
	v_lshl_add_u64 v[168:169], s[42:43], 0, v[140:141]
	s_mov_b32 m0, s48
	ds_read_b128 v[192:195], v157 offset:16384
	ds_read_b128 v[196:199], v157 offset:17408
	ds_read_b128 v[200:203], v157 offset:18432
	ds_read_b128 v[204:207], v157 offset:19456
	ds_read_b128 v[208:211], v157 offset:20480
	ds_read_b128 v[212:215], v157 offset:21504
	ds_read_b128 v[216:219], v157 offset:22528
	ds_read_b128 v[220:223], v157 offset:23552
	global_load_lds_dwordx4 v[168:169], off
	s_add_i32 m0, s48, 0x2000
	s_add_u32 s48, s42, 0x80000
	v_lshl_add_u64 v[224:225], s[42:43], 0, v[144:145]
	s_addc_u32 s49, s43, 0
	s_add_i32 s50, s50, s9
	global_load_lds_dwordx4 v[224:225], off
	v_lshl_add_u64 v[226:227], s[48:49], 0, v[140:141]
	s_mov_b32 m0, s50
	v_lshl_add_u64 v[228:229], s[44:45], 0, v[142:143]
	global_load_lds_dwordx4 v[226:227], off
	v_lshl_add_u64 v[226:227], s[48:49], 0, v[144:145]
	s_add_i32 m0, s50, 0x2000
	s_nop 0
	global_load_lds_dwordx4 v[226:227], off
	v_lshl_add_u64 v[226:227], s[44:45], 0, v[138:139]
	s_mov_b32 m0, s11
	s_nop 0
	global_load_lds_dwordx4 v[226:227], off
	s_mov_b32 m0, s13
	s_nop 0
	global_load_lds_dwordx4 v[228:229], off
	s_waitcnt vmcnt(8)
	s_waitcnt lgkmcnt(0)
	s_barrier
	s_setprio 1
	s_waitcnt lgkmcnt(0)
	v_mfma_f32_16x16x32_bf16 v[62:65], v[130:133], v[192:195], 0
	v_mfma_f32_16x16x32_bf16 v[58:61], v[152:155], v[192:195], 0
	v_mfma_f32_16x16x32_bf16 v[46:49], v[130:133], v[200:203], 0
	v_mfma_f32_16x16x32_bf16 v[42:45], v[152:155], v[200:203], 0
	v_mfma_f32_16x16x32_bf16 v[30:33], v[130:133], v[208:211], 0
	v_mfma_f32_16x16x32_bf16 v[26:29], v[152:155], v[208:211], 0
	v_mfma_f32_16x16x32_bf16 v[14:17], v[130:133], v[216:219], 0
	v_mfma_f32_16x16x32_bf16 v[10:13], v[152:155], v[216:219], 0
	v_mfma_f32_16x16x32_bf16 v[62:65], v[134:137], v[196:199], v[62:65]
	v_mfma_f32_16x16x32_bf16 v[58:61], v[158:161], v[196:199], v[58:61]
	v_mfma_f32_16x16x32_bf16 v[46:49], v[134:137], v[204:207], v[46:49]
	v_mfma_f32_16x16x32_bf16 v[42:45], v[158:161], v[204:207], v[42:45]
	v_mfma_f32_16x16x32_bf16 v[30:33], v[134:137], v[212:215], v[30:33]
	v_mfma_f32_16x16x32_bf16 v[26:29], v[158:161], v[212:215], v[26:29]
	v_mfma_f32_16x16x32_bf16 v[14:17], v[134:137], v[220:223], v[14:17]
	v_mfma_f32_16x16x32_bf16 v[10:13], v[158:161], v[220:223], v[10:13]
	s_setprio 0
	s_setprio 1
	v_mfma_f32_16x16x32_bf16 v[54:57], v[164:167], v[192:195], 0
	v_mfma_f32_16x16x32_bf16 v[50:53], v[184:187], v[192:195], 0
	v_mfma_f32_16x16x32_bf16 v[38:41], v[164:167], v[200:203], 0
	v_mfma_f32_16x16x32_bf16 v[34:37], v[184:187], v[200:203], 0
	v_mfma_f32_16x16x32_bf16 v[22:25], v[164:167], v[208:211], 0
	v_mfma_f32_16x16x32_bf16 v[18:21], v[184:187], v[208:211], 0
	v_mfma_f32_16x16x32_bf16 v[6:9], v[164:167], v[216:219], 0
	v_mfma_f32_16x16x32_bf16 v[2:5], v[184:187], v[216:219], 0
	v_mfma_f32_16x16x32_bf16 v[54:57], v[180:183], v[196:199], v[54:57]
	v_mfma_f32_16x16x32_bf16 v[50:53], v[188:191], v[196:199], v[50:53]
	v_mfma_f32_16x16x32_bf16 v[38:41], v[180:183], v[204:207], v[38:41]
	v_mfma_f32_16x16x32_bf16 v[34:37], v[188:191], v[204:207], v[34:37]
	v_mfma_f32_16x16x32_bf16 v[22:25], v[180:183], v[212:215], v[22:25]
	v_mfma_f32_16x16x32_bf16 v[18:21], v[188:191], v[212:215], v[18:21]
	s_setprio 2
	s_barrier
	v_mfma_f32_16x16x32_bf16 v[6:9], v[180:183], v[220:223], v[6:9]
	v_mfma_f32_16x16x32_bf16 v[2:5], v[188:191], v[220:223], v[2:5]
	s_setprio 0
	s_add_i32 s48, 0, 0x18000
	s_add_i32 s49, 0, 0x1c000
	v_add_u32_e32 v158, s48, v147
	v_add_u32_e32 v162, s49, v147
	ds_read_b128 v[130:133], v158
	ds_read_b128 v[134:137], v158 offset:1024
	ds_read_b128 v[152:155], v158 offset:2048
	ds_read_b128 v[158:161], v158 offset:3072
	ds_read_b128 v[164:167], v162
	ds_read_b128 v[180:183], v162 offset:1024
	ds_read_b128 v[184:187], v162 offset:2048
	ds_read_b128 v[188:191], v162 offset:3072
	s_add_u32 s44, s44, 0x80000
	s_addc_u32 s45, s45, 0
	s_mov_b32 m0, s20
	v_lshl_add_u64 v[230:231], s[44:45], 0, v[138:139]
	ds_read_b128 v[192:195], v157 offset:32768
	ds_read_b128 v[196:199], v157 offset:33792
	ds_read_b128 v[200:203], v157 offset:34816
	ds_read_b128 v[204:207], v157 offset:35840
	ds_read_b128 v[208:211], v157 offset:36864
	ds_read_b128 v[212:215], v157 offset:37888
	ds_read_b128 v[216:219], v157 offset:38912
	ds_read_b128 v[220:223], v157 offset:39936
	global_load_lds_dwordx4 v[230:231], off
	v_lshl_add_u64 v[230:231], s[44:45], 0, v[142:143]
	s_mov_b32 m0, s25
	s_nop 0
	global_load_lds_dwordx4 v[230:231], off
	s_waitcnt vmcnt(8)
	s_waitcnt lgkmcnt(0)
	s_barrier
	s_setprio 1
	s_waitcnt lgkmcnt(0)
	v_mfma_f32_16x16x32_bf16 v[126:129], v[130:133], v[192:195], v[126:129]
	v_mfma_f32_16x16x32_bf16 v[122:125], v[152:155], v[192:195], v[122:125]
	v_mfma_f32_16x16x32_bf16 v[110:113], v[130:133], v[200:203], v[110:113]
	v_mfma_f32_16x16x32_bf16 v[106:109], v[152:155], v[200:203], v[106:109]
	v_mfma_f32_16x16x32_bf16 v[94:97], v[130:133], v[208:211], v[94:97]
	v_mfma_f32_16x16x32_bf16 v[90:93], v[152:155], v[208:211], v[90:93]
	v_mfma_f32_16x16x32_bf16 v[78:81], v[130:133], v[216:219], v[78:81]
	v_mfma_f32_16x16x32_bf16 v[74:77], v[152:155], v[216:219], v[74:77]
	v_mfma_f32_16x16x32_bf16 v[126:129], v[134:137], v[196:199], v[126:129]
	v_mfma_f32_16x16x32_bf16 v[122:125], v[158:161], v[196:199], v[122:125]
	v_mfma_f32_16x16x32_bf16 v[110:113], v[134:137], v[204:207], v[110:113]
	v_mfma_f32_16x16x32_bf16 v[106:109], v[158:161], v[204:207], v[106:109]
	v_mfma_f32_16x16x32_bf16 v[94:97], v[134:137], v[212:215], v[94:97]
	v_mfma_f32_16x16x32_bf16 v[90:93], v[158:161], v[212:215], v[90:93]
	v_mfma_f32_16x16x32_bf16 v[78:81], v[134:137], v[220:223], v[78:81]
	v_mfma_f32_16x16x32_bf16 v[74:77], v[158:161], v[220:223], v[74:77]
	s_setprio 0
	s_setprio 1
	v_mfma_f32_16x16x32_bf16 v[118:121], v[164:167], v[192:195], v[118:121]
	v_mfma_f32_16x16x32_bf16 v[114:117], v[184:187], v[192:195], v[114:117]
	v_mfma_f32_16x16x32_bf16 v[102:105], v[164:167], v[200:203], v[102:105]
	v_mfma_f32_16x16x32_bf16 v[98:101], v[184:187], v[200:203], v[98:101]
	v_mfma_f32_16x16x32_bf16 v[86:89], v[164:167], v[208:211], v[86:89]
	v_mfma_f32_16x16x32_bf16 v[82:85], v[184:187], v[208:211], v[82:85]
	v_mfma_f32_16x16x32_bf16 v[70:73], v[164:167], v[216:219], v[70:73]
	v_mfma_f32_16x16x32_bf16 v[66:69], v[184:187], v[216:219], v[66:69]
	v_mfma_f32_16x16x32_bf16 v[118:121], v[180:183], v[196:199], v[118:121]
	v_mfma_f32_16x16x32_bf16 v[114:117], v[188:191], v[196:199], v[114:117]
	v_mfma_f32_16x16x32_bf16 v[102:105], v[180:183], v[204:207], v[102:105]
	v_mfma_f32_16x16x32_bf16 v[98:101], v[188:191], v[204:207], v[98:101]
	v_mfma_f32_16x16x32_bf16 v[86:89], v[180:183], v[212:215], v[86:89]
	v_mfma_f32_16x16x32_bf16 v[82:85], v[188:191], v[212:215], v[82:85]
	s_setprio 2
	s_barrier
	v_mfma_f32_16x16x32_bf16 v[70:73], v[180:183], v[220:223], v[70:73]
	v_mfma_f32_16x16x32_bf16 v[66:69], v[188:191], v[220:223], v[66:69]
	s_setprio 0
	s_add_i32 s44, s48, s9
	v_lshl_add_u64 v[168:169], v[168:169], 0, s[6:7]
	s_mov_b32 m0, s44
	ds_read_b128 v[192:195], v157 offset:49152
	ds_read_b128 v[196:199], v157 offset:50176
	ds_read_b128 v[200:203], v157 offset:51200
	ds_read_b128 v[204:207], v157 offset:52224
	ds_read_b128 v[208:211], v157 offset:53248
	ds_read_b128 v[212:215], v157 offset:54272
	ds_read_b128 v[216:219], v157 offset:55296
	ds_read_b128 v[220:223], v157 offset:56320
	global_load_lds_dwordx4 v[168:169], off
	s_add_i32 m0, s44, 0x2000
	s_add_u32 s42, s42, 0x80080
	v_lshl_add_u64 v[168:169], v[224:225], 0, s[6:7]
	s_addc_u32 s43, s43, 0
	s_add_i32 s44, s49, s9
	global_load_lds_dwordx4 v[168:169], off
	v_lshl_add_u64 v[168:169], s[42:43], 0, v[140:141]
	s_mov_b32 m0, s44
	s_nop 0
	global_load_lds_dwordx4 v[168:169], off
	v_lshl_add_u64 v[168:169], s[42:43], 0, v[144:145]
	s_add_i32 m0, s44, 0x2000
	s_nop 0
	global_load_lds_dwordx4 v[168:169], off
	v_lshl_add_u64 v[168:169], v[226:227], 0, s[6:7]
	s_mov_b32 m0, s26
	s_nop 0
	global_load_lds_dwordx4 v[168:169], off
	v_lshl_add_u64 v[168:169], v[228:229], 0, s[6:7]
	s_mov_b32 m0, s27
	s_nop 0
	global_load_lds_dwordx4 v[168:169], off
	s_waitcnt vmcnt(8)
	s_waitcnt lgkmcnt(0)
	s_barrier
	s_setprio 1
	s_waitcnt lgkmcnt(0)
	v_mfma_f32_16x16x32_bf16 v[62:65], v[130:133], v[192:195], v[62:65]
	v_mfma_f32_16x16x32_bf16 v[58:61], v[152:155], v[192:195], v[58:61]
	v_mfma_f32_16x16x32_bf16 v[46:49], v[130:133], v[200:203], v[46:49]
	v_mfma_f32_16x16x32_bf16 v[42:45], v[152:155], v[200:203], v[42:45]
	v_mfma_f32_16x16x32_bf16 v[30:33], v[130:133], v[208:211], v[30:33]
	v_mfma_f32_16x16x32_bf16 v[26:29], v[152:155], v[208:211], v[26:29]
	v_mfma_f32_16x16x32_bf16 v[14:17], v[130:133], v[216:219], v[14:17]
	v_mfma_f32_16x16x32_bf16 v[10:13], v[152:155], v[216:219], v[10:13]
	v_mfma_f32_16x16x32_bf16 v[62:65], v[134:137], v[196:199], v[62:65]
	v_mfma_f32_16x16x32_bf16 v[58:61], v[158:161], v[196:199], v[58:61]
	v_mfma_f32_16x16x32_bf16 v[46:49], v[134:137], v[204:207], v[46:49]
	v_mfma_f32_16x16x32_bf16 v[42:45], v[158:161], v[204:207], v[42:45]
	v_mfma_f32_16x16x32_bf16 v[30:33], v[134:137], v[212:215], v[30:33]
	v_mfma_f32_16x16x32_bf16 v[26:29], v[158:161], v[212:215], v[26:29]
	v_mfma_f32_16x16x32_bf16 v[14:17], v[134:137], v[220:223], v[14:17]
	v_mfma_f32_16x16x32_bf16 v[10:13], v[158:161], v[220:223], v[10:13]
	s_setprio 0
	s_setprio 1
	v_mfma_f32_16x16x32_bf16 v[54:57], v[164:167], v[192:195], v[54:57]
	v_mfma_f32_16x16x32_bf16 v[50:53], v[184:187], v[192:195], v[50:53]
	v_mfma_f32_16x16x32_bf16 v[38:41], v[164:167], v[200:203], v[38:41]
	v_mfma_f32_16x16x32_bf16 v[34:37], v[184:187], v[200:203], v[34:37]
	v_mfma_f32_16x16x32_bf16 v[22:25], v[164:167], v[208:211], v[22:25]
	v_mfma_f32_16x16x32_bf16 v[18:21], v[184:187], v[208:211], v[18:21]
	v_mfma_f32_16x16x32_bf16 v[6:9], v[164:167], v[216:219], v[6:9]
	v_mfma_f32_16x16x32_bf16 v[2:5], v[184:187], v[216:219], v[2:5]
	v_mfma_f32_16x16x32_bf16 v[54:57], v[180:183], v[196:199], v[54:57]
	v_mfma_f32_16x16x32_bf16 v[50:53], v[188:191], v[196:199], v[50:53]
	v_mfma_f32_16x16x32_bf16 v[38:41], v[180:183], v[204:207], v[38:41]
	v_mfma_f32_16x16x32_bf16 v[34:37], v[188:191], v[204:207], v[34:37]
	v_mfma_f32_16x16x32_bf16 v[22:25], v[180:183], v[212:215], v[22:25]
	v_mfma_f32_16x16x32_bf16 v[18:21], v[188:191], v[212:215], v[18:21]
	s_setprio 2
	s_barrier
	v_mfma_f32_16x16x32_bf16 v[6:9], v[180:183], v[220:223], v[6:9]
	v_mfma_f32_16x16x32_bf16 v[2:5], v[188:191], v[220:223], v[2:5]
	s_setprio 0
	s_add_i32 s47, s47, 2
	s_add_u32 s36, s36, 0x100
	s_addc_u32 s37, s37, 0
	s_add_u32 s41, s41, 0x100
	s_addc_u32 s46, s46, 0
	s_cmp_gt_u32 s47, 29
.LBB0_292:
	s_add_u32 s42, s36, 0xfff80080
	s_addc_u32 s43, s37, -1
	s_add_i32 s48, 0, 0x10000
	s_cmp_eq_u32 s47, 28
	s_cselect_b32 s45, s5, s43
	s_cselect_b32 s44, s8, s42
	s_cselect_b32 s43, s19, s46
	s_cselect_b32 s42, s21, s41
	s_add_i32 s50, 0, 0x14000
	v_add_u32_e32 v158, s48, v147
	v_add_u32_e32 v162, s50, v147
	ds_read_b128 v[130:133], v158
	ds_read_b128 v[134:137], v158 offset:1024
	ds_read_b128 v[152:155], v158 offset:2048
	ds_read_b128 v[158:161], v158 offset:3072
	ds_read_b128 v[164:167], v162
	ds_read_b128 v[180:183], v162 offset:1024
	ds_read_b128 v[184:187], v162 offset:2048
	ds_read_b128 v[188:191], v162 offset:3072
	v_lshl_add_u64 v[168:169], s[36:37], 0, v[148:149]
	s_add_i32 m0, s11, 0xc000
	ds_read_b128 v[192:195], v157
	ds_read_b128 v[196:199], v157 offset:1024
	ds_read_b128 v[200:203], v157 offset:2048
	ds_read_b128 v[204:207], v157 offset:3072
	ds_read_b128 v[208:211], v157 offset:4096
	ds_read_b128 v[212:215], v157 offset:5120
	ds_read_b128 v[216:219], v157 offset:6144
	ds_read_b128 v[220:223], v157 offset:7168
	global_load_lds_dwordx4 v[168:169], off
	v_lshl_add_u64 v[168:169], s[36:37], 0, v[150:151]
	s_add_i32 m0, s11, 0xe000
	s_nop 0
	global_load_lds_dwordx4 v[168:169], off
	s_waitcnt vmcnt(8)
	s_waitcnt lgkmcnt(0)
	s_barrier
	s_setprio 1
	s_waitcnt lgkmcnt(0)
	v_mfma_f32_16x16x32_bf16 v[126:129], v[130:133], v[192:195], v[126:129]
	v_mfma_f32_16x16x32_bf16 v[122:125], v[152:155], v[192:195], v[122:125]
	v_mfma_f32_16x16x32_bf16 v[110:113], v[130:133], v[200:203], v[110:113]
	v_mfma_f32_16x16x32_bf16 v[106:109], v[152:155], v[200:203], v[106:109]
	v_mfma_f32_16x16x32_bf16 v[94:97], v[130:133], v[208:211], v[94:97]
	v_mfma_f32_16x16x32_bf16 v[90:93], v[152:155], v[208:211], v[90:93]
	v_mfma_f32_16x16x32_bf16 v[78:81], v[130:133], v[216:219], v[78:81]
	v_mfma_f32_16x16x32_bf16 v[74:77], v[152:155], v[216:219], v[74:77]
	v_mfma_f32_16x16x32_bf16 v[126:129], v[134:137], v[196:199], v[126:129]
	v_mfma_f32_16x16x32_bf16 v[122:125], v[158:161], v[196:199], v[122:125]
	v_mfma_f32_16x16x32_bf16 v[110:113], v[134:137], v[204:207], v[110:113]
	v_mfma_f32_16x16x32_bf16 v[106:109], v[158:161], v[204:207], v[106:109]
	v_mfma_f32_16x16x32_bf16 v[94:97], v[134:137], v[212:215], v[94:97]
	v_mfma_f32_16x16x32_bf16 v[90:93], v[158:161], v[212:215], v[90:93]
	v_mfma_f32_16x16x32_bf16 v[78:81], v[134:137], v[220:223], v[78:81]
	v_mfma_f32_16x16x32_bf16 v[74:77], v[158:161], v[220:223], v[74:77]
	s_setprio 0
	s_setprio 1
	v_mfma_f32_16x16x32_bf16 v[118:121], v[164:167], v[192:195], v[118:121]
	v_mfma_f32_16x16x32_bf16 v[114:117], v[184:187], v[192:195], v[114:117]
	v_mfma_f32_16x16x32_bf16 v[102:105], v[164:167], v[200:203], v[102:105]
	v_mfma_f32_16x16x32_bf16 v[98:101], v[184:187], v[200:203], v[98:101]
	v_mfma_f32_16x16x32_bf16 v[86:89], v[164:167], v[208:211], v[86:89]
	v_mfma_f32_16x16x32_bf16 v[82:85], v[184:187], v[208:211], v[82:85]
	v_mfma_f32_16x16x32_bf16 v[70:73], v[164:167], v[216:219], v[70:73]
	v_mfma_f32_16x16x32_bf16 v[66:69], v[184:187], v[216:219], v[66:69]
	v_mfma_f32_16x16x32_bf16 v[118:121], v[180:183], v[196:199], v[118:121]
	v_mfma_f32_16x16x32_bf16 v[114:117], v[188:191], v[196:199], v[114:117]
	v_mfma_f32_16x16x32_bf16 v[102:105], v[180:183], v[204:207], v[102:105]
	v_mfma_f32_16x16x32_bf16 v[98:101], v[188:191], v[204:207], v[98:101]
	v_mfma_f32_16x16x32_bf16 v[86:89], v[180:183], v[212:215], v[86:89]
	v_mfma_f32_16x16x32_bf16 v[82:85], v[188:191], v[212:215], v[82:85]
	s_setprio 2
	s_barrier
	v_mfma_f32_16x16x32_bf16 v[70:73], v[180:183], v[220:223], v[70:73]
	v_mfma_f32_16x16x32_bf16 v[66:69], v[188:191], v[220:223], v[66:69]
	s_setprio 0
	s_add_i32 s48, s48, s9
	v_lshl_add_u64 v[168:169], s[42:43], 0, v[140:141]
	s_mov_b32 m0, s48
	ds_read_b128 v[192:195], v157 offset:16384
	ds_read_b128 v[196:199], v157 offset:17408
	ds_read_b128 v[200:203], v157 offset:18432
	ds_read_b128 v[204:207], v157 offset:19456
	ds_read_b128 v[208:211], v157 offset:20480
	ds_read_b128 v[212:215], v157 offset:21504
	ds_read_b128 v[216:219], v157 offset:22528
	ds_read_b128 v[220:223], v157 offset:23552
	global_load_lds_dwordx4 v[168:169], off
	s_add_i32 m0, s48, 0x2000
	s_add_u32 s48, s42, 0x80000
	v_lshl_add_u64 v[224:225], s[42:43], 0, v[144:145]
	s_addc_u32 s49, s43, 0
	s_add_i32 s50, s50, s9
	global_load_lds_dwordx4 v[224:225], off
	v_lshl_add_u64 v[226:227], s[48:49], 0, v[140:141]
	s_mov_b32 m0, s50
	v_lshl_add_u64 v[228:229], s[44:45], 0, v[142:143]
	global_load_lds_dwordx4 v[226:227], off
	v_lshl_add_u64 v[226:227], s[48:49], 0, v[144:145]
	s_add_i32 m0, s50, 0x2000
	s_nop 0
	global_load_lds_dwordx4 v[226:227], off
	v_lshl_add_u64 v[226:227], s[44:45], 0, v[138:139]
	s_mov_b32 m0, s11
	s_nop 0
	global_load_lds_dwordx4 v[226:227], off
	s_mov_b32 m0, s13
	s_nop 0
	global_load_lds_dwordx4 v[228:229], off
	s_waitcnt vmcnt(8)
	s_waitcnt lgkmcnt(0)
	s_barrier
	s_setprio 1
	s_waitcnt lgkmcnt(0)
	v_mfma_f32_16x16x32_bf16 v[62:65], v[130:133], v[192:195], v[62:65]
	v_mfma_f32_16x16x32_bf16 v[58:61], v[152:155], v[192:195], v[58:61]
	v_mfma_f32_16x16x32_bf16 v[46:49], v[130:133], v[200:203], v[46:49]
	v_mfma_f32_16x16x32_bf16 v[42:45], v[152:155], v[200:203], v[42:45]
	v_mfma_f32_16x16x32_bf16 v[30:33], v[130:133], v[208:211], v[30:33]
	v_mfma_f32_16x16x32_bf16 v[26:29], v[152:155], v[208:211], v[26:29]
	v_mfma_f32_16x16x32_bf16 v[14:17], v[130:133], v[216:219], v[14:17]
	v_mfma_f32_16x16x32_bf16 v[10:13], v[152:155], v[216:219], v[10:13]
	v_mfma_f32_16x16x32_bf16 v[62:65], v[134:137], v[196:199], v[62:65]
	v_mfma_f32_16x16x32_bf16 v[58:61], v[158:161], v[196:199], v[58:61]
	v_mfma_f32_16x16x32_bf16 v[46:49], v[134:137], v[204:207], v[46:49]
	v_mfma_f32_16x16x32_bf16 v[42:45], v[158:161], v[204:207], v[42:45]
	v_mfma_f32_16x16x32_bf16 v[30:33], v[134:137], v[212:215], v[30:33]
	v_mfma_f32_16x16x32_bf16 v[26:29], v[158:161], v[212:215], v[26:29]
	v_mfma_f32_16x16x32_bf16 v[14:17], v[134:137], v[220:223], v[14:17]
	v_mfma_f32_16x16x32_bf16 v[10:13], v[158:161], v[220:223], v[10:13]
	s_setprio 0
	s_setprio 1
	v_mfma_f32_16x16x32_bf16 v[54:57], v[164:167], v[192:195], v[54:57]
	v_mfma_f32_16x16x32_bf16 v[50:53], v[184:187], v[192:195], v[50:53]
	v_mfma_f32_16x16x32_bf16 v[38:41], v[164:167], v[200:203], v[38:41]
	v_mfma_f32_16x16x32_bf16 v[34:37], v[184:187], v[200:203], v[34:37]
	v_mfma_f32_16x16x32_bf16 v[22:25], v[164:167], v[208:211], v[22:25]
	v_mfma_f32_16x16x32_bf16 v[18:21], v[184:187], v[208:211], v[18:21]
	v_mfma_f32_16x16x32_bf16 v[6:9], v[164:167], v[216:219], v[6:9]
	v_mfma_f32_16x16x32_bf16 v[2:5], v[184:187], v[216:219], v[2:5]
	v_mfma_f32_16x16x32_bf16 v[54:57], v[180:183], v[196:199], v[54:57]
	v_mfma_f32_16x16x32_bf16 v[50:53], v[188:191], v[196:199], v[50:53]
	v_mfma_f32_16x16x32_bf16 v[38:41], v[180:183], v[204:207], v[38:41]
	v_mfma_f32_16x16x32_bf16 v[34:37], v[188:191], v[204:207], v[34:37]
	v_mfma_f32_16x16x32_bf16 v[22:25], v[180:183], v[212:215], v[22:25]
	v_mfma_f32_16x16x32_bf16 v[18:21], v[188:191], v[212:215], v[18:21]
	s_setprio 2
	s_barrier
	v_mfma_f32_16x16x32_bf16 v[6:9], v[180:183], v[220:223], v[6:9]
	v_mfma_f32_16x16x32_bf16 v[2:5], v[188:191], v[220:223], v[2:5]
	s_setprio 0
	s_add_i32 s48, 0, 0x18000
	s_add_i32 s49, 0, 0x1c000
	v_add_u32_e32 v158, s48, v147
	v_add_u32_e32 v162, s49, v147
	ds_read_b128 v[130:133], v158
	ds_read_b128 v[134:137], v158 offset:1024
	ds_read_b128 v[152:155], v158 offset:2048
	ds_read_b128 v[158:161], v158 offset:3072
	ds_read_b128 v[164:167], v162
	ds_read_b128 v[180:183], v162 offset:1024
	ds_read_b128 v[184:187], v162 offset:2048
	ds_read_b128 v[188:191], v162 offset:3072
	s_add_u32 s44, s44, 0x80000
	s_addc_u32 s45, s45, 0
	s_mov_b32 m0, s20
	v_lshl_add_u64 v[230:231], s[44:45], 0, v[138:139]
	ds_read_b128 v[192:195], v157 offset:32768
	ds_read_b128 v[196:199], v157 offset:33792
	ds_read_b128 v[200:203], v157 offset:34816
	ds_read_b128 v[204:207], v157 offset:35840
	ds_read_b128 v[208:211], v157 offset:36864
	ds_read_b128 v[212:215], v157 offset:37888
	ds_read_b128 v[216:219], v157 offset:38912
	ds_read_b128 v[220:223], v157 offset:39936
	global_load_lds_dwordx4 v[230:231], off
	v_lshl_add_u64 v[230:231], s[44:45], 0, v[142:143]
	s_mov_b32 m0, s25
	s_nop 0
	global_load_lds_dwordx4 v[230:231], off
	s_waitcnt vmcnt(8)
	s_waitcnt lgkmcnt(0)
	s_barrier
	s_setprio 1
	s_waitcnt lgkmcnt(0)
	v_mfma_f32_16x16x32_bf16 v[126:129], v[130:133], v[192:195], v[126:129]
	v_mfma_f32_16x16x32_bf16 v[122:125], v[152:155], v[192:195], v[122:125]
	v_mfma_f32_16x16x32_bf16 v[110:113], v[130:133], v[200:203], v[110:113]
	v_mfma_f32_16x16x32_bf16 v[106:109], v[152:155], v[200:203], v[106:109]
	v_mfma_f32_16x16x32_bf16 v[94:97], v[130:133], v[208:211], v[94:97]
	v_mfma_f32_16x16x32_bf16 v[90:93], v[152:155], v[208:211], v[90:93]
	v_mfma_f32_16x16x32_bf16 v[78:81], v[130:133], v[216:219], v[78:81]
	v_mfma_f32_16x16x32_bf16 v[74:77], v[152:155], v[216:219], v[74:77]
	v_mfma_f32_16x16x32_bf16 v[126:129], v[134:137], v[196:199], v[126:129]
	v_mfma_f32_16x16x32_bf16 v[122:125], v[158:161], v[196:199], v[122:125]
	v_mfma_f32_16x16x32_bf16 v[110:113], v[134:137], v[204:207], v[110:113]
	v_mfma_f32_16x16x32_bf16 v[106:109], v[158:161], v[204:207], v[106:109]
	v_mfma_f32_16x16x32_bf16 v[94:97], v[134:137], v[212:215], v[94:97]
	v_mfma_f32_16x16x32_bf16 v[90:93], v[158:161], v[212:215], v[90:93]
	v_mfma_f32_16x16x32_bf16 v[78:81], v[134:137], v[220:223], v[78:81]
	v_mfma_f32_16x16x32_bf16 v[74:77], v[158:161], v[220:223], v[74:77]
	s_setprio 0
	s_setprio 1
	v_mfma_f32_16x16x32_bf16 v[118:121], v[164:167], v[192:195], v[118:121]
	v_mfma_f32_16x16x32_bf16 v[114:117], v[184:187], v[192:195], v[114:117]
	v_mfma_f32_16x16x32_bf16 v[102:105], v[164:167], v[200:203], v[102:105]
	v_mfma_f32_16x16x32_bf16 v[98:101], v[184:187], v[200:203], v[98:101]
	v_mfma_f32_16x16x32_bf16 v[86:89], v[164:167], v[208:211], v[86:89]
	v_mfma_f32_16x16x32_bf16 v[82:85], v[184:187], v[208:211], v[82:85]
	v_mfma_f32_16x16x32_bf16 v[70:73], v[164:167], v[216:219], v[70:73]
	v_mfma_f32_16x16x32_bf16 v[66:69], v[184:187], v[216:219], v[66:69]
	v_mfma_f32_16x16x32_bf16 v[118:121], v[180:183], v[196:199], v[118:121]
	v_mfma_f32_16x16x32_bf16 v[114:117], v[188:191], v[196:199], v[114:117]
	v_mfma_f32_16x16x32_bf16 v[102:105], v[180:183], v[204:207], v[102:105]
	v_mfma_f32_16x16x32_bf16 v[98:101], v[188:191], v[204:207], v[98:101]
	v_mfma_f32_16x16x32_bf16 v[86:89], v[180:183], v[212:215], v[86:89]
	v_mfma_f32_16x16x32_bf16 v[82:85], v[188:191], v[212:215], v[82:85]
	s_setprio 2
	s_barrier
	v_mfma_f32_16x16x32_bf16 v[70:73], v[180:183], v[220:223], v[70:73]
	v_mfma_f32_16x16x32_bf16 v[66:69], v[188:191], v[220:223], v[66:69]
	s_setprio 0
	s_add_i32 s44, s48, s9
	v_lshl_add_u64 v[168:169], v[168:169], 0, s[6:7]
	s_mov_b32 m0, s44
	ds_read_b128 v[192:195], v157 offset:49152
	ds_read_b128 v[196:199], v157 offset:50176
	ds_read_b128 v[200:203], v157 offset:51200
	ds_read_b128 v[204:207], v157 offset:52224
	ds_read_b128 v[208:211], v157 offset:53248
	ds_read_b128 v[212:215], v157 offset:54272
	ds_read_b128 v[216:219], v157 offset:55296
	ds_read_b128 v[220:223], v157 offset:56320
	global_load_lds_dwordx4 v[168:169], off
	s_add_i32 m0, s44, 0x2000
	s_add_u32 s42, s42, 0x80080
	v_lshl_add_u64 v[168:169], v[224:225], 0, s[6:7]
	s_addc_u32 s43, s43, 0
	s_add_i32 s44, s49, s9
	global_load_lds_dwordx4 v[168:169], off
	v_lshl_add_u64 v[168:169], s[42:43], 0, v[140:141]
	s_mov_b32 m0, s44
	s_nop 0
	global_load_lds_dwordx4 v[168:169], off
	v_lshl_add_u64 v[168:169], s[42:43], 0, v[144:145]
	s_add_i32 m0, s44, 0x2000
	s_nop 0
	global_load_lds_dwordx4 v[168:169], off
	v_lshl_add_u64 v[168:169], v[226:227], 0, s[6:7]
	s_mov_b32 m0, s26
	s_nop 0
	global_load_lds_dwordx4 v[168:169], off
	v_lshl_add_u64 v[168:169], v[228:229], 0, s[6:7]
	s_mov_b32 m0, s27
	s_nop 0
	global_load_lds_dwordx4 v[168:169], off
	s_waitcnt vmcnt(8)
	s_waitcnt lgkmcnt(0)
	s_barrier
	s_setprio 1
	s_waitcnt lgkmcnt(0)
	v_mfma_f32_16x16x32_bf16 v[62:65], v[130:133], v[192:195], v[62:65]
	v_mfma_f32_16x16x32_bf16 v[58:61], v[152:155], v[192:195], v[58:61]
	v_mfma_f32_16x16x32_bf16 v[46:49], v[130:133], v[200:203], v[46:49]
	v_mfma_f32_16x16x32_bf16 v[42:45], v[152:155], v[200:203], v[42:45]
	v_mfma_f32_16x16x32_bf16 v[30:33], v[130:133], v[208:211], v[30:33]
	v_mfma_f32_16x16x32_bf16 v[26:29], v[152:155], v[208:211], v[26:29]
	v_mfma_f32_16x16x32_bf16 v[14:17], v[130:133], v[216:219], v[14:17]
	v_mfma_f32_16x16x32_bf16 v[10:13], v[152:155], v[216:219], v[10:13]
	v_mfma_f32_16x16x32_bf16 v[62:65], v[134:137], v[196:199], v[62:65]
	v_mfma_f32_16x16x32_bf16 v[58:61], v[158:161], v[196:199], v[58:61]
	v_mfma_f32_16x16x32_bf16 v[46:49], v[134:137], v[204:207], v[46:49]
	v_mfma_f32_16x16x32_bf16 v[42:45], v[158:161], v[204:207], v[42:45]
	v_mfma_f32_16x16x32_bf16 v[30:33], v[134:137], v[212:215], v[30:33]
	v_mfma_f32_16x16x32_bf16 v[26:29], v[158:161], v[212:215], v[26:29]
	v_mfma_f32_16x16x32_bf16 v[14:17], v[134:137], v[220:223], v[14:17]
	v_mfma_f32_16x16x32_bf16 v[10:13], v[158:161], v[220:223], v[10:13]
	s_setprio 0
	s_setprio 1
	v_mfma_f32_16x16x32_bf16 v[54:57], v[164:167], v[192:195], v[54:57]
	v_mfma_f32_16x16x32_bf16 v[50:53], v[184:187], v[192:195], v[50:53]
	v_mfma_f32_16x16x32_bf16 v[38:41], v[164:167], v[200:203], v[38:41]
	v_mfma_f32_16x16x32_bf16 v[34:37], v[184:187], v[200:203], v[34:37]
	v_mfma_f32_16x16x32_bf16 v[22:25], v[164:167], v[208:211], v[22:25]
	v_mfma_f32_16x16x32_bf16 v[18:21], v[184:187], v[208:211], v[18:21]
	v_mfma_f32_16x16x32_bf16 v[6:9], v[164:167], v[216:219], v[6:9]
	v_mfma_f32_16x16x32_bf16 v[2:5], v[184:187], v[216:219], v[2:5]
	v_mfma_f32_16x16x32_bf16 v[54:57], v[180:183], v[196:199], v[54:57]
	v_mfma_f32_16x16x32_bf16 v[50:53], v[188:191], v[196:199], v[50:53]
	v_mfma_f32_16x16x32_bf16 v[38:41], v[180:183], v[204:207], v[38:41]
	v_mfma_f32_16x16x32_bf16 v[34:37], v[188:191], v[204:207], v[34:37]
	v_mfma_f32_16x16x32_bf16 v[22:25], v[180:183], v[212:215], v[22:25]
	v_mfma_f32_16x16x32_bf16 v[18:21], v[188:191], v[212:215], v[18:21]
	s_setprio 2
	s_barrier
	v_mfma_f32_16x16x32_bf16 v[6:9], v[180:183], v[220:223], v[6:9]
	v_mfma_f32_16x16x32_bf16 v[2:5], v[188:191], v[220:223], v[2:5]
	s_setprio 0
	s_add_i32 s47, s47, 2
	s_add_u32 s36, s36, 0x100
	s_addc_u32 s37, s37, 0
	s_add_u32 s41, s41, 0x100
	s_addc_u32 s46, s46, 0
	s_cmp_gt_u32 s47, 29
	s_cbranch_scc0 .LBB0_292
	s_and_b64 vcc, exec, s[2:3]
	s_cbranch_vccz .LBB0_295
	s_barrier

.LBB0_357:
	s_ashr_i32 s19, s18, 31
	s_lshl_b64 s[8:9], s[18:19], 20
	v_readlane_b32 s5, v243, 17
	s_add_u32 s28, s5, s8
	v_readlane_b32 s5, v243, 18
	s_addc_u32 s29, s5, s9
	s_and_b64 s[8:9], s[34:35], exec
	s_cselect_b32 s8, s29, s37
	s_cselect_b32 s9, s28, s36
	s_ashr_i32 s5, s4, 31
	s_lshl_b64 s[20:21], s[4:5], 20
	s_add_u32 s38, s30, s20
	v_readlane_b32 s5, v242, 4
	s_addc_u32 s39, s5, s21
	s_and_b64 s[20:21], s[34:35], exec
	s_cselect_b32 s5, s39, s43
	s_cselect_b32 s11, s38, s42
	s_add_u32 s36, s36, 0x80080
	s_addc_u32 s37, s37, 0
	s_add_u32 s13, s42, 0x100
	s_addc_u32 s19, s43, 0
	s_mov_b32 s20, -2
	s_waitcnt vmcnt(0)
	s_add_u32 s21, s36, 0xfff80080
	s_addc_u32 s23, s37, -1
	s_add_i32 s26, 0, 0x10000
	s_cmp_eq_u32 s20, 28
	s_cselect_b32 s45, s8, s23
	s_cselect_b32 s44, s9, s21
	v_add_u32_e32 v153, s26, v179
	s_cselect_b32 s43, s5, s19
	s_cselect_b32 s42, s11, s13
	s_add_i32 s21, 0, 0x14000
	ds_read_b128 v[130:133], v153
	ds_read_b128 v[134:137], v153 offset:1024
	ds_read_b128 v[164:167], v153 offset:2048
	ds_read_b128 v[182:185], v153 offset:3072
	v_add_u32_e32 v153, s21, v179
	ds_read_b128 v[186:189], v153
	ds_read_b128 v[190:193], v153 offset:1024
	ds_read_b128 v[194:197], v153 offset:2048
	ds_read_b128 v[198:201], v153 offset:3072
	v_lshl_add_u64 v[168:169], s[36:37], 0, v[148:149]
	s_add_i32 m0, s27, 0xc000
	ds_read_b128 v[202:205], v181
	ds_read_b128 v[206:209], v181 offset:1024
	ds_read_b128 v[210:213], v181 offset:2048
	ds_read_b128 v[214:217], v181 offset:3072
	ds_read_b128 v[218:221], v181 offset:4096
	ds_read_b128 v[222:225], v181 offset:5120
	ds_read_b128 v[226:229], v181 offset:6144
	ds_read_b128 v[230:233], v181 offset:7168
	global_load_lds_dwordx4 v[168:169], off
	v_lshl_add_u64 v[168:169], s[36:37], 0, v[150:151]
	s_add_i32 m0, s27, 0xe000
	s_nop 0
	global_load_lds_dwordx4 v[168:169], off
	s_waitcnt vmcnt(8)
	s_waitcnt lgkmcnt(0)
	s_barrier
	s_setprio 1
	s_waitcnt lgkmcnt(0)
	v_mfma_f32_16x16x32_bf16 v[126:129], v[130:133], v[202:205], 0
	v_mfma_f32_16x16x32_bf16 v[122:125], v[164:167], v[202:205], 0
	v_mfma_f32_16x16x32_bf16 v[110:113], v[130:133], v[210:213], 0
	v_mfma_f32_16x16x32_bf16 v[106:109], v[164:167], v[210:213], 0
	v_mfma_f32_16x16x32_bf16 v[94:97], v[130:133], v[218:221], 0
	v_mfma_f32_16x16x32_bf16 v[90:93], v[164:167], v[218:221], 0
	v_mfma_f32_16x16x32_bf16 v[78:81], v[130:133], v[226:229], 0
	v_mfma_f32_16x16x32_bf16 v[74:77], v[164:167], v[226:229], 0
	v_mfma_f32_16x16x32_bf16 v[126:129], v[134:137], v[206:209], v[126:129]
	v_mfma_f32_16x16x32_bf16 v[122:125], v[182:185], v[206:209], v[122:125]
	v_mfma_f32_16x16x32_bf16 v[110:113], v[134:137], v[214:217], v[110:113]
	v_mfma_f32_16x16x32_bf16 v[106:109], v[182:185], v[214:217], v[106:109]
	v_mfma_f32_16x16x32_bf16 v[94:97], v[134:137], v[222:225], v[94:97]
	v_mfma_f32_16x16x32_bf16 v[90:93], v[182:185], v[222:225], v[90:93]
	v_mfma_f32_16x16x32_bf16 v[78:81], v[134:137], v[230:233], v[78:81]
	v_mfma_f32_16x16x32_bf16 v[74:77], v[182:185], v[230:233], v[74:77]
	s_setprio 0
	s_setprio 1
	v_mfma_f32_16x16x32_bf16 v[118:121], v[186:189], v[202:205], 0
	v_mfma_f32_16x16x32_bf16 v[114:117], v[194:197], v[202:205], 0
	v_mfma_f32_16x16x32_bf16 v[102:105], v[186:189], v[210:213], 0
	v_mfma_f32_16x16x32_bf16 v[98:101], v[194:197], v[210:213], 0
	v_mfma_f32_16x16x32_bf16 v[86:89], v[186:189], v[218:221], 0
	v_mfma_f32_16x16x32_bf16 v[82:85], v[194:197], v[218:221], 0
	v_mfma_f32_16x16x32_bf16 v[70:73], v[186:189], v[226:229], 0
	v_mfma_f32_16x16x32_bf16 v[66:69], v[194:197], v[226:229], 0
	v_mfma_f32_16x16x32_bf16 v[118:121], v[190:193], v[206:209], v[118:121]
	v_mfma_f32_16x16x32_bf16 v[114:117], v[198:201], v[206:209], v[114:117]
	v_mfma_f32_16x16x32_bf16 v[102:105], v[190:193], v[214:217], v[102:105]
	v_mfma_f32_16x16x32_bf16 v[98:101], v[198:201], v[214:217], v[98:101]
	v_mfma_f32_16x16x32_bf16 v[86:89], v[190:193], v[222:225], v[86:89]
	v_mfma_f32_16x16x32_bf16 v[82:85], v[198:201], v[222:225], v[82:85]
	s_setprio 2
	s_barrier
	v_mfma_f32_16x16x32_bf16 v[70:73], v[190:193], v[230:233], v[70:73]
	v_mfma_f32_16x16x32_bf16 v[66:69], v[198:201], v[230:233], v[66:69]
	s_setprio 0
	s_add_i32 s23, s26, s25
	v_lshl_add_u64 v[168:169], s[42:43], 0, v[162:163]
	s_mov_b32 m0, s23
	ds_read_b128 v[202:205], v181 offset:16384
	ds_read_b128 v[206:209], v181 offset:17408
	ds_read_b128 v[210:213], v181 offset:18432
	ds_read_b128 v[214:217], v181 offset:19456
	ds_read_b128 v[218:221], v181 offset:20480
	ds_read_b128 v[222:225], v181 offset:21504
	ds_read_b128 v[226:229], v181 offset:22528
	ds_read_b128 v[230:233], v181 offset:23552
	global_load_lds_dwordx4 v[168:169], off
	s_add_i32 m0, s23, 0x2000
	s_add_u32 s52, s42, 0x80000
	v_lshl_add_u64 v[234:235], s[42:43], 0, v[142:143]
	s_addc_u32 s53, s43, 0
	s_add_i32 s21, s21, s25
	global_load_lds_dwordx4 v[234:235], off
	v_lshl_add_u64 v[236:237], s[52:53], 0, v[162:163]
	s_mov_b32 m0, s21
	v_lshl_add_u64 v[238:239], s[44:45], 0, v[140:141]
	global_load_lds_dwordx4 v[236:237], off
	v_lshl_add_u64 v[236:237], s[52:53], 0, v[142:143]
	s_add_i32 m0, s21, 0x2000
	s_nop 0
	global_load_lds_dwordx4 v[236:237], off
	v_lshl_add_u64 v[236:237], s[44:45], 0, v[138:139]
	s_mov_b32 m0, s27
	s_nop 0
	global_load_lds_dwordx4 v[236:237], off
	s_mov_b32 m0, s46
	s_nop 0
	global_load_lds_dwordx4 v[238:239], off
	s_waitcnt vmcnt(8)
	s_waitcnt lgkmcnt(0)
	s_barrier
	s_setprio 1
	s_waitcnt lgkmcnt(0)
	v_mfma_f32_16x16x32_bf16 v[62:65], v[130:133], v[202:205], 0
	v_mfma_f32_16x16x32_bf16 v[58:61], v[164:167], v[202:205], 0
	v_mfma_f32_16x16x32_bf16 v[46:49], v[130:133], v[210:213], 0
	v_mfma_f32_16x16x32_bf16 v[42:45], v[164:167], v[210:213], 0
	v_mfma_f32_16x16x32_bf16 v[30:33], v[130:133], v[218:221], 0
	v_mfma_f32_16x16x32_bf16 v[26:29], v[164:167], v[218:221], 0
	v_mfma_f32_16x16x32_bf16 v[14:17], v[130:133], v[226:229], 0
	v_mfma_f32_16x16x32_bf16 v[10:13], v[164:167], v[226:229], 0
	v_mfma_f32_16x16x32_bf16 v[62:65], v[134:137], v[206:209], v[62:65]
	v_mfma_f32_16x16x32_bf16 v[58:61], v[182:185], v[206:209], v[58:61]
	v_mfma_f32_16x16x32_bf16 v[46:49], v[134:137], v[214:217], v[46:49]
	v_mfma_f32_16x16x32_bf16 v[42:45], v[182:185], v[214:217], v[42:45]
	v_mfma_f32_16x16x32_bf16 v[30:33], v[134:137], v[222:225], v[30:33]
	v_mfma_f32_16x16x32_bf16 v[26:29], v[182:185], v[222:225], v[26:29]
	v_mfma_f32_16x16x32_bf16 v[14:17], v[134:137], v[230:233], v[14:17]
	v_mfma_f32_16x16x32_bf16 v[10:13], v[182:185], v[230:233], v[10:13]
	s_setprio 0
	s_setprio 1
	v_mfma_f32_16x16x32_bf16 v[54:57], v[186:189], v[202:205], 0
	v_mfma_f32_16x16x32_bf16 v[50:53], v[194:197], v[202:205], 0
	v_mfma_f32_16x16x32_bf16 v[38:41], v[186:189], v[210:213], 0
	v_mfma_f32_16x16x32_bf16 v[34:37], v[194:197], v[210:213], 0
	v_mfma_f32_16x16x32_bf16 v[22:25], v[186:189], v[218:221], 0
	v_mfma_f32_16x16x32_bf16 v[18:21], v[194:197], v[218:221], 0
	v_mfma_f32_16x16x32_bf16 v[6:9], v[186:189], v[226:229], 0
	v_mfma_f32_16x16x32_bf16 v[2:5], v[194:197], v[226:229], 0
	v_mfma_f32_16x16x32_bf16 v[54:57], v[190:193], v[206:209], v[54:57]
	v_mfma_f32_16x16x32_bf16 v[50:53], v[198:201], v[206:209], v[50:53]
	v_mfma_f32_16x16x32_bf16 v[38:41], v[190:193], v[214:217], v[38:41]
	v_mfma_f32_16x16x32_bf16 v[34:37], v[198:201], v[214:217], v[34:37]
	v_mfma_f32_16x16x32_bf16 v[22:25], v[190:193], v[222:225], v[22:25]
	v_mfma_f32_16x16x32_bf16 v[18:21], v[198:201], v[222:225], v[18:21]
	s_setprio 2
	s_barrier
	v_mfma_f32_16x16x32_bf16 v[6:9], v[190:193], v[230:233], v[6:9]
	v_mfma_f32_16x16x32_bf16 v[2:5], v[198:201], v[230:233], v[2:5]
	s_setprio 0
	s_add_i32 s21, 0, 0x18000
	v_add_u32_e32 v153, s21, v179
	s_add_i32 s23, 0, 0x1c000
	ds_read_b128 v[130:133], v153
	ds_read_b128 v[134:137], v153 offset:1024
	ds_read_b128 v[164:167], v153 offset:2048
	ds_read_b128 v[182:185], v153 offset:3072
	v_add_u32_e32 v153, s23, v179
	ds_read_b128 v[186:189], v153
	ds_read_b128 v[190:193], v153 offset:1024
	ds_read_b128 v[194:197], v153 offset:2048
	ds_read_b128 v[198:201], v153 offset:3072
	s_add_u32 s44, s44, 0x80000
	s_addc_u32 s45, s45, 0
	s_mov_b32 m0, s47
	v_lshl_add_u64 v[240:241], s[44:45], 0, v[138:139]
	ds_read_b128 v[202:205], v181 offset:32768
	ds_read_b128 v[206:209], v181 offset:33792
	ds_read_b128 v[210:213], v181 offset:34816
	ds_read_b128 v[214:217], v181 offset:35840
	ds_read_b128 v[218:221], v181 offset:36864
	ds_read_b128 v[222:225], v181 offset:37888
	ds_read_b128 v[226:229], v181 offset:38912
	ds_read_b128 v[230:233], v181 offset:39936
	global_load_lds_dwordx4 v[240:241], off
	v_lshl_add_u64 v[240:241], s[44:45], 0, v[140:141]
	s_mov_b32 m0, s48
	s_nop 0
	global_load_lds_dwordx4 v[240:241], off
	s_waitcnt vmcnt(8)
	s_waitcnt lgkmcnt(0)
	s_barrier
	s_setprio 1
	s_waitcnt lgkmcnt(0)
	v_mfma_f32_16x16x32_bf16 v[126:129], v[130:133], v[202:205], v[126:129]
	v_mfma_f32_16x16x32_bf16 v[122:125], v[164:167], v[202:205], v[122:125]
	v_mfma_f32_16x16x32_bf16 v[110:113], v[130:133], v[210:213], v[110:113]
	v_mfma_f32_16x16x32_bf16 v[106:109], v[164:167], v[210:213], v[106:109]
	v_mfma_f32_16x16x32_bf16 v[94:97], v[130:133], v[218:221], v[94:97]
	v_mfma_f32_16x16x32_bf16 v[90:93], v[164:167], v[218:221], v[90:93]
	v_mfma_f32_16x16x32_bf16 v[78:81], v[130:133], v[226:229], v[78:81]
	v_mfma_f32_16x16x32_bf16 v[74:77], v[164:167], v[226:229], v[74:77]
	v_mfma_f32_16x16x32_bf16 v[126:129], v[134:137], v[206:209], v[126:129]
	v_mfma_f32_16x16x32_bf16 v[122:125], v[182:185], v[206:209], v[122:125]
	v_mfma_f32_16x16x32_bf16 v[110:113], v[134:137], v[214:217], v[110:113]
	v_mfma_f32_16x16x32_bf16 v[106:109], v[182:185], v[214:217], v[106:109]
	v_mfma_f32_16x16x32_bf16 v[94:97], v[134:137], v[222:225], v[94:97]
	v_mfma_f32_16x16x32_bf16 v[90:93], v[182:185], v[222:225], v[90:93]
	v_mfma_f32_16x16x32_bf16 v[78:81], v[134:137], v[230:233], v[78:81]
	v_mfma_f32_16x16x32_bf16 v[74:77], v[182:185], v[230:233], v[74:77]
	s_setprio 0
	s_setprio 1
	v_mfma_f32_16x16x32_bf16 v[118:121], v[186:189], v[202:205], v[118:121]
	v_mfma_f32_16x16x32_bf16 v[114:117], v[194:197], v[202:205], v[114:117]
	v_mfma_f32_16x16x32_bf16 v[102:105], v[186:189], v[210:213], v[102:105]
	v_mfma_f32_16x16x32_bf16 v[98:101], v[194:197], v[210:213], v[98:101]
	v_mfma_f32_16x16x32_bf16 v[86:89], v[186:189], v[218:221], v[86:89]
	v_mfma_f32_16x16x32_bf16 v[82:85], v[194:197], v[218:221], v[82:85]
	v_mfma_f32_16x16x32_bf16 v[70:73], v[186:189], v[226:229], v[70:73]
	v_mfma_f32_16x16x32_bf16 v[66:69], v[194:197], v[226:229], v[66:69]
	v_mfma_f32_16x16x32_bf16 v[118:121], v[190:193], v[206:209], v[118:121]
	v_mfma_f32_16x16x32_bf16 v[114:117], v[198:201], v[206:209], v[114:117]
	v_mfma_f32_16x16x32_bf16 v[102:105], v[190:193], v[214:217], v[102:105]
	v_mfma_f32_16x16x32_bf16 v[98:101], v[198:201], v[214:217], v[98:101]
	v_mfma_f32_16x16x32_bf16 v[86:89], v[190:193], v[222:225], v[86:89]
	v_mfma_f32_16x16x32_bf16 v[82:85], v[198:201], v[222:225], v[82:85]
	s_setprio 2
	s_barrier
	v_mfma_f32_16x16x32_bf16 v[70:73], v[190:193], v[230:233], v[70:73]
	v_mfma_f32_16x16x32_bf16 v[66:69], v[198:201], v[230:233], v[66:69]
	s_setprio 0
	s_add_i32 s21, s21, s25
	v_lshl_add_u64 v[168:169], v[168:169], 0, s[6:7]
	s_mov_b32 m0, s21
	ds_read_b128 v[202:205], v181 offset:49152
	ds_read_b128 v[206:209], v181 offset:50176
	ds_read_b128 v[210:213], v181 offset:51200
	ds_read_b128 v[214:217], v181 offset:52224
	ds_read_b128 v[218:221], v181 offset:53248
	ds_read_b128 v[222:225], v181 offset:54272
	ds_read_b128 v[226:229], v181 offset:55296
	ds_read_b128 v[230:233], v181 offset:56320
	global_load_lds_dwordx4 v[168:169], off
	s_add_i32 m0, s21, 0x2000
	s_add_u32 s42, s42, 0x80080
	v_lshl_add_u64 v[168:169], v[234:235], 0, s[6:7]
	s_addc_u32 s43, s43, 0
	s_add_i32 s21, s23, s25
	global_load_lds_dwordx4 v[168:169], off
	v_lshl_add_u64 v[168:169], s[42:43], 0, v[162:163]
	s_mov_b32 m0, s21
	s_nop 0
	global_load_lds_dwordx4 v[168:169], off
	v_lshl_add_u64 v[168:169], s[42:43], 0, v[142:143]
	s_add_i32 m0, s21, 0x2000
	s_nop 0
	global_load_lds_dwordx4 v[168:169], off
	v_lshl_add_u64 v[168:169], v[236:237], 0, s[6:7]
	s_mov_b32 m0, s49
	s_nop 0
	global_load_lds_dwordx4 v[168:169], off
	v_lshl_add_u64 v[168:169], v[238:239], 0, s[6:7]
	s_mov_b32 m0, s50
	s_nop 0
	global_load_lds_dwordx4 v[168:169], off
	s_waitcnt vmcnt(8)
	s_waitcnt lgkmcnt(0)
	s_barrier
	s_setprio 1
	s_waitcnt lgkmcnt(0)
	v_mfma_f32_16x16x32_bf16 v[62:65], v[130:133], v[202:205], v[62:65]
	v_mfma_f32_16x16x32_bf16 v[58:61], v[164:167], v[202:205], v[58:61]
	v_mfma_f32_16x16x32_bf16 v[46:49], v[130:133], v[210:213], v[46:49]
	v_mfma_f32_16x16x32_bf16 v[42:45], v[164:167], v[210:213], v[42:45]
	v_mfma_f32_16x16x32_bf16 v[30:33], v[130:133], v[218:221], v[30:33]
	v_mfma_f32_16x16x32_bf16 v[26:29], v[164:167], v[218:221], v[26:29]
	v_mfma_f32_16x16x32_bf16 v[14:17], v[130:133], v[226:229], v[14:17]
	v_mfma_f32_16x16x32_bf16 v[10:13], v[164:167], v[226:229], v[10:13]
	v_mfma_f32_16x16x32_bf16 v[62:65], v[134:137], v[206:209], v[62:65]
	v_mfma_f32_16x16x32_bf16 v[58:61], v[182:185], v[206:209], v[58:61]
	v_mfma_f32_16x16x32_bf16 v[46:49], v[134:137], v[214:217], v[46:49]
	v_mfma_f32_16x16x32_bf16 v[42:45], v[182:185], v[214:217], v[42:45]
	v_mfma_f32_16x16x32_bf16 v[30:33], v[134:137], v[222:225], v[30:33]
	v_mfma_f32_16x16x32_bf16 v[26:29], v[182:185], v[222:225], v[26:29]
	v_mfma_f32_16x16x32_bf16 v[14:17], v[134:137], v[230:233], v[14:17]
	v_mfma_f32_16x16x32_bf16 v[10:13], v[182:185], v[230:233], v[10:13]
	s_setprio 0
	s_setprio 1
	v_mfma_f32_16x16x32_bf16 v[54:57], v[186:189], v[202:205], v[54:57]
	v_mfma_f32_16x16x32_bf16 v[50:53], v[194:197], v[202:205], v[50:53]
	v_mfma_f32_16x16x32_bf16 v[38:41], v[186:189], v[210:213], v[38:41]
	v_mfma_f32_16x16x32_bf16 v[34:37], v[194:197], v[210:213], v[34:37]
	v_mfma_f32_16x16x32_bf16 v[22:25], v[186:189], v[218:221], v[22:25]
	v_mfma_f32_16x16x32_bf16 v[18:21], v[194:197], v[218:221], v[18:21]
	v_mfma_f32_16x16x32_bf16 v[6:9], v[186:189], v[226:229], v[6:9]
	v_mfma_f32_16x16x32_bf16 v[2:5], v[194:197], v[226:229], v[2:5]
	v_mfma_f32_16x16x32_bf16 v[54:57], v[190:193], v[206:209], v[54:57]
	v_mfma_f32_16x16x32_bf16 v[50:53], v[198:201], v[206:209], v[50:53]
	v_mfma_f32_16x16x32_bf16 v[38:41], v[190:193], v[214:217], v[38:41]
	v_mfma_f32_16x16x32_bf16 v[34:37], v[198:201], v[214:217], v[34:37]
	v_mfma_f32_16x16x32_bf16 v[22:25], v[190:193], v[222:225], v[22:25]
	v_mfma_f32_16x16x32_bf16 v[18:21], v[198:201], v[222:225], v[18:21]
	s_setprio 2
	s_barrier
	v_mfma_f32_16x16x32_bf16 v[6:9], v[190:193], v[230:233], v[6:9]
	v_mfma_f32_16x16x32_bf16 v[2:5], v[198:201], v[230:233], v[2:5]
	s_setprio 0
	s_add_i32 s20, s20, 2
	s_add_u32 s36, s36, 0x100
	s_addc_u32 s37, s37, 0
	s_add_u32 s13, s13, 0x100
	s_addc_u32 s19, s19, 0
	s_cmp_gt_u32 s20, 29
.LBB0_358:
	s_add_u32 s21, s36, 0xfff80080
	s_addc_u32 s23, s37, -1
	s_add_i32 s26, 0, 0x10000
	s_cmp_eq_u32 s20, 28
	s_cselect_b32 s45, s8, s23
	s_cselect_b32 s44, s9, s21
	v_add_u32_e32 v153, s26, v179
	s_cselect_b32 s43, s5, s19
	s_cselect_b32 s42, s11, s13
	s_add_i32 s21, 0, 0x14000
	ds_read_b128 v[130:133], v153
	ds_read_b128 v[134:137], v153 offset:1024
	ds_read_b128 v[164:167], v153 offset:2048
	ds_read_b128 v[182:185], v153 offset:3072
	v_add_u32_e32 v153, s21, v179
	ds_read_b128 v[186:189], v153
	ds_read_b128 v[190:193], v153 offset:1024
	ds_read_b128 v[194:197], v153 offset:2048
	ds_read_b128 v[198:201], v153 offset:3072
	v_lshl_add_u64 v[168:169], s[36:37], 0, v[148:149]
	s_add_i32 m0, s27, 0xc000
	ds_read_b128 v[202:205], v181
	ds_read_b128 v[206:209], v181 offset:1024
	ds_read_b128 v[210:213], v181 offset:2048
	ds_read_b128 v[214:217], v181 offset:3072
	ds_read_b128 v[218:221], v181 offset:4096
	ds_read_b128 v[222:225], v181 offset:5120
	ds_read_b128 v[226:229], v181 offset:6144
	ds_read_b128 v[230:233], v181 offset:7168
	global_load_lds_dwordx4 v[168:169], off
	v_lshl_add_u64 v[168:169], s[36:37], 0, v[150:151]
	s_add_i32 m0, s27, 0xe000
	s_nop 0
	global_load_lds_dwordx4 v[168:169], off
	s_waitcnt vmcnt(8)
	s_waitcnt lgkmcnt(0)
	s_barrier
	s_setprio 1
	s_waitcnt lgkmcnt(0)
	v_mfma_f32_16x16x32_bf16 v[126:129], v[130:133], v[202:205], v[126:129]
	v_mfma_f32_16x16x32_bf16 v[122:125], v[164:167], v[202:205], v[122:125]
	v_mfma_f32_16x16x32_bf16 v[110:113], v[130:133], v[210:213], v[110:113]
	v_mfma_f32_16x16x32_bf16 v[106:109], v[164:167], v[210:213], v[106:109]
	v_mfma_f32_16x16x32_bf16 v[94:97], v[130:133], v[218:221], v[94:97]
	v_mfma_f32_16x16x32_bf16 v[90:93], v[164:167], v[218:221], v[90:93]
	v_mfma_f32_16x16x32_bf16 v[78:81], v[130:133], v[226:229], v[78:81]
	v_mfma_f32_16x16x32_bf16 v[74:77], v[164:167], v[226:229], v[74:77]
	v_mfma_f32_16x16x32_bf16 v[126:129], v[134:137], v[206:209], v[126:129]
	v_mfma_f32_16x16x32_bf16 v[122:125], v[182:185], v[206:209], v[122:125]
	v_mfma_f32_16x16x32_bf16 v[110:113], v[134:137], v[214:217], v[110:113]
	v_mfma_f32_16x16x32_bf16 v[106:109], v[182:185], v[214:217], v[106:109]
	v_mfma_f32_16x16x32_bf16 v[94:97], v[134:137], v[222:225], v[94:97]
	v_mfma_f32_16x16x32_bf16 v[90:93], v[182:185], v[222:225], v[90:93]
	v_mfma_f32_16x16x32_bf16 v[78:81], v[134:137], v[230:233], v[78:81]
	v_mfma_f32_16x16x32_bf16 v[74:77], v[182:185], v[230:233], v[74:77]
	s_setprio 0
	s_setprio 1
	v_mfma_f32_16x16x32_bf16 v[118:121], v[186:189], v[202:205], v[118:121]
	v_mfma_f32_16x16x32_bf16 v[114:117], v[194:197], v[202:205], v[114:117]
	v_mfma_f32_16x16x32_bf16 v[102:105], v[186:189], v[210:213], v[102:105]
	v_mfma_f32_16x16x32_bf16 v[98:101], v[194:197], v[210:213], v[98:101]
	v_mfma_f32_16x16x32_bf16 v[86:89], v[186:189], v[218:221], v[86:89]
	v_mfma_f32_16x16x32_bf16 v[82:85], v[194:197], v[218:221], v[82:85]
	v_mfma_f32_16x16x32_bf16 v[70:73], v[186:189], v[226:229], v[70:73]
	v_mfma_f32_16x16x32_bf16 v[66:69], v[194:197], v[226:229], v[66:69]
	v_mfma_f32_16x16x32_bf16 v[118:121], v[190:193], v[206:209], v[118:121]
	v_mfma_f32_16x16x32_bf16 v[114:117], v[198:201], v[206:209], v[114:117]
	v_mfma_f32_16x16x32_bf16 v[102:105], v[190:193], v[214:217], v[102:105]
	v_mfma_f32_16x16x32_bf16 v[98:101], v[198:201], v[214:217], v[98:101]
	v_mfma_f32_16x16x32_bf16 v[86:89], v[190:193], v[222:225], v[86:89]
	v_mfma_f32_16x16x32_bf16 v[82:85], v[198:201], v[222:225], v[82:85]
	s_setprio 2
	s_barrier
	v_mfma_f32_16x16x32_bf16 v[70:73], v[190:193], v[230:233], v[70:73]
	v_mfma_f32_16x16x32_bf16 v[66:69], v[198:201], v[230:233], v[66:69]
	s_setprio 0
	s_add_i32 s23, s26, s25
	v_lshl_add_u64 v[168:169], s[42:43], 0, v[162:163]
	s_mov_b32 m0, s23
	ds_read_b128 v[202:205], v181 offset:16384
	ds_read_b128 v[206:209], v181 offset:17408
	ds_read_b128 v[210:213], v181 offset:18432
	ds_read_b128 v[214:217], v181 offset:19456
	ds_read_b128 v[218:221], v181 offset:20480
	ds_read_b128 v[222:225], v181 offset:21504
	ds_read_b128 v[226:229], v181 offset:22528
	ds_read_b128 v[230:233], v181 offset:23552
	global_load_lds_dwordx4 v[168:169], off
	s_add_i32 m0, s23, 0x2000
	s_add_u32 s52, s42, 0x80000
	v_lshl_add_u64 v[234:235], s[42:43], 0, v[142:143]
	s_addc_u32 s53, s43, 0
	s_add_i32 s21, s21, s25
	global_load_lds_dwordx4 v[234:235], off
	v_lshl_add_u64 v[236:237], s[52:53], 0, v[162:163]
	s_mov_b32 m0, s21
	v_lshl_add_u64 v[238:239], s[44:45], 0, v[140:141]
	global_load_lds_dwordx4 v[236:237], off
	v_lshl_add_u64 v[236:237], s[52:53], 0, v[142:143]
	s_add_i32 m0, s21, 0x2000
	s_nop 0
	global_load_lds_dwordx4 v[236:237], off
	v_lshl_add_u64 v[236:237], s[44:45], 0, v[138:139]
	s_mov_b32 m0, s27
	s_nop 0
	global_load_lds_dwordx4 v[236:237], off
	s_mov_b32 m0, s46
	s_nop 0
	global_load_lds_dwordx4 v[238:239], off
	s_waitcnt vmcnt(8)
	s_waitcnt lgkmcnt(0)
	s_barrier
	s_setprio 1
	s_waitcnt lgkmcnt(0)
	v_mfma_f32_16x16x32_bf16 v[62:65], v[130:133], v[202:205], v[62:65]
	v_mfma_f32_16x16x32_bf16 v[58:61], v[164:167], v[202:205], v[58:61]
	v_mfma_f32_16x16x32_bf16 v[46:49], v[130:133], v[210:213], v[46:49]
	v_mfma_f32_16x16x32_bf16 v[42:45], v[164:167], v[210:213], v[42:45]
	v_mfma_f32_16x16x32_bf16 v[30:33], v[130:133], v[218:221], v[30:33]
	v_mfma_f32_16x16x32_bf16 v[26:29], v[164:167], v[218:221], v[26:29]
	v_mfma_f32_16x16x32_bf16 v[14:17], v[130:133], v[226:229], v[14:17]
	v_mfma_f32_16x16x32_bf16 v[10:13], v[164:167], v[226:229], v[10:13]
	v_mfma_f32_16x16x32_bf16 v[62:65], v[134:137], v[206:209], v[62:65]
	v_mfma_f32_16x16x32_bf16 v[58:61], v[182:185], v[206:209], v[58:61]
	v_mfma_f32_16x16x32_bf16 v[46:49], v[134:137], v[214:217], v[46:49]
	v_mfma_f32_16x16x32_bf16 v[42:45], v[182:185], v[214:217], v[42:45]
	v_mfma_f32_16x16x32_bf16 v[30:33], v[134:137], v[222:225], v[30:33]
	v_mfma_f32_16x16x32_bf16 v[26:29], v[182:185], v[222:225], v[26:29]
	v_mfma_f32_16x16x32_bf16 v[14:17], v[134:137], v[230:233], v[14:17]
	v_mfma_f32_16x16x32_bf16 v[10:13], v[182:185], v[230:233], v[10:13]
	s_setprio 0
	s_setprio 1
	v_mfma_f32_16x16x32_bf16 v[54:57], v[186:189], v[202:205], v[54:57]
	v_mfma_f32_16x16x32_bf16 v[50:53], v[194:197], v[202:205], v[50:53]
	v_mfma_f32_16x16x32_bf16 v[38:41], v[186:189], v[210:213], v[38:41]
	v_mfma_f32_16x16x32_bf16 v[34:37], v[194:197], v[210:213], v[34:37]
	v_mfma_f32_16x16x32_bf16 v[22:25], v[186:189], v[218:221], v[22:25]
	v_mfma_f32_16x16x32_bf16 v[18:21], v[194:197], v[218:221], v[18:21]
	v_mfma_f32_16x16x32_bf16 v[6:9], v[186:189], v[226:229], v[6:9]
	v_mfma_f32_16x16x32_bf16 v[2:5], v[194:197], v[226:229], v[2:5]
	v_mfma_f32_16x16x32_bf16 v[54:57], v[190:193], v[206:209], v[54:57]
	v_mfma_f32_16x16x32_bf16 v[50:53], v[198:201], v[206:209], v[50:53]
	v_mfma_f32_16x16x32_bf16 v[38:41], v[190:193], v[214:217], v[38:41]
	v_mfma_f32_16x16x32_bf16 v[34:37], v[198:201], v[214:217], v[34:37]
	v_mfma_f32_16x16x32_bf16 v[22:25], v[190:193], v[222:225], v[22:25]
	v_mfma_f32_16x16x32_bf16 v[18:21], v[198:201], v[222:225], v[18:21]
	s_setprio 2
	s_barrier
	v_mfma_f32_16x16x32_bf16 v[6:9], v[190:193], v[230:233], v[6:9]
	v_mfma_f32_16x16x32_bf16 v[2:5], v[198:201], v[230:233], v[2:5]
	s_setprio 0
	s_add_i32 s21, 0, 0x18000
	v_add_u32_e32 v153, s21, v179
	s_add_i32 s23, 0, 0x1c000
	ds_read_b128 v[130:133], v153
	ds_read_b128 v[134:137], v153 offset:1024
	ds_read_b128 v[164:167], v153 offset:2048
	ds_read_b128 v[182:185], v153 offset:3072
	v_add_u32_e32 v153, s23, v179
	ds_read_b128 v[186:189], v153
	ds_read_b128 v[190:193], v153 offset:1024
	ds_read_b128 v[194:197], v153 offset:2048
	ds_read_b128 v[198:201], v153 offset:3072
	s_add_u32 s44, s44, 0x80000
	s_addc_u32 s45, s45, 0
	s_mov_b32 m0, s47
	v_lshl_add_u64 v[240:241], s[44:45], 0, v[138:139]
	ds_read_b128 v[202:205], v181 offset:32768
	ds_read_b128 v[206:209], v181 offset:33792
	ds_read_b128 v[210:213], v181 offset:34816
	ds_read_b128 v[214:217], v181 offset:35840
	ds_read_b128 v[218:221], v181 offset:36864
	ds_read_b128 v[222:225], v181 offset:37888
	ds_read_b128 v[226:229], v181 offset:38912
	ds_read_b128 v[230:233], v181 offset:39936
	global_load_lds_dwordx4 v[240:241], off
	v_lshl_add_u64 v[240:241], s[44:45], 0, v[140:141]
	s_mov_b32 m0, s48
	s_nop 0
	global_load_lds_dwordx4 v[240:241], off
	s_waitcnt vmcnt(8)
	s_waitcnt lgkmcnt(0)
	s_barrier
	s_setprio 1
	s_waitcnt lgkmcnt(0)
	v_mfma_f32_16x16x32_bf16 v[126:129], v[130:133], v[202:205], v[126:129]
	v_mfma_f32_16x16x32_bf16 v[122:125], v[164:167], v[202:205], v[122:125]
	v_mfma_f32_16x16x32_bf16 v[110:113], v[130:133], v[210:213], v[110:113]
	v_mfma_f32_16x16x32_bf16 v[106:109], v[164:167], v[210:213], v[106:109]
	v_mfma_f32_16x16x32_bf16 v[94:97], v[130:133], v[218:221], v[94:97]
	v_mfma_f32_16x16x32_bf16 v[90:93], v[164:167], v[218:221], v[90:93]
	v_mfma_f32_16x16x32_bf16 v[78:81], v[130:133], v[226:229], v[78:81]
	v_mfma_f32_16x16x32_bf16 v[74:77], v[164:167], v[226:229], v[74:77]
	v_mfma_f32_16x16x32_bf16 v[126:129], v[134:137], v[206:209], v[126:129]
	v_mfma_f32_16x16x32_bf16 v[122:125], v[182:185], v[206:209], v[122:125]
	v_mfma_f32_16x16x32_bf16 v[110:113], v[134:137], v[214:217], v[110:113]
	v_mfma_f32_16x16x32_bf16 v[106:109], v[182:185], v[214:217], v[106:109]
	v_mfma_f32_16x16x32_bf16 v[94:97], v[134:137], v[222:225], v[94:97]
	v_mfma_f32_16x16x32_bf16 v[90:93], v[182:185], v[222:225], v[90:93]
	v_mfma_f32_16x16x32_bf16 v[78:81], v[134:137], v[230:233], v[78:81]
	v_mfma_f32_16x16x32_bf16 v[74:77], v[182:185], v[230:233], v[74:77]
	s_setprio 0
	s_setprio 1
	v_mfma_f32_16x16x32_bf16 v[118:121], v[186:189], v[202:205], v[118:121]
	v_mfma_f32_16x16x32_bf16 v[114:117], v[194:197], v[202:205], v[114:117]
	v_mfma_f32_16x16x32_bf16 v[102:105], v[186:189], v[210:213], v[102:105]
	v_mfma_f32_16x16x32_bf16 v[98:101], v[194:197], v[210:213], v[98:101]
	v_mfma_f32_16x16x32_bf16 v[86:89], v[186:189], v[218:221], v[86:89]
	v_mfma_f32_16x16x32_bf16 v[82:85], v[194:197], v[218:221], v[82:85]
	v_mfma_f32_16x16x32_bf16 v[70:73], v[186:189], v[226:229], v[70:73]
	v_mfma_f32_16x16x32_bf16 v[66:69], v[194:197], v[226:229], v[66:69]
	v_mfma_f32_16x16x32_bf16 v[118:121], v[190:193], v[206:209], v[118:121]
	v_mfma_f32_16x16x32_bf16 v[114:117], v[198:201], v[206:209], v[114:117]
	v_mfma_f32_16x16x32_bf16 v[102:105], v[190:193], v[214:217], v[102:105]
	v_mfma_f32_16x16x32_bf16 v[98:101], v[198:201], v[214:217], v[98:101]
	v_mfma_f32_16x16x32_bf16 v[86:89], v[190:193], v[222:225], v[86:89]
	v_mfma_f32_16x16x32_bf16 v[82:85], v[198:201], v[222:225], v[82:85]
	s_setprio 2
	s_barrier
	v_mfma_f32_16x16x32_bf16 v[70:73], v[190:193], v[230:233], v[70:73]
	v_mfma_f32_16x16x32_bf16 v[66:69], v[198:201], v[230:233], v[66:69]
	s_setprio 0
	s_add_i32 s21, s21, s25
	v_lshl_add_u64 v[168:169], v[168:169], 0, s[6:7]
	s_mov_b32 m0, s21
	ds_read_b128 v[202:205], v181 offset:49152
	ds_read_b128 v[206:209], v181 offset:50176
	ds_read_b128 v[210:213], v181 offset:51200
	ds_read_b128 v[214:217], v181 offset:52224
	ds_read_b128 v[218:221], v181 offset:53248
	ds_read_b128 v[222:225], v181 offset:54272
	ds_read_b128 v[226:229], v181 offset:55296
	ds_read_b128 v[230:233], v181 offset:56320
	global_load_lds_dwordx4 v[168:169], off
	s_add_i32 m0, s21, 0x2000
	s_add_u32 s42, s42, 0x80080
	v_lshl_add_u64 v[168:169], v[234:235], 0, s[6:7]
	s_addc_u32 s43, s43, 0
	s_add_i32 s21, s23, s25
	global_load_lds_dwordx4 v[168:169], off
	v_lshl_add_u64 v[168:169], s[42:43], 0, v[162:163]
	s_mov_b32 m0, s21
	s_nop 0
	global_load_lds_dwordx4 v[168:169], off
	v_lshl_add_u64 v[168:169], s[42:43], 0, v[142:143]
	s_add_i32 m0, s21, 0x2000
	s_nop 0
	global_load_lds_dwordx4 v[168:169], off
	v_lshl_add_u64 v[168:169], v[236:237], 0, s[6:7]
	s_mov_b32 m0, s49
	s_nop 0
	global_load_lds_dwordx4 v[168:169], off
	v_lshl_add_u64 v[168:169], v[238:239], 0, s[6:7]
	s_mov_b32 m0, s50
	s_nop 0
	global_load_lds_dwordx4 v[168:169], off
	s_waitcnt vmcnt(8)
	s_waitcnt lgkmcnt(0)
	s_barrier
	s_setprio 1
	s_waitcnt lgkmcnt(0)
	v_mfma_f32_16x16x32_bf16 v[62:65], v[130:133], v[202:205], v[62:65]
	v_mfma_f32_16x16x32_bf16 v[58:61], v[164:167], v[202:205], v[58:61]
	v_mfma_f32_16x16x32_bf16 v[46:49], v[130:133], v[210:213], v[46:49]
	v_mfma_f32_16x16x32_bf16 v[42:45], v[164:167], v[210:213], v[42:45]
	v_mfma_f32_16x16x32_bf16 v[30:33], v[130:133], v[218:221], v[30:33]
	v_mfma_f32_16x16x32_bf16 v[26:29], v[164:167], v[218:221], v[26:29]
	v_mfma_f32_16x16x32_bf16 v[14:17], v[130:133], v[226:229], v[14:17]
	v_mfma_f32_16x16x32_bf16 v[10:13], v[164:167], v[226:229], v[10:13]
	v_mfma_f32_16x16x32_bf16 v[62:65], v[134:137], v[206:209], v[62:65]
	v_mfma_f32_16x16x32_bf16 v[58:61], v[182:185], v[206:209], v[58:61]
	v_mfma_f32_16x16x32_bf16 v[46:49], v[134:137], v[214:217], v[46:49]
	v_mfma_f32_16x16x32_bf16 v[42:45], v[182:185], v[214:217], v[42:45]
	v_mfma_f32_16x16x32_bf16 v[30:33], v[134:137], v[222:225], v[30:33]
	v_mfma_f32_16x16x32_bf16 v[26:29], v[182:185], v[222:225], v[26:29]
	v_mfma_f32_16x16x32_bf16 v[14:17], v[134:137], v[230:233], v[14:17]
	v_mfma_f32_16x16x32_bf16 v[10:13], v[182:185], v[230:233], v[10:13]
	s_setprio 0
	s_setprio 1
	v_mfma_f32_16x16x32_bf16 v[54:57], v[186:189], v[202:205], v[54:57]
	v_mfma_f32_16x16x32_bf16 v[50:53], v[194:197], v[202:205], v[50:53]
	v_mfma_f32_16x16x32_bf16 v[38:41], v[186:189], v[210:213], v[38:41]
	v_mfma_f32_16x16x32_bf16 v[34:37], v[194:197], v[210:213], v[34:37]
	v_mfma_f32_16x16x32_bf16 v[22:25], v[186:189], v[218:221], v[22:25]
	v_mfma_f32_16x16x32_bf16 v[18:21], v[194:197], v[218:221], v[18:21]
	v_mfma_f32_16x16x32_bf16 v[6:9], v[186:189], v[226:229], v[6:9]
	v_mfma_f32_16x16x32_bf16 v[2:5], v[194:197], v[226:229], v[2:5]
	v_mfma_f32_16x16x32_bf16 v[54:57], v[190:193], v[206:209], v[54:57]
	v_mfma_f32_16x16x32_bf16 v[50:53], v[198:201], v[206:209], v[50:53]
	v_mfma_f32_16x16x32_bf16 v[38:41], v[190:193], v[214:217], v[38:41]
	v_mfma_f32_16x16x32_bf16 v[34:37], v[198:201], v[214:217], v[34:37]
	v_mfma_f32_16x16x32_bf16 v[22:25], v[190:193], v[222:225], v[22:25]
	v_mfma_f32_16x16x32_bf16 v[18:21], v[198:201], v[222:225], v[18:21]
	s_setprio 2
	s_barrier
	v_mfma_f32_16x16x32_bf16 v[6:9], v[190:193], v[230:233], v[6:9]
	v_mfma_f32_16x16x32_bf16 v[2:5], v[198:201], v[230:233], v[2:5]
	s_setprio 0
	s_add_i32 s20, s20, 2
	s_add_u32 s36, s36, 0x100
	s_addc_u32 s37, s37, 0
	s_add_u32 s13, s13, 0x100
	s_addc_u32 s19, s19, 0
	s_cmp_gt_u32 s20, 29
	s_cbranch_scc0 .LBB0_358
	s_and_b64 vcc, exec, s[2:3]
	s_cbranch_vccz .LBB0_361
	s_barrier

.LBB0_1114:
	s_ashr_i32 s19, s18, 31
	s_lshl_b64 s[28:29], s[18:19], 20
	v_readlane_b32 s5, v245, 28
	s_add_u32 s28, s5, s28
	v_readlane_b32 s5, v245, 29
	s_addc_u32 s29, s5, s29
	s_and_b64 s[34:35], s[22:23], exec
	s_cselect_b32 s8, s29, s37
	s_cselect_b32 s19, s28, s36
	s_ashr_i32 s5, s4, 31
	s_lshl_b64 s[34:35], s[4:5], 20
	s_add_u32 s34, s11, s34
	s_addc_u32 s35, s13, s35
	s_and_b64 s[44:45], s[22:23], exec
	s_cselect_b32 s5, s35, s43
	s_cselect_b32 s21, s34, s42
	s_add_u32 s36, s36, 0x80080
	s_addc_u32 s37, s37, 0
	s_add_u32 s41, s42, 0x100
	s_addc_u32 s48, s43, 0
	s_mov_b32 s49, -2
	s_waitcnt vmcnt(0) lgkmcnt(0)
	s_add_u32 s42, s36, 0xfff80080
	s_addc_u32 s43, s37, -1
	s_add_i32 s50, 0, 0x10000
	s_cmp_eq_u32 s49, 28
	s_cselect_b32 s45, s8, s43
	s_cselect_b32 s44, s19, s42
	v_add_u32_e32 v154, s50, v145
	s_cselect_b32 s43, s5, s48
	s_cselect_b32 s42, s21, s41
	s_add_i32 s52, 0, 0x14000
	ds_read_b128 v[130:133], v154
	ds_read_b128 v[134:137], v154 offset:1024
	ds_read_b128 v[150:153], v154 offset:2048
	ds_read_b128 v[158:161], v154 offset:3072
	v_add_u32_e32 v154, s52, v145
	ds_read_b128 v[164:167], v154
	ds_read_b128 v[180:183], v154 offset:1024
	ds_read_b128 v[184:187], v154 offset:2048
	ds_read_b128 v[188:191], v154 offset:3072
	v_lshl_add_u64 v[154:155], s[36:37], 0, v[146:147]
	s_add_i32 m0, s20, 0xc000
	ds_read_b128 v[192:195], v157
	ds_read_b128 v[196:199], v157 offset:1024
	ds_read_b128 v[200:203], v157 offset:2048
	ds_read_b128 v[204:207], v157 offset:3072
	ds_read_b128 v[208:211], v157 offset:4096
	ds_read_b128 v[212:215], v157 offset:5120
	ds_read_b128 v[216:219], v157 offset:6144
	ds_read_b128 v[220:223], v157 offset:7168
	global_load_lds_dwordx4 v[154:155], off
	v_lshl_add_u64 v[154:155], s[36:37], 0, v[148:149]
	s_add_i32 m0, s20, 0xe000
	s_nop 0
	global_load_lds_dwordx4 v[154:155], off
	s_waitcnt vmcnt(8)
	s_waitcnt lgkmcnt(0)
	s_barrier
	s_setprio 1
	s_waitcnt lgkmcnt(0)
	v_mfma_f32_16x16x32_bf16 v[126:129], v[130:133], v[192:195], 0
	v_mfma_f32_16x16x32_bf16 v[122:125], v[150:153], v[192:195], 0
	v_mfma_f32_16x16x32_bf16 v[110:113], v[130:133], v[200:203], 0
	v_mfma_f32_16x16x32_bf16 v[106:109], v[150:153], v[200:203], 0
	v_mfma_f32_16x16x32_bf16 v[94:97], v[130:133], v[208:211], 0
	v_mfma_f32_16x16x32_bf16 v[90:93], v[150:153], v[208:211], 0
	v_mfma_f32_16x16x32_bf16 v[78:81], v[130:133], v[216:219], 0
	v_mfma_f32_16x16x32_bf16 v[74:77], v[150:153], v[216:219], 0
	v_mfma_f32_16x16x32_bf16 v[126:129], v[134:137], v[196:199], v[126:129]
	v_mfma_f32_16x16x32_bf16 v[122:125], v[158:161], v[196:199], v[122:125]
	v_mfma_f32_16x16x32_bf16 v[110:113], v[134:137], v[204:207], v[110:113]
	v_mfma_f32_16x16x32_bf16 v[106:109], v[158:161], v[204:207], v[106:109]
	v_mfma_f32_16x16x32_bf16 v[94:97], v[134:137], v[212:215], v[94:97]
	v_mfma_f32_16x16x32_bf16 v[90:93], v[158:161], v[212:215], v[90:93]
	v_mfma_f32_16x16x32_bf16 v[78:81], v[134:137], v[220:223], v[78:81]
	v_mfma_f32_16x16x32_bf16 v[74:77], v[158:161], v[220:223], v[74:77]
	s_setprio 0
	s_setprio 1
	v_mfma_f32_16x16x32_bf16 v[118:121], v[164:167], v[192:195], 0
	v_mfma_f32_16x16x32_bf16 v[114:117], v[184:187], v[192:195], 0
	v_mfma_f32_16x16x32_bf16 v[102:105], v[164:167], v[200:203], 0
	v_mfma_f32_16x16x32_bf16 v[98:101], v[184:187], v[200:203], 0
	v_mfma_f32_16x16x32_bf16 v[86:89], v[164:167], v[208:211], 0
	v_mfma_f32_16x16x32_bf16 v[82:85], v[184:187], v[208:211], 0
	v_mfma_f32_16x16x32_bf16 v[70:73], v[164:167], v[216:219], 0
	v_mfma_f32_16x16x32_bf16 v[66:69], v[184:187], v[216:219], 0
	v_mfma_f32_16x16x32_bf16 v[118:121], v[180:183], v[196:199], v[118:121]
	v_mfma_f32_16x16x32_bf16 v[114:117], v[188:191], v[196:199], v[114:117]
	v_mfma_f32_16x16x32_bf16 v[102:105], v[180:183], v[204:207], v[102:105]
	v_mfma_f32_16x16x32_bf16 v[98:101], v[188:191], v[204:207], v[98:101]
	v_mfma_f32_16x16x32_bf16 v[86:89], v[180:183], v[212:215], v[86:89]
	v_mfma_f32_16x16x32_bf16 v[82:85], v[188:191], v[212:215], v[82:85]
	s_setprio 2
	s_barrier
	v_mfma_f32_16x16x32_bf16 v[70:73], v[180:183], v[220:223], v[70:73]
	v_mfma_f32_16x16x32_bf16 v[66:69], v[188:191], v[220:223], v[66:69]
	s_setprio 0
	s_add_i32 s50, s50, s9
	v_lshl_add_u64 v[154:155], s[42:43], 0, v[162:163]
	s_mov_b32 m0, s50
	ds_read_b128 v[192:195], v157 offset:16384
	ds_read_b128 v[196:199], v157 offset:17408
	ds_read_b128 v[200:203], v157 offset:18432
	ds_read_b128 v[204:207], v157 offset:19456
	ds_read_b128 v[208:211], v157 offset:20480
	ds_read_b128 v[212:215], v157 offset:21504
	ds_read_b128 v[216:219], v157 offset:22528
	ds_read_b128 v[220:223], v157 offset:23552
	global_load_lds_dwordx4 v[154:155], off
	s_add_i32 m0, s50, 0x2000
	s_add_u32 s50, s42, 0x80000
	v_lshl_add_u64 v[168:169], s[42:43], 0, v[142:143]
	s_addc_u32 s51, s43, 0
	s_add_i32 s52, s52, s9
	global_load_lds_dwordx4 v[168:169], off
	v_lshl_add_u64 v[224:225], s[50:51], 0, v[162:163]
	s_mov_b32 m0, s52
	v_lshl_add_u64 v[226:227], s[44:45], 0, v[140:141]
	global_load_lds_dwordx4 v[224:225], off
	v_lshl_add_u64 v[224:225], s[50:51], 0, v[142:143]
	s_add_i32 m0, s52, 0x2000
	s_nop 0
	global_load_lds_dwordx4 v[224:225], off
	v_lshl_add_u64 v[224:225], s[44:45], 0, v[138:139]
	s_mov_b32 m0, s20
	s_nop 0
	global_load_lds_dwordx4 v[224:225], off
	s_mov_b32 m0, s25
	s_nop 0
	global_load_lds_dwordx4 v[226:227], off
	s_waitcnt vmcnt(8)
	s_waitcnt lgkmcnt(0)
	s_barrier
	s_setprio 1
	s_waitcnt lgkmcnt(0)
	v_mfma_f32_16x16x32_bf16 v[62:65], v[130:133], v[192:195], 0
	v_mfma_f32_16x16x32_bf16 v[58:61], v[150:153], v[192:195], 0
	v_mfma_f32_16x16x32_bf16 v[46:49], v[130:133], v[200:203], 0
	v_mfma_f32_16x16x32_bf16 v[42:45], v[150:153], v[200:203], 0
	v_mfma_f32_16x16x32_bf16 v[30:33], v[130:133], v[208:211], 0
	v_mfma_f32_16x16x32_bf16 v[26:29], v[150:153], v[208:211], 0
	v_mfma_f32_16x16x32_bf16 v[14:17], v[130:133], v[216:219], 0
	v_mfma_f32_16x16x32_bf16 v[10:13], v[150:153], v[216:219], 0
	v_mfma_f32_16x16x32_bf16 v[62:65], v[134:137], v[196:199], v[62:65]
	v_mfma_f32_16x16x32_bf16 v[58:61], v[158:161], v[196:199], v[58:61]
	v_mfma_f32_16x16x32_bf16 v[46:49], v[134:137], v[204:207], v[46:49]
	v_mfma_f32_16x16x32_bf16 v[42:45], v[158:161], v[204:207], v[42:45]
	v_mfma_f32_16x16x32_bf16 v[30:33], v[134:137], v[212:215], v[30:33]
	v_mfma_f32_16x16x32_bf16 v[26:29], v[158:161], v[212:215], v[26:29]
	v_mfma_f32_16x16x32_bf16 v[14:17], v[134:137], v[220:223], v[14:17]
	v_mfma_f32_16x16x32_bf16 v[10:13], v[158:161], v[220:223], v[10:13]
	s_setprio 0
	s_setprio 1
	v_mfma_f32_16x16x32_bf16 v[54:57], v[164:167], v[192:195], 0
	v_mfma_f32_16x16x32_bf16 v[50:53], v[184:187], v[192:195], 0
	v_mfma_f32_16x16x32_bf16 v[38:41], v[164:167], v[200:203], 0
	v_mfma_f32_16x16x32_bf16 v[34:37], v[184:187], v[200:203], 0
	v_mfma_f32_16x16x32_bf16 v[22:25], v[164:167], v[208:211], 0
	v_mfma_f32_16x16x32_bf16 v[18:21], v[184:187], v[208:211], 0
	v_mfma_f32_16x16x32_bf16 v[6:9], v[164:167], v[216:219], 0
	v_mfma_f32_16x16x32_bf16 v[2:5], v[184:187], v[216:219], 0
	v_mfma_f32_16x16x32_bf16 v[54:57], v[180:183], v[196:199], v[54:57]
	v_mfma_f32_16x16x32_bf16 v[50:53], v[188:191], v[196:199], v[50:53]
	v_mfma_f32_16x16x32_bf16 v[38:41], v[180:183], v[204:207], v[38:41]
	v_mfma_f32_16x16x32_bf16 v[34:37], v[188:191], v[204:207], v[34:37]
	v_mfma_f32_16x16x32_bf16 v[22:25], v[180:183], v[212:215], v[22:25]
	v_mfma_f32_16x16x32_bf16 v[18:21], v[188:191], v[212:215], v[18:21]
	s_setprio 2
	s_barrier
	v_mfma_f32_16x16x32_bf16 v[6:9], v[180:183], v[220:223], v[6:9]
	v_mfma_f32_16x16x32_bf16 v[2:5], v[188:191], v[220:223], v[2:5]
	s_setprio 0
	s_add_i32 s50, 0, 0x18000
	s_add_i32 s51, 0, 0x1c000
	v_add_u32_e32 v158, s50, v145
	v_add_u32_e32 v179, s51, v145
	ds_read_b128 v[130:133], v158
	ds_read_b128 v[134:137], v158 offset:1024
	ds_read_b128 v[150:153], v158 offset:2048
	ds_read_b128 v[158:161], v158 offset:3072
	ds_read_b128 v[164:167], v179
	ds_read_b128 v[180:183], v179 offset:1024
	ds_read_b128 v[184:187], v179 offset:2048
	ds_read_b128 v[188:191], v179 offset:3072
	s_add_u32 s44, s44, 0x80000
	s_addc_u32 s45, s45, 0
	s_mov_b32 m0, s26
	v_lshl_add_u64 v[228:229], s[44:45], 0, v[138:139]
	ds_read_b128 v[192:195], v157 offset:32768
	ds_read_b128 v[196:199], v157 offset:33792
	ds_read_b128 v[200:203], v157 offset:34816
	ds_read_b128 v[204:207], v157 offset:35840
	ds_read_b128 v[208:211], v157 offset:36864
	ds_read_b128 v[212:215], v157 offset:37888
	ds_read_b128 v[216:219], v157 offset:38912
	ds_read_b128 v[220:223], v157 offset:39936
	global_load_lds_dwordx4 v[228:229], off
	v_lshl_add_u64 v[228:229], s[44:45], 0, v[140:141]
	s_mov_b32 m0, s27
	s_nop 0
	global_load_lds_dwordx4 v[228:229], off
	s_waitcnt vmcnt(8)
	s_waitcnt lgkmcnt(0)
	s_barrier
	s_setprio 1
	s_waitcnt lgkmcnt(0)
	v_mfma_f32_16x16x32_bf16 v[126:129], v[130:133], v[192:195], v[126:129]
	v_mfma_f32_16x16x32_bf16 v[122:125], v[150:153], v[192:195], v[122:125]
	v_mfma_f32_16x16x32_bf16 v[110:113], v[130:133], v[200:203], v[110:113]
	v_mfma_f32_16x16x32_bf16 v[106:109], v[150:153], v[200:203], v[106:109]
	v_mfma_f32_16x16x32_bf16 v[94:97], v[130:133], v[208:211], v[94:97]
	v_mfma_f32_16x16x32_bf16 v[90:93], v[150:153], v[208:211], v[90:93]
	v_mfma_f32_16x16x32_bf16 v[78:81], v[130:133], v[216:219], v[78:81]
	v_mfma_f32_16x16x32_bf16 v[74:77], v[150:153], v[216:219], v[74:77]
	v_mfma_f32_16x16x32_bf16 v[126:129], v[134:137], v[196:199], v[126:129]
	v_mfma_f32_16x16x32_bf16 v[122:125], v[158:161], v[196:199], v[122:125]
	v_mfma_f32_16x16x32_bf16 v[110:113], v[134:137], v[204:207], v[110:113]
	v_mfma_f32_16x16x32_bf16 v[106:109], v[158:161], v[204:207], v[106:109]
	v_mfma_f32_16x16x32_bf16 v[94:97], v[134:137], v[212:215], v[94:97]
	v_mfma_f32_16x16x32_bf16 v[90:93], v[158:161], v[212:215], v[90:93]
	v_mfma_f32_16x16x32_bf16 v[78:81], v[134:137], v[220:223], v[78:81]
	v_mfma_f32_16x16x32_bf16 v[74:77], v[158:161], v[220:223], v[74:77]
	s_setprio 0
	s_setprio 1
	v_mfma_f32_16x16x32_bf16 v[118:121], v[164:167], v[192:195], v[118:121]
	v_mfma_f32_16x16x32_bf16 v[114:117], v[184:187], v[192:195], v[114:117]
	v_mfma_f32_16x16x32_bf16 v[102:105], v[164:167], v[200:203], v[102:105]
	v_mfma_f32_16x16x32_bf16 v[98:101], v[184:187], v[200:203], v[98:101]
	v_mfma_f32_16x16x32_bf16 v[86:89], v[164:167], v[208:211], v[86:89]
	v_mfma_f32_16x16x32_bf16 v[82:85], v[184:187], v[208:211], v[82:85]
	v_mfma_f32_16x16x32_bf16 v[70:73], v[164:167], v[216:219], v[70:73]
	v_mfma_f32_16x16x32_bf16 v[66:69], v[184:187], v[216:219], v[66:69]
	v_mfma_f32_16x16x32_bf16 v[118:121], v[180:183], v[196:199], v[118:121]
	v_mfma_f32_16x16x32_bf16 v[114:117], v[188:191], v[196:199], v[114:117]
	v_mfma_f32_16x16x32_bf16 v[102:105], v[180:183], v[204:207], v[102:105]
	v_mfma_f32_16x16x32_bf16 v[98:101], v[188:191], v[204:207], v[98:101]
	v_mfma_f32_16x16x32_bf16 v[86:89], v[180:183], v[212:215], v[86:89]
	v_mfma_f32_16x16x32_bf16 v[82:85], v[188:191], v[212:215], v[82:85]
	s_setprio 2
	s_barrier
	v_mfma_f32_16x16x32_bf16 v[70:73], v[180:183], v[220:223], v[70:73]
	v_mfma_f32_16x16x32_bf16 v[66:69], v[188:191], v[220:223], v[66:69]
	s_setprio 0
	s_add_i32 s44, s50, s9
	v_lshl_add_u64 v[154:155], v[154:155], 0, s[6:7]
	s_mov_b32 m0, s44
	ds_read_b128 v[192:195], v157 offset:49152
	ds_read_b128 v[196:199], v157 offset:50176
	ds_read_b128 v[200:203], v157 offset:51200
	ds_read_b128 v[204:207], v157 offset:52224
	ds_read_b128 v[208:211], v157 offset:53248
	ds_read_b128 v[212:215], v157 offset:54272
	ds_read_b128 v[216:219], v157 offset:55296
	ds_read_b128 v[220:223], v157 offset:56320
	global_load_lds_dwordx4 v[154:155], off
	s_add_i32 m0, s44, 0x2000
	s_add_u32 s42, s42, 0x80080
	v_lshl_add_u64 v[154:155], v[168:169], 0, s[6:7]
	s_addc_u32 s43, s43, 0
	s_add_i32 s44, s51, s9
	global_load_lds_dwordx4 v[154:155], off
	v_lshl_add_u64 v[154:155], s[42:43], 0, v[162:163]
	s_mov_b32 m0, s44
	s_nop 0
	global_load_lds_dwordx4 v[154:155], off
	v_lshl_add_u64 v[154:155], s[42:43], 0, v[142:143]
	s_add_i32 m0, s44, 0x2000
	s_nop 0
	global_load_lds_dwordx4 v[154:155], off
	v_lshl_add_u64 v[154:155], v[224:225], 0, s[6:7]
	s_mov_b32 m0, s39
	s_nop 0
	global_load_lds_dwordx4 v[154:155], off
	v_lshl_add_u64 v[154:155], v[226:227], 0, s[6:7]
	s_mov_b32 m0, s46
	s_nop 0
	global_load_lds_dwordx4 v[154:155], off
	s_waitcnt vmcnt(8)
	s_waitcnt lgkmcnt(0)
	s_barrier
	s_setprio 1
	s_waitcnt lgkmcnt(0)
	v_mfma_f32_16x16x32_bf16 v[62:65], v[130:133], v[192:195], v[62:65]
	v_mfma_f32_16x16x32_bf16 v[58:61], v[150:153], v[192:195], v[58:61]
	v_mfma_f32_16x16x32_bf16 v[46:49], v[130:133], v[200:203], v[46:49]
	v_mfma_f32_16x16x32_bf16 v[42:45], v[150:153], v[200:203], v[42:45]
	v_mfma_f32_16x16x32_bf16 v[30:33], v[130:133], v[208:211], v[30:33]
	v_mfma_f32_16x16x32_bf16 v[26:29], v[150:153], v[208:211], v[26:29]
	v_mfma_f32_16x16x32_bf16 v[14:17], v[130:133], v[216:219], v[14:17]
	v_mfma_f32_16x16x32_bf16 v[10:13], v[150:153], v[216:219], v[10:13]
	v_mfma_f32_16x16x32_bf16 v[62:65], v[134:137], v[196:199], v[62:65]
	v_mfma_f32_16x16x32_bf16 v[58:61], v[158:161], v[196:199], v[58:61]
	v_mfma_f32_16x16x32_bf16 v[46:49], v[134:137], v[204:207], v[46:49]
	v_mfma_f32_16x16x32_bf16 v[42:45], v[158:161], v[204:207], v[42:45]
	v_mfma_f32_16x16x32_bf16 v[30:33], v[134:137], v[212:215], v[30:33]
	v_mfma_f32_16x16x32_bf16 v[26:29], v[158:161], v[212:215], v[26:29]
	v_mfma_f32_16x16x32_bf16 v[14:17], v[134:137], v[220:223], v[14:17]
	v_mfma_f32_16x16x32_bf16 v[10:13], v[158:161], v[220:223], v[10:13]
	s_setprio 0
	s_setprio 1
	v_mfma_f32_16x16x32_bf16 v[54:57], v[164:167], v[192:195], v[54:57]
	v_mfma_f32_16x16x32_bf16 v[50:53], v[184:187], v[192:195], v[50:53]
	v_mfma_f32_16x16x32_bf16 v[38:41], v[164:167], v[200:203], v[38:41]
	v_mfma_f32_16x16x32_bf16 v[34:37], v[184:187], v[200:203], v[34:37]
	v_mfma_f32_16x16x32_bf16 v[22:25], v[164:167], v[208:211], v[22:25]
	v_mfma_f32_16x16x32_bf16 v[18:21], v[184:187], v[208:211], v[18:21]
	v_mfma_f32_16x16x32_bf16 v[6:9], v[164:167], v[216:219], v[6:9]
	v_mfma_f32_16x16x32_bf16 v[2:5], v[184:187], v[216:219], v[2:5]
	v_mfma_f32_16x16x32_bf16 v[54:57], v[180:183], v[196:199], v[54:57]
	v_mfma_f32_16x16x32_bf16 v[50:53], v[188:191], v[196:199], v[50:53]
	v_mfma_f32_16x16x32_bf16 v[38:41], v[180:183], v[204:207], v[38:41]
	v_mfma_f32_16x16x32_bf16 v[34:37], v[188:191], v[204:207], v[34:37]
	v_mfma_f32_16x16x32_bf16 v[22:25], v[180:183], v[212:215], v[22:25]
	v_mfma_f32_16x16x32_bf16 v[18:21], v[188:191], v[212:215], v[18:21]
	s_setprio 2
	s_barrier
	v_mfma_f32_16x16x32_bf16 v[6:9], v[180:183], v[220:223], v[6:9]
	v_mfma_f32_16x16x32_bf16 v[2:5], v[188:191], v[220:223], v[2:5]
	s_setprio 0
	s_add_i32 s49, s49, 2
	s_add_u32 s36, s36, 0x100
	s_addc_u32 s37, s37, 0
	s_add_u32 s41, s41, 0x100
	s_addc_u32 s48, s48, 0
	s_cmp_gt_u32 s49, 29
.LBB0_1115:
	s_add_u32 s42, s36, 0xfff80080
	s_addc_u32 s43, s37, -1
	s_add_i32 s50, 0, 0x10000
	s_cmp_eq_u32 s49, 28
	s_cselect_b32 s45, s8, s43
	s_cselect_b32 s44, s19, s42
	v_add_u32_e32 v154, s50, v145
	s_cselect_b32 s43, s5, s48
	s_cselect_b32 s42, s21, s41
	s_add_i32 s52, 0, 0x14000
	ds_read_b128 v[130:133], v154
	ds_read_b128 v[134:137], v154 offset:1024
	ds_read_b128 v[150:153], v154 offset:2048
	ds_read_b128 v[158:161], v154 offset:3072
	v_add_u32_e32 v154, s52, v145
	ds_read_b128 v[164:167], v154
	ds_read_b128 v[180:183], v154 offset:1024
	ds_read_b128 v[184:187], v154 offset:2048
	ds_read_b128 v[188:191], v154 offset:3072
	v_lshl_add_u64 v[154:155], s[36:37], 0, v[146:147]
	s_add_i32 m0, s20, 0xc000
	ds_read_b128 v[192:195], v157
	ds_read_b128 v[196:199], v157 offset:1024
	ds_read_b128 v[200:203], v157 offset:2048
	ds_read_b128 v[204:207], v157 offset:3072
	ds_read_b128 v[208:211], v157 offset:4096
	ds_read_b128 v[212:215], v157 offset:5120
	ds_read_b128 v[216:219], v157 offset:6144
	ds_read_b128 v[220:223], v157 offset:7168
	global_load_lds_dwordx4 v[154:155], off
	v_lshl_add_u64 v[154:155], s[36:37], 0, v[148:149]
	s_add_i32 m0, s20, 0xe000
	s_nop 0
	global_load_lds_dwordx4 v[154:155], off
	s_waitcnt vmcnt(8)
	s_waitcnt lgkmcnt(0)
	s_barrier
	s_setprio 1
	s_waitcnt lgkmcnt(0)
	v_mfma_f32_16x16x32_bf16 v[126:129], v[130:133], v[192:195], v[126:129]
	v_mfma_f32_16x16x32_bf16 v[122:125], v[150:153], v[192:195], v[122:125]
	v_mfma_f32_16x16x32_bf16 v[110:113], v[130:133], v[200:203], v[110:113]
	v_mfma_f32_16x16x32_bf16 v[106:109], v[150:153], v[200:203], v[106:109]
	v_mfma_f32_16x16x32_bf16 v[94:97], v[130:133], v[208:211], v[94:97]
	v_mfma_f32_16x16x32_bf16 v[90:93], v[150:153], v[208:211], v[90:93]
	v_mfma_f32_16x16x32_bf16 v[78:81], v[130:133], v[216:219], v[78:81]
	v_mfma_f32_16x16x32_bf16 v[74:77], v[150:153], v[216:219], v[74:77]
	v_mfma_f32_16x16x32_bf16 v[126:129], v[134:137], v[196:199], v[126:129]
	v_mfma_f32_16x16x32_bf16 v[122:125], v[158:161], v[196:199], v[122:125]
	v_mfma_f32_16x16x32_bf16 v[110:113], v[134:137], v[204:207], v[110:113]
	v_mfma_f32_16x16x32_bf16 v[106:109], v[158:161], v[204:207], v[106:109]
	v_mfma_f32_16x16x32_bf16 v[94:97], v[134:137], v[212:215], v[94:97]
	v_mfma_f32_16x16x32_bf16 v[90:93], v[158:161], v[212:215], v[90:93]
	v_mfma_f32_16x16x32_bf16 v[78:81], v[134:137], v[220:223], v[78:81]
	v_mfma_f32_16x16x32_bf16 v[74:77], v[158:161], v[220:223], v[74:77]
	s_setprio 0
	s_setprio 1
	v_mfma_f32_16x16x32_bf16 v[118:121], v[164:167], v[192:195], v[118:121]
	v_mfma_f32_16x16x32_bf16 v[114:117], v[184:187], v[192:195], v[114:117]
	v_mfma_f32_16x16x32_bf16 v[102:105], v[164:167], v[200:203], v[102:105]
	v_mfma_f32_16x16x32_bf16 v[98:101], v[184:187], v[200:203], v[98:101]
	v_mfma_f32_16x16x32_bf16 v[86:89], v[164:167], v[208:211], v[86:89]
	v_mfma_f32_16x16x32_bf16 v[82:85], v[184:187], v[208:211], v[82:85]
	v_mfma_f32_16x16x32_bf16 v[70:73], v[164:167], v[216:219], v[70:73]
	v_mfma_f32_16x16x32_bf16 v[66:69], v[184:187], v[216:219], v[66:69]
	v_mfma_f32_16x16x32_bf16 v[118:121], v[180:183], v[196:199], v[118:121]
	v_mfma_f32_16x16x32_bf16 v[114:117], v[188:191], v[196:199], v[114:117]
	v_mfma_f32_16x16x32_bf16 v[102:105], v[180:183], v[204:207], v[102:105]
	v_mfma_f32_16x16x32_bf16 v[98:101], v[188:191], v[204:207], v[98:101]
	v_mfma_f32_16x16x32_bf16 v[86:89], v[180:183], v[212:215], v[86:89]
	v_mfma_f32_16x16x32_bf16 v[82:85], v[188:191], v[212:215], v[82:85]
	s_setprio 2
	s_barrier
	v_mfma_f32_16x16x32_bf16 v[70:73], v[180:183], v[220:223], v[70:73]
	v_mfma_f32_16x16x32_bf16 v[66:69], v[188:191], v[220:223], v[66:69]
	s_setprio 0
	s_add_i32 s50, s50, s9
	v_lshl_add_u64 v[154:155], s[42:43], 0, v[162:163]
	s_mov_b32 m0, s50
	ds_read_b128 v[192:195], v157 offset:16384
	ds_read_b128 v[196:199], v157 offset:17408
	ds_read_b128 v[200:203], v157 offset:18432
	ds_read_b128 v[204:207], v157 offset:19456
	ds_read_b128 v[208:211], v157 offset:20480
	ds_read_b128 v[212:215], v157 offset:21504
	ds_read_b128 v[216:219], v157 offset:22528
	ds_read_b128 v[220:223], v157 offset:23552
	global_load_lds_dwordx4 v[154:155], off
	s_add_i32 m0, s50, 0x2000
	s_add_u32 s50, s42, 0x80000
	v_lshl_add_u64 v[168:169], s[42:43], 0, v[142:143]
	s_addc_u32 s51, s43, 0
	s_add_i32 s52, s52, s9
	global_load_lds_dwordx4 v[168:169], off
	v_lshl_add_u64 v[224:225], s[50:51], 0, v[162:163]
	s_mov_b32 m0, s52
	v_lshl_add_u64 v[226:227], s[44:45], 0, v[140:141]
	global_load_lds_dwordx4 v[224:225], off
	v_lshl_add_u64 v[224:225], s[50:51], 0, v[142:143]
	s_add_i32 m0, s52, 0x2000
	s_nop 0
	global_load_lds_dwordx4 v[224:225], off
	v_lshl_add_u64 v[224:225], s[44:45], 0, v[138:139]
	s_mov_b32 m0, s20
	s_nop 0
	global_load_lds_dwordx4 v[224:225], off
	s_mov_b32 m0, s25
	s_nop 0
	global_load_lds_dwordx4 v[226:227], off
	s_waitcnt vmcnt(8)
	s_waitcnt lgkmcnt(0)
	s_barrier
	s_setprio 1
	s_waitcnt lgkmcnt(0)
	v_mfma_f32_16x16x32_bf16 v[62:65], v[130:133], v[192:195], v[62:65]
	v_mfma_f32_16x16x32_bf16 v[58:61], v[150:153], v[192:195], v[58:61]
	v_mfma_f32_16x16x32_bf16 v[46:49], v[130:133], v[200:203], v[46:49]
	v_mfma_f32_16x16x32_bf16 v[42:45], v[150:153], v[200:203], v[42:45]
	v_mfma_f32_16x16x32_bf16 v[30:33], v[130:133], v[208:211], v[30:33]
	v_mfma_f32_16x16x32_bf16 v[26:29], v[150:153], v[208:211], v[26:29]
	v_mfma_f32_16x16x32_bf16 v[14:17], v[130:133], v[216:219], v[14:17]
	v_mfma_f32_16x16x32_bf16 v[10:13], v[150:153], v[216:219], v[10:13]
	v_mfma_f32_16x16x32_bf16 v[62:65], v[134:137], v[196:199], v[62:65]
	v_mfma_f32_16x16x32_bf16 v[58:61], v[158:161], v[196:199], v[58:61]
	v_mfma_f32_16x16x32_bf16 v[46:49], v[134:137], v[204:207], v[46:49]
	v_mfma_f32_16x16x32_bf16 v[42:45], v[158:161], v[204:207], v[42:45]
	v_mfma_f32_16x16x32_bf16 v[30:33], v[134:137], v[212:215], v[30:33]
	v_mfma_f32_16x16x32_bf16 v[26:29], v[158:161], v[212:215], v[26:29]
	v_mfma_f32_16x16x32_bf16 v[14:17], v[134:137], v[220:223], v[14:17]
	v_mfma_f32_16x16x32_bf16 v[10:13], v[158:161], v[220:223], v[10:13]
	s_setprio 0
	s_setprio 1
	v_mfma_f32_16x16x32_bf16 v[54:57], v[164:167], v[192:195], v[54:57]
	v_mfma_f32_16x16x32_bf16 v[50:53], v[184:187], v[192:195], v[50:53]
	v_mfma_f32_16x16x32_bf16 v[38:41], v[164:167], v[200:203], v[38:41]
	v_mfma_f32_16x16x32_bf16 v[34:37], v[184:187], v[200:203], v[34:37]
	v_mfma_f32_16x16x32_bf16 v[22:25], v[164:167], v[208:211], v[22:25]
	v_mfma_f32_16x16x32_bf16 v[18:21], v[184:187], v[208:211], v[18:21]
	v_mfma_f32_16x16x32_bf16 v[6:9], v[164:167], v[216:219], v[6:9]
	v_mfma_f32_16x16x32_bf16 v[2:5], v[184:187], v[216:219], v[2:5]
	v_mfma_f32_16x16x32_bf16 v[54:57], v[180:183], v[196:199], v[54:57]
	v_mfma_f32_16x16x32_bf16 v[50:53], v[188:191], v[196:199], v[50:53]
	v_mfma_f32_16x16x32_bf16 v[38:41], v[180:183], v[204:207], v[38:41]
	v_mfma_f32_16x16x32_bf16 v[34:37], v[188:191], v[204:207], v[34:37]
	v_mfma_f32_16x16x32_bf16 v[22:25], v[180:183], v[212:215], v[22:25]
	v_mfma_f32_16x16x32_bf16 v[18:21], v[188:191], v[212:215], v[18:21]
	s_setprio 2
	s_barrier
	v_mfma_f32_16x16x32_bf16 v[6:9], v[180:183], v[220:223], v[6:9]
	v_mfma_f32_16x16x32_bf16 v[2:5], v[188:191], v[220:223], v[2:5]
	s_setprio 0
	s_add_i32 s50, 0, 0x18000
	s_add_i32 s51, 0, 0x1c000
	v_add_u32_e32 v158, s50, v145
	v_add_u32_e32 v179, s51, v145
	ds_read_b128 v[130:133], v158
	ds_read_b128 v[134:137], v158 offset:1024
	ds_read_b128 v[150:153], v158 offset:2048
	ds_read_b128 v[158:161], v158 offset:3072
	ds_read_b128 v[164:167], v179
	ds_read_b128 v[180:183], v179 offset:1024
	ds_read_b128 v[184:187], v179 offset:2048
	ds_read_b128 v[188:191], v179 offset:3072
	s_add_u32 s44, s44, 0x80000
	s_addc_u32 s45, s45, 0
	s_mov_b32 m0, s26
	v_lshl_add_u64 v[228:229], s[44:45], 0, v[138:139]
	ds_read_b128 v[192:195], v157 offset:32768
	ds_read_b128 v[196:199], v157 offset:33792
	ds_read_b128 v[200:203], v157 offset:34816
	ds_read_b128 v[204:207], v157 offset:35840
	ds_read_b128 v[208:211], v157 offset:36864
	ds_read_b128 v[212:215], v157 offset:37888
	ds_read_b128 v[216:219], v157 offset:38912
	ds_read_b128 v[220:223], v157 offset:39936
	global_load_lds_dwordx4 v[228:229], off
	v_lshl_add_u64 v[228:229], s[44:45], 0, v[140:141]
	s_mov_b32 m0, s27
	s_nop 0
	global_load_lds_dwordx4 v[228:229], off
	s_waitcnt vmcnt(8)
	s_waitcnt lgkmcnt(0)
	s_barrier
	s_setprio 1
	s_waitcnt lgkmcnt(0)
	v_mfma_f32_16x16x32_bf16 v[126:129], v[130:133], v[192:195], v[126:129]
	v_mfma_f32_16x16x32_bf16 v[122:125], v[150:153], v[192:195], v[122:125]
	v_mfma_f32_16x16x32_bf16 v[110:113], v[130:133], v[200:203], v[110:113]
	v_mfma_f32_16x16x32_bf16 v[106:109], v[150:153], v[200:203], v[106:109]
	v_mfma_f32_16x16x32_bf16 v[94:97], v[130:133], v[208:211], v[94:97]
	v_mfma_f32_16x16x32_bf16 v[90:93], v[150:153], v[208:211], v[90:93]
	v_mfma_f32_16x16x32_bf16 v[78:81], v[130:133], v[216:219], v[78:81]
	v_mfma_f32_16x16x32_bf16 v[74:77], v[150:153], v[216:219], v[74:77]
	v_mfma_f32_16x16x32_bf16 v[126:129], v[134:137], v[196:199], v[126:129]
	v_mfma_f32_16x16x32_bf16 v[122:125], v[158:161], v[196:199], v[122:125]
	v_mfma_f32_16x16x32_bf16 v[110:113], v[134:137], v[204:207], v[110:113]
	v_mfma_f32_16x16x32_bf16 v[106:109], v[158:161], v[204:207], v[106:109]
	v_mfma_f32_16x16x32_bf16 v[94:97], v[134:137], v[212:215], v[94:97]
	v_mfma_f32_16x16x32_bf16 v[90:93], v[158:161], v[212:215], v[90:93]
	v_mfma_f32_16x16x32_bf16 v[78:81], v[134:137], v[220:223], v[78:81]
	v_mfma_f32_16x16x32_bf16 v[74:77], v[158:161], v[220:223], v[74:77]
	s_setprio 0
	s_setprio 1
	v_mfma_f32_16x16x32_bf16 v[118:121], v[164:167], v[192:195], v[118:121]
	v_mfma_f32_16x16x32_bf16 v[114:117], v[184:187], v[192:195], v[114:117]
	v_mfma_f32_16x16x32_bf16 v[102:105], v[164:167], v[200:203], v[102:105]
	v_mfma_f32_16x16x32_bf16 v[98:101], v[184:187], v[200:203], v[98:101]
	v_mfma_f32_16x16x32_bf16 v[86:89], v[164:167], v[208:211], v[86:89]
	v_mfma_f32_16x16x32_bf16 v[82:85], v[184:187], v[208:211], v[82:85]
	v_mfma_f32_16x16x32_bf16 v[70:73], v[164:167], v[216:219], v[70:73]
	v_mfma_f32_16x16x32_bf16 v[66:69], v[184:187], v[216:219], v[66:69]
	v_mfma_f32_16x16x32_bf16 v[118:121], v[180:183], v[196:199], v[118:121]
	v_mfma_f32_16x16x32_bf16 v[114:117], v[188:191], v[196:199], v[114:117]
	v_mfma_f32_16x16x32_bf16 v[102:105], v[180:183], v[204:207], v[102:105]
	v_mfma_f32_16x16x32_bf16 v[98:101], v[188:191], v[204:207], v[98:101]
	v_mfma_f32_16x16x32_bf16 v[86:89], v[180:183], v[212:215], v[86:89]
	v_mfma_f32_16x16x32_bf16 v[82:85], v[188:191], v[212:215], v[82:85]
	s_setprio 2
	s_barrier
	v_mfma_f32_16x16x32_bf16 v[70:73], v[180:183], v[220:223], v[70:73]
	v_mfma_f32_16x16x32_bf16 v[66:69], v[188:191], v[220:223], v[66:69]
	s_setprio 0
	s_add_i32 s44, s50, s9
	v_lshl_add_u64 v[154:155], v[154:155], 0, s[6:7]
	s_mov_b32 m0, s44
	ds_read_b128 v[192:195], v157 offset:49152
	ds_read_b128 v[196:199], v157 offset:50176
	ds_read_b128 v[200:203], v157 offset:51200
	ds_read_b128 v[204:207], v157 offset:52224
	ds_read_b128 v[208:211], v157 offset:53248
	ds_read_b128 v[212:215], v157 offset:54272
	ds_read_b128 v[216:219], v157 offset:55296
	ds_read_b128 v[220:223], v157 offset:56320
	global_load_lds_dwordx4 v[154:155], off
	s_add_i32 m0, s44, 0x2000
	s_add_u32 s42, s42, 0x80080
	v_lshl_add_u64 v[154:155], v[168:169], 0, s[6:7]
	s_addc_u32 s43, s43, 0
	s_add_i32 s44, s51, s9
	global_load_lds_dwordx4 v[154:155], off
	v_lshl_add_u64 v[154:155], s[42:43], 0, v[162:163]
	s_mov_b32 m0, s44
	s_nop 0
	global_load_lds_dwordx4 v[154:155], off
	v_lshl_add_u64 v[154:155], s[42:43], 0, v[142:143]
	s_add_i32 m0, s44, 0x2000
	s_nop 0
	global_load_lds_dwordx4 v[154:155], off
	v_lshl_add_u64 v[154:155], v[224:225], 0, s[6:7]
	s_mov_b32 m0, s39
	s_nop 0
	global_load_lds_dwordx4 v[154:155], off
	v_lshl_add_u64 v[154:155], v[226:227], 0, s[6:7]
	s_mov_b32 m0, s46
	s_nop 0
	global_load_lds_dwordx4 v[154:155], off
	s_waitcnt vmcnt(8)
	s_waitcnt lgkmcnt(0)
	s_barrier
	s_setprio 1
	s_waitcnt lgkmcnt(0)
	v_mfma_f32_16x16x32_bf16 v[62:65], v[130:133], v[192:195], v[62:65]
	v_mfma_f32_16x16x32_bf16 v[58:61], v[150:153], v[192:195], v[58:61]
	v_mfma_f32_16x16x32_bf16 v[46:49], v[130:133], v[200:203], v[46:49]
	v_mfma_f32_16x16x32_bf16 v[42:45], v[150:153], v[200:203], v[42:45]
	v_mfma_f32_16x16x32_bf16 v[30:33], v[130:133], v[208:211], v[30:33]
	v_mfma_f32_16x16x32_bf16 v[26:29], v[150:153], v[208:211], v[26:29]
	v_mfma_f32_16x16x32_bf16 v[14:17], v[130:133], v[216:219], v[14:17]
	v_mfma_f32_16x16x32_bf16 v[10:13], v[150:153], v[216:219], v[10:13]
	v_mfma_f32_16x16x32_bf16 v[62:65], v[134:137], v[196:199], v[62:65]
	v_mfma_f32_16x16x32_bf16 v[58:61], v[158:161], v[196:199], v[58:61]
	v_mfma_f32_16x16x32_bf16 v[46:49], v[134:137], v[204:207], v[46:49]
	v_mfma_f32_16x16x32_bf16 v[42:45], v[158:161], v[204:207], v[42:45]
	v_mfma_f32_16x16x32_bf16 v[30:33], v[134:137], v[212:215], v[30:33]
	v_mfma_f32_16x16x32_bf16 v[26:29], v[158:161], v[212:215], v[26:29]
	v_mfma_f32_16x16x32_bf16 v[14:17], v[134:137], v[220:223], v[14:17]
	v_mfma_f32_16x16x32_bf16 v[10:13], v[158:161], v[220:223], v[10:13]
	s_setprio 0
	s_setprio 1
	v_mfma_f32_16x16x32_bf16 v[54:57], v[164:167], v[192:195], v[54:57]
	v_mfma_f32_16x16x32_bf16 v[50:53], v[184:187], v[192:195], v[50:53]
	v_mfma_f32_16x16x32_bf16 v[38:41], v[164:167], v[200:203], v[38:41]
	v_mfma_f32_16x16x32_bf16 v[34:37], v[184:187], v[200:203], v[34:37]
	v_mfma_f32_16x16x32_bf16 v[22:25], v[164:167], v[208:211], v[22:25]
	v_mfma_f32_16x16x32_bf16 v[18:21], v[184:187], v[208:211], v[18:21]
	v_mfma_f32_16x16x32_bf16 v[6:9], v[164:167], v[216:219], v[6:9]
	v_mfma_f32_16x16x32_bf16 v[2:5], v[184:187], v[216:219], v[2:5]
	v_mfma_f32_16x16x32_bf16 v[54:57], v[180:183], v[196:199], v[54:57]
	v_mfma_f32_16x16x32_bf16 v[50:53], v[188:191], v[196:199], v[50:53]
	v_mfma_f32_16x16x32_bf16 v[38:41], v[180:183], v[204:207], v[38:41]
	v_mfma_f32_16x16x32_bf16 v[34:37], v[188:191], v[204:207], v[34:37]
	v_mfma_f32_16x16x32_bf16 v[22:25], v[180:183], v[212:215], v[22:25]
	v_mfma_f32_16x16x32_bf16 v[18:21], v[188:191], v[212:215], v[18:21]
	s_setprio 2
	s_barrier
	v_mfma_f32_16x16x32_bf16 v[6:9], v[180:183], v[220:223], v[6:9]
	v_mfma_f32_16x16x32_bf16 v[2:5], v[188:191], v[220:223], v[2:5]
	s_setprio 0
	s_add_i32 s49, s49, 2
	s_add_u32 s36, s36, 0x100
	s_addc_u32 s37, s37, 0
	s_add_u32 s41, s41, 0x100
	s_addc_u32 s48, s48, 0
	s_cmp_gt_u32 s49, 29
	s_cbranch_scc0 .LBB0_1115
	s_and_b64 vcc, exec, s[2:3]
	s_cbranch_vccz .LBB0_1118
	s_barrier

.LBB0_1293:
	s_ashr_i32 s19, s18, 31
	s_lshl_b64 s[8:9], s[18:19], 20
	v_readlane_b32 s5, v243, 17
	s_add_u32 s28, s5, s8
	v_readlane_b32 s5, v243, 18
	s_addc_u32 s29, s5, s9
	s_and_b64 s[8:9], s[34:35], exec
	s_cselect_b32 s8, s29, s37
	s_cselect_b32 s9, s28, s36
	s_ashr_i32 s5, s4, 31
	s_lshl_b64 s[20:21], s[4:5], 20
	s_add_u32 s38, s25, s20
	s_addc_u32 s39, s27, s21
	s_and_b64 s[20:21], s[34:35], exec
	s_cselect_b32 s5, s39, s43
	s_cselect_b32 s11, s38, s42
	s_add_u32 s36, s36, 0x80080
	s_addc_u32 s37, s37, 0
	s_add_u32 s13, s42, 0x100
	s_addc_u32 s19, s43, 0
	s_mov_b32 s20, -2
	s_waitcnt vmcnt(0) lgkmcnt(0)
	s_add_u32 s21, s36, 0xfff80080
	s_addc_u32 s23, s37, -1
	s_add_i32 s26, 0, 0x10000
	s_cmp_eq_u32 s20, 28
	s_cselect_b32 s45, s8, s23
	s_cselect_b32 s44, s9, s21
	v_add_u32_e32 v153, s26, v147
	s_cselect_b32 s43, s5, s19
	s_cselect_b32 s42, s11, s13
	s_add_i32 s21, 0, 0x14000
	ds_read_b128 v[130:133], v153
	ds_read_b128 v[134:137], v153 offset:1024
	ds_read_b128 v[164:167], v153 offset:2048
	ds_read_b128 v[182:185], v153 offset:3072
	v_add_u32_e32 v153, s21, v147
	ds_read_b128 v[186:189], v153
	ds_read_b128 v[190:193], v153 offset:1024
	ds_read_b128 v[194:197], v153 offset:2048
	ds_read_b128 v[198:201], v153 offset:3072
	v_lshl_add_u64 v[168:169], s[36:37], 0, v[148:149]
	s_add_i32 m0, s47, 0xc000
	ds_read_b128 v[202:205], v180
	ds_read_b128 v[206:209], v180 offset:1024
	ds_read_b128 v[210:213], v180 offset:2048
	ds_read_b128 v[214:217], v180 offset:3072
	ds_read_b128 v[218:221], v180 offset:4096
	ds_read_b128 v[222:225], v180 offset:5120
	ds_read_b128 v[226:229], v180 offset:6144
	ds_read_b128 v[230:233], v180 offset:7168
	global_load_lds_dwordx4 v[168:169], off
	v_lshl_add_u64 v[168:169], s[36:37], 0, v[150:151]
	s_add_i32 m0, s47, 0xe000
	s_nop 0
	global_load_lds_dwordx4 v[168:169], off
	s_waitcnt vmcnt(8)
	s_waitcnt lgkmcnt(0)
	s_barrier
	s_setprio 1
	s_waitcnt lgkmcnt(0)
	v_mfma_f32_16x16x32_bf16 v[126:129], v[130:133], v[202:205], 0
	v_mfma_f32_16x16x32_bf16 v[122:125], v[164:167], v[202:205], 0
	v_mfma_f32_16x16x32_bf16 v[110:113], v[130:133], v[210:213], 0
	v_mfma_f32_16x16x32_bf16 v[106:109], v[164:167], v[210:213], 0
	v_mfma_f32_16x16x32_bf16 v[94:97], v[130:133], v[218:221], 0
	v_mfma_f32_16x16x32_bf16 v[90:93], v[164:167], v[218:221], 0
	v_mfma_f32_16x16x32_bf16 v[78:81], v[130:133], v[226:229], 0
	v_mfma_f32_16x16x32_bf16 v[74:77], v[164:167], v[226:229], 0
	v_mfma_f32_16x16x32_bf16 v[126:129], v[134:137], v[206:209], v[126:129]
	v_mfma_f32_16x16x32_bf16 v[122:125], v[182:185], v[206:209], v[122:125]
	v_mfma_f32_16x16x32_bf16 v[110:113], v[134:137], v[214:217], v[110:113]
	v_mfma_f32_16x16x32_bf16 v[106:109], v[182:185], v[214:217], v[106:109]
	v_mfma_f32_16x16x32_bf16 v[94:97], v[134:137], v[222:225], v[94:97]
	v_mfma_f32_16x16x32_bf16 v[90:93], v[182:185], v[222:225], v[90:93]
	v_mfma_f32_16x16x32_bf16 v[78:81], v[134:137], v[230:233], v[78:81]
	v_mfma_f32_16x16x32_bf16 v[74:77], v[182:185], v[230:233], v[74:77]
	s_setprio 0
	s_setprio 1
	v_mfma_f32_16x16x32_bf16 v[118:121], v[186:189], v[202:205], 0
	v_mfma_f32_16x16x32_bf16 v[114:117], v[194:197], v[202:205], 0
	v_mfma_f32_16x16x32_bf16 v[102:105], v[186:189], v[210:213], 0
	v_mfma_f32_16x16x32_bf16 v[98:101], v[194:197], v[210:213], 0
	v_mfma_f32_16x16x32_bf16 v[86:89], v[186:189], v[218:221], 0
	v_mfma_f32_16x16x32_bf16 v[82:85], v[194:197], v[218:221], 0
	v_mfma_f32_16x16x32_bf16 v[70:73], v[186:189], v[226:229], 0
	v_mfma_f32_16x16x32_bf16 v[66:69], v[194:197], v[226:229], 0
	v_mfma_f32_16x16x32_bf16 v[118:121], v[190:193], v[206:209], v[118:121]
	v_mfma_f32_16x16x32_bf16 v[114:117], v[198:201], v[206:209], v[114:117]
	v_mfma_f32_16x16x32_bf16 v[102:105], v[190:193], v[214:217], v[102:105]
	v_mfma_f32_16x16x32_bf16 v[98:101], v[198:201], v[214:217], v[98:101]
	v_mfma_f32_16x16x32_bf16 v[86:89], v[190:193], v[222:225], v[86:89]
	v_mfma_f32_16x16x32_bf16 v[82:85], v[198:201], v[222:225], v[82:85]
	s_setprio 2
	s_barrier
	v_mfma_f32_16x16x32_bf16 v[70:73], v[190:193], v[230:233], v[70:73]
	v_mfma_f32_16x16x32_bf16 v[66:69], v[198:201], v[230:233], v[66:69]
	s_setprio 0
	s_add_i32 s23, s26, s46
	v_lshl_add_u64 v[168:169], s[42:43], 0, v[162:163]
	s_mov_b32 m0, s23
	ds_read_b128 v[202:205], v180 offset:16384
	ds_read_b128 v[206:209], v180 offset:17408
	ds_read_b128 v[210:213], v180 offset:18432
	ds_read_b128 v[214:217], v180 offset:19456
	ds_read_b128 v[218:221], v180 offset:20480
	ds_read_b128 v[222:225], v180 offset:21504
	ds_read_b128 v[226:229], v180 offset:22528
	ds_read_b128 v[230:233], v180 offset:23552
	global_load_lds_dwordx4 v[168:169], off
	s_add_i32 m0, s23, 0x2000
	s_add_u32 s54, s42, 0x80000
	v_lshl_add_u64 v[234:235], s[42:43], 0, v[142:143]
	s_addc_u32 s55, s43, 0
	s_add_i32 s21, s21, s46
	global_load_lds_dwordx4 v[234:235], off
	v_lshl_add_u64 v[236:237], s[54:55], 0, v[162:163]
	s_mov_b32 m0, s21
	v_lshl_add_u64 v[238:239], s[44:45], 0, v[140:141]
	global_load_lds_dwordx4 v[236:237], off
	v_lshl_add_u64 v[236:237], s[54:55], 0, v[142:143]
	s_add_i32 m0, s21, 0x2000
	s_nop 0
	global_load_lds_dwordx4 v[236:237], off
	v_lshl_add_u64 v[236:237], s[44:45], 0, v[138:139]
	s_mov_b32 m0, s47
	s_nop 0
	global_load_lds_dwordx4 v[236:237], off
	s_mov_b32 m0, s48
	s_nop 0
	global_load_lds_dwordx4 v[238:239], off
	s_waitcnt vmcnt(8)
	s_waitcnt lgkmcnt(0)
	s_barrier
	s_setprio 1
	s_waitcnt lgkmcnt(0)
	v_mfma_f32_16x16x32_bf16 v[62:65], v[130:133], v[202:205], 0
	v_mfma_f32_16x16x32_bf16 v[58:61], v[164:167], v[202:205], 0
	v_mfma_f32_16x16x32_bf16 v[46:49], v[130:133], v[210:213], 0
	v_mfma_f32_16x16x32_bf16 v[42:45], v[164:167], v[210:213], 0
	v_mfma_f32_16x16x32_bf16 v[30:33], v[130:133], v[218:221], 0
	v_mfma_f32_16x16x32_bf16 v[26:29], v[164:167], v[218:221], 0
	v_mfma_f32_16x16x32_bf16 v[14:17], v[130:133], v[226:229], 0
	v_mfma_f32_16x16x32_bf16 v[10:13], v[164:167], v[226:229], 0
	v_mfma_f32_16x16x32_bf16 v[62:65], v[134:137], v[206:209], v[62:65]
	v_mfma_f32_16x16x32_bf16 v[58:61], v[182:185], v[206:209], v[58:61]
	v_mfma_f32_16x16x32_bf16 v[46:49], v[134:137], v[214:217], v[46:49]
	v_mfma_f32_16x16x32_bf16 v[42:45], v[182:185], v[214:217], v[42:45]
	v_mfma_f32_16x16x32_bf16 v[30:33], v[134:137], v[222:225], v[30:33]
	v_mfma_f32_16x16x32_bf16 v[26:29], v[182:185], v[222:225], v[26:29]
	v_mfma_f32_16x16x32_bf16 v[14:17], v[134:137], v[230:233], v[14:17]
	v_mfma_f32_16x16x32_bf16 v[10:13], v[182:185], v[230:233], v[10:13]
	s_setprio 0
	s_setprio 1
	v_mfma_f32_16x16x32_bf16 v[54:57], v[186:189], v[202:205], 0
	v_mfma_f32_16x16x32_bf16 v[50:53], v[194:197], v[202:205], 0
	v_mfma_f32_16x16x32_bf16 v[38:41], v[186:189], v[210:213], 0
	v_mfma_f32_16x16x32_bf16 v[34:37], v[194:197], v[210:213], 0
	v_mfma_f32_16x16x32_bf16 v[22:25], v[186:189], v[218:221], 0
	v_mfma_f32_16x16x32_bf16 v[18:21], v[194:197], v[218:221], 0
	v_mfma_f32_16x16x32_bf16 v[6:9], v[186:189], v[226:229], 0
	v_mfma_f32_16x16x32_bf16 v[2:5], v[194:197], v[226:229], 0
	v_mfma_f32_16x16x32_bf16 v[54:57], v[190:193], v[206:209], v[54:57]
	v_mfma_f32_16x16x32_bf16 v[50:53], v[198:201], v[206:209], v[50:53]
	v_mfma_f32_16x16x32_bf16 v[38:41], v[190:193], v[214:217], v[38:41]
	v_mfma_f32_16x16x32_bf16 v[34:37], v[198:201], v[214:217], v[34:37]
	v_mfma_f32_16x16x32_bf16 v[22:25], v[190:193], v[222:225], v[22:25]
	v_mfma_f32_16x16x32_bf16 v[18:21], v[198:201], v[222:225], v[18:21]
	s_setprio 2
	s_barrier
	v_mfma_f32_16x16x32_bf16 v[6:9], v[190:193], v[230:233], v[6:9]
	v_mfma_f32_16x16x32_bf16 v[2:5], v[198:201], v[230:233], v[2:5]
	s_setprio 0
	s_add_i32 s21, 0, 0x18000
	v_add_u32_e32 v153, s21, v147
	s_add_i32 s23, 0, 0x1c000
	ds_read_b128 v[130:133], v153
	ds_read_b128 v[134:137], v153 offset:1024
	ds_read_b128 v[164:167], v153 offset:2048
	ds_read_b128 v[182:185], v153 offset:3072
	v_add_u32_e32 v153, s23, v147
	ds_read_b128 v[186:189], v153
	ds_read_b128 v[190:193], v153 offset:1024
	ds_read_b128 v[194:197], v153 offset:2048
	ds_read_b128 v[198:201], v153 offset:3072
	s_add_u32 s44, s44, 0x80000
	s_addc_u32 s45, s45, 0
	s_mov_b32 m0, s49
	v_lshl_add_u64 v[240:241], s[44:45], 0, v[138:139]
	ds_read_b128 v[202:205], v180 offset:32768
	ds_read_b128 v[206:209], v180 offset:33792
	ds_read_b128 v[210:213], v180 offset:34816
	ds_read_b128 v[214:217], v180 offset:35840
	ds_read_b128 v[218:221], v180 offset:36864
	ds_read_b128 v[222:225], v180 offset:37888
	ds_read_b128 v[226:229], v180 offset:38912
	ds_read_b128 v[230:233], v180 offset:39936
	global_load_lds_dwordx4 v[240:241], off
	v_lshl_add_u64 v[240:241], s[44:45], 0, v[140:141]
	s_mov_b32 m0, s50
	s_nop 0
	global_load_lds_dwordx4 v[240:241], off
	s_waitcnt vmcnt(8)
	s_waitcnt lgkmcnt(0)
	s_barrier
	s_setprio 1
	s_waitcnt lgkmcnt(0)
	v_mfma_f32_16x16x32_bf16 v[126:129], v[130:133], v[202:205], v[126:129]
	v_mfma_f32_16x16x32_bf16 v[122:125], v[164:167], v[202:205], v[122:125]
	v_mfma_f32_16x16x32_bf16 v[110:113], v[130:133], v[210:213], v[110:113]
	v_mfma_f32_16x16x32_bf16 v[106:109], v[164:167], v[210:213], v[106:109]
	v_mfma_f32_16x16x32_bf16 v[94:97], v[130:133], v[218:221], v[94:97]
	v_mfma_f32_16x16x32_bf16 v[90:93], v[164:167], v[218:221], v[90:93]
	v_mfma_f32_16x16x32_bf16 v[78:81], v[130:133], v[226:229], v[78:81]
	v_mfma_f32_16x16x32_bf16 v[74:77], v[164:167], v[226:229], v[74:77]
	v_mfma_f32_16x16x32_bf16 v[126:129], v[134:137], v[206:209], v[126:129]
	v_mfma_f32_16x16x32_bf16 v[122:125], v[182:185], v[206:209], v[122:125]
	v_mfma_f32_16x16x32_bf16 v[110:113], v[134:137], v[214:217], v[110:113]
	v_mfma_f32_16x16x32_bf16 v[106:109], v[182:185], v[214:217], v[106:109]
	v_mfma_f32_16x16x32_bf16 v[94:97], v[134:137], v[222:225], v[94:97]
	v_mfma_f32_16x16x32_bf16 v[90:93], v[182:185], v[222:225], v[90:93]
	v_mfma_f32_16x16x32_bf16 v[78:81], v[134:137], v[230:233], v[78:81]
	v_mfma_f32_16x16x32_bf16 v[74:77], v[182:185], v[230:233], v[74:77]
	s_setprio 0
	s_setprio 1
	v_mfma_f32_16x16x32_bf16 v[118:121], v[186:189], v[202:205], v[118:121]
	v_mfma_f32_16x16x32_bf16 v[114:117], v[194:197], v[202:205], v[114:117]
	v_mfma_f32_16x16x32_bf16 v[102:105], v[186:189], v[210:213], v[102:105]
	v_mfma_f32_16x16x32_bf16 v[98:101], v[194:197], v[210:213], v[98:101]
	v_mfma_f32_16x16x32_bf16 v[86:89], v[186:189], v[218:221], v[86:89]
	v_mfma_f32_16x16x32_bf16 v[82:85], v[194:197], v[218:221], v[82:85]
	v_mfma_f32_16x16x32_bf16 v[70:73], v[186:189], v[226:229], v[70:73]
	v_mfma_f32_16x16x32_bf16 v[66:69], v[194:197], v[226:229], v[66:69]
	v_mfma_f32_16x16x32_bf16 v[118:121], v[190:193], v[206:209], v[118:121]
	v_mfma_f32_16x16x32_bf16 v[114:117], v[198:201], v[206:209], v[114:117]
	v_mfma_f32_16x16x32_bf16 v[102:105], v[190:193], v[214:217], v[102:105]
	v_mfma_f32_16x16x32_bf16 v[98:101], v[198:201], v[214:217], v[98:101]
	v_mfma_f32_16x16x32_bf16 v[86:89], v[190:193], v[222:225], v[86:89]
	v_mfma_f32_16x16x32_bf16 v[82:85], v[198:201], v[222:225], v[82:85]
	s_setprio 2
	s_barrier
	v_mfma_f32_16x16x32_bf16 v[70:73], v[190:193], v[230:233], v[70:73]
	v_mfma_f32_16x16x32_bf16 v[66:69], v[198:201], v[230:233], v[66:69]
	s_setprio 0
	s_add_i32 s21, s21, s46
	v_lshl_add_u64 v[168:169], v[168:169], 0, s[6:7]
	s_mov_b32 m0, s21
	ds_read_b128 v[202:205], v180 offset:49152
	ds_read_b128 v[206:209], v180 offset:50176
	ds_read_b128 v[210:213], v180 offset:51200
	ds_read_b128 v[214:217], v180 offset:52224
	ds_read_b128 v[218:221], v180 offset:53248
	ds_read_b128 v[222:225], v180 offset:54272
	ds_read_b128 v[226:229], v180 offset:55296
	ds_read_b128 v[230:233], v180 offset:56320
	global_load_lds_dwordx4 v[168:169], off
	s_add_i32 m0, s21, 0x2000
	s_add_u32 s42, s42, 0x80080
	v_lshl_add_u64 v[168:169], v[234:235], 0, s[6:7]
	s_addc_u32 s43, s43, 0
	s_add_i32 s21, s23, s46
	global_load_lds_dwordx4 v[168:169], off
	v_lshl_add_u64 v[168:169], s[42:43], 0, v[162:163]
	s_mov_b32 m0, s21
	s_nop 0
	global_load_lds_dwordx4 v[168:169], off
	v_lshl_add_u64 v[168:169], s[42:43], 0, v[142:143]
	s_add_i32 m0, s21, 0x2000
	s_nop 0
	global_load_lds_dwordx4 v[168:169], off
	v_lshl_add_u64 v[168:169], v[236:237], 0, s[6:7]
	s_mov_b32 m0, s51
	s_nop 0
	global_load_lds_dwordx4 v[168:169], off
	v_lshl_add_u64 v[168:169], v[238:239], 0, s[6:7]
	s_mov_b32 m0, s52
	s_nop 0
	global_load_lds_dwordx4 v[168:169], off
	s_waitcnt vmcnt(8)
	s_waitcnt lgkmcnt(0)
	s_barrier
	s_setprio 1
	s_waitcnt lgkmcnt(0)
	v_mfma_f32_16x16x32_bf16 v[62:65], v[130:133], v[202:205], v[62:65]
	v_mfma_f32_16x16x32_bf16 v[58:61], v[164:167], v[202:205], v[58:61]
	v_mfma_f32_16x16x32_bf16 v[46:49], v[130:133], v[210:213], v[46:49]
	v_mfma_f32_16x16x32_bf16 v[42:45], v[164:167], v[210:213], v[42:45]
	v_mfma_f32_16x16x32_bf16 v[30:33], v[130:133], v[218:221], v[30:33]
	v_mfma_f32_16x16x32_bf16 v[26:29], v[164:167], v[218:221], v[26:29]
	v_mfma_f32_16x16x32_bf16 v[14:17], v[130:133], v[226:229], v[14:17]
	v_mfma_f32_16x16x32_bf16 v[10:13], v[164:167], v[226:229], v[10:13]
	v_mfma_f32_16x16x32_bf16 v[62:65], v[134:137], v[206:209], v[62:65]
	v_mfma_f32_16x16x32_bf16 v[58:61], v[182:185], v[206:209], v[58:61]
	v_mfma_f32_16x16x32_bf16 v[46:49], v[134:137], v[214:217], v[46:49]
	v_mfma_f32_16x16x32_bf16 v[42:45], v[182:185], v[214:217], v[42:45]
	v_mfma_f32_16x16x32_bf16 v[30:33], v[134:137], v[222:225], v[30:33]
	v_mfma_f32_16x16x32_bf16 v[26:29], v[182:185], v[222:225], v[26:29]
	v_mfma_f32_16x16x32_bf16 v[14:17], v[134:137], v[230:233], v[14:17]
	v_mfma_f32_16x16x32_bf16 v[10:13], v[182:185], v[230:233], v[10:13]
	s_setprio 0
	s_setprio 1
	v_mfma_f32_16x16x32_bf16 v[54:57], v[186:189], v[202:205], v[54:57]
	v_mfma_f32_16x16x32_bf16 v[50:53], v[194:197], v[202:205], v[50:53]
	v_mfma_f32_16x16x32_bf16 v[38:41], v[186:189], v[210:213], v[38:41]
	v_mfma_f32_16x16x32_bf16 v[34:37], v[194:197], v[210:213], v[34:37]
	v_mfma_f32_16x16x32_bf16 v[22:25], v[186:189], v[218:221], v[22:25]
	v_mfma_f32_16x16x32_bf16 v[18:21], v[194:197], v[218:221], v[18:21]
	v_mfma_f32_16x16x32_bf16 v[6:9], v[186:189], v[226:229], v[6:9]
	v_mfma_f32_16x16x32_bf16 v[2:5], v[194:197], v[226:229], v[2:5]
	v_mfma_f32_16x16x32_bf16 v[54:57], v[190:193], v[206:209], v[54:57]
	v_mfma_f32_16x16x32_bf16 v[50:53], v[198:201], v[206:209], v[50:53]
	v_mfma_f32_16x16x32_bf16 v[38:41], v[190:193], v[214:217], v[38:41]
	v_mfma_f32_16x16x32_bf16 v[34:37], v[198:201], v[214:217], v[34:37]
	v_mfma_f32_16x16x32_bf16 v[22:25], v[190:193], v[222:225], v[22:25]
	v_mfma_f32_16x16x32_bf16 v[18:21], v[198:201], v[222:225], v[18:21]
	s_setprio 2
	s_barrier
	v_mfma_f32_16x16x32_bf16 v[6:9], v[190:193], v[230:233], v[6:9]
	v_mfma_f32_16x16x32_bf16 v[2:5], v[198:201], v[230:233], v[2:5]
	s_setprio 0
	s_add_i32 s20, s20, 2
	s_add_u32 s36, s36, 0x100
	s_addc_u32 s37, s37, 0
	s_add_u32 s13, s13, 0x100
	s_addc_u32 s19, s19, 0
	s_cmp_gt_u32 s20, 29
.LBB0_1294:
	s_add_u32 s21, s36, 0xfff80080
	s_addc_u32 s23, s37, -1
	s_add_i32 s26, 0, 0x10000
	s_cmp_eq_u32 s20, 28
	s_cselect_b32 s45, s8, s23
	s_cselect_b32 s44, s9, s21
	v_add_u32_e32 v153, s26, v147
	s_cselect_b32 s43, s5, s19
	s_cselect_b32 s42, s11, s13
	s_add_i32 s21, 0, 0x14000
	ds_read_b128 v[130:133], v153
	ds_read_b128 v[134:137], v153 offset:1024
	ds_read_b128 v[164:167], v153 offset:2048
	ds_read_b128 v[182:185], v153 offset:3072
	v_add_u32_e32 v153, s21, v147
	ds_read_b128 v[186:189], v153
	ds_read_b128 v[190:193], v153 offset:1024
	ds_read_b128 v[194:197], v153 offset:2048
	ds_read_b128 v[198:201], v153 offset:3072
	v_lshl_add_u64 v[168:169], s[36:37], 0, v[148:149]
	s_add_i32 m0, s47, 0xc000
	ds_read_b128 v[202:205], v180
	ds_read_b128 v[206:209], v180 offset:1024
	ds_read_b128 v[210:213], v180 offset:2048
	ds_read_b128 v[214:217], v180 offset:3072
	ds_read_b128 v[218:221], v180 offset:4096
	ds_read_b128 v[222:225], v180 offset:5120
	ds_read_b128 v[226:229], v180 offset:6144
	ds_read_b128 v[230:233], v180 offset:7168
	global_load_lds_dwordx4 v[168:169], off
	v_lshl_add_u64 v[168:169], s[36:37], 0, v[150:151]
	s_add_i32 m0, s47, 0xe000
	s_nop 0
	global_load_lds_dwordx4 v[168:169], off
	s_waitcnt vmcnt(8)
	s_waitcnt lgkmcnt(0)
	s_barrier
	s_setprio 1
	s_waitcnt lgkmcnt(0)
	v_mfma_f32_16x16x32_bf16 v[126:129], v[130:133], v[202:205], v[126:129]
	v_mfma_f32_16x16x32_bf16 v[122:125], v[164:167], v[202:205], v[122:125]
	v_mfma_f32_16x16x32_bf16 v[110:113], v[130:133], v[210:213], v[110:113]
	v_mfma_f32_16x16x32_bf16 v[106:109], v[164:167], v[210:213], v[106:109]
	v_mfma_f32_16x16x32_bf16 v[94:97], v[130:133], v[218:221], v[94:97]
	v_mfma_f32_16x16x32_bf16 v[90:93], v[164:167], v[218:221], v[90:93]
	v_mfma_f32_16x16x32_bf16 v[78:81], v[130:133], v[226:229], v[78:81]
	v_mfma_f32_16x16x32_bf16 v[74:77], v[164:167], v[226:229], v[74:77]
	v_mfma_f32_16x16x32_bf16 v[126:129], v[134:137], v[206:209], v[126:129]
	v_mfma_f32_16x16x32_bf16 v[122:125], v[182:185], v[206:209], v[122:125]
	v_mfma_f32_16x16x32_bf16 v[110:113], v[134:137], v[214:217], v[110:113]
	v_mfma_f32_16x16x32_bf16 v[106:109], v[182:185], v[214:217], v[106:109]
	v_mfma_f32_16x16x32_bf16 v[94:97], v[134:137], v[222:225], v[94:97]
	v_mfma_f32_16x16x32_bf16 v[90:93], v[182:185], v[222:225], v[90:93]
	v_mfma_f32_16x16x32_bf16 v[78:81], v[134:137], v[230:233], v[78:81]
	v_mfma_f32_16x16x32_bf16 v[74:77], v[182:185], v[230:233], v[74:77]
	s_setprio 0
	s_setprio 1
	v_mfma_f32_16x16x32_bf16 v[118:121], v[186:189], v[202:205], v[118:121]
	v_mfma_f32_16x16x32_bf16 v[114:117], v[194:197], v[202:205], v[114:117]
	v_mfma_f32_16x16x32_bf16 v[102:105], v[186:189], v[210:213], v[102:105]
	v_mfma_f32_16x16x32_bf16 v[98:101], v[194:197], v[210:213], v[98:101]
	v_mfma_f32_16x16x32_bf16 v[86:89], v[186:189], v[218:221], v[86:89]
	v_mfma_f32_16x16x32_bf16 v[82:85], v[194:197], v[218:221], v[82:85]
	v_mfma_f32_16x16x32_bf16 v[70:73], v[186:189], v[226:229], v[70:73]
	v_mfma_f32_16x16x32_bf16 v[66:69], v[194:197], v[226:229], v[66:69]
	v_mfma_f32_16x16x32_bf16 v[118:121], v[190:193], v[206:209], v[118:121]
	v_mfma_f32_16x16x32_bf16 v[114:117], v[198:201], v[206:209], v[114:117]
	v_mfma_f32_16x16x32_bf16 v[102:105], v[190:193], v[214:217], v[102:105]
	v_mfma_f32_16x16x32_bf16 v[98:101], v[198:201], v[214:217], v[98:101]
	v_mfma_f32_16x16x32_bf16 v[86:89], v[190:193], v[222:225], v[86:89]
	v_mfma_f32_16x16x32_bf16 v[82:85], v[198:201], v[222:225], v[82:85]
	s_setprio 2
	s_barrier
	v_mfma_f32_16x16x32_bf16 v[70:73], v[190:193], v[230:233], v[70:73]
	v_mfma_f32_16x16x32_bf16 v[66:69], v[198:201], v[230:233], v[66:69]
	s_setprio 0
	s_add_i32 s23, s26, s46
	v_lshl_add_u64 v[168:169], s[42:43], 0, v[162:163]
	s_mov_b32 m0, s23
	ds_read_b128 v[202:205], v180 offset:16384
	ds_read_b128 v[206:209], v180 offset:17408
	ds_read_b128 v[210:213], v180 offset:18432
	ds_read_b128 v[214:217], v180 offset:19456
	ds_read_b128 v[218:221], v180 offset:20480
	ds_read_b128 v[222:225], v180 offset:21504
	ds_read_b128 v[226:229], v180 offset:22528
	ds_read_b128 v[230:233], v180 offset:23552
	global_load_lds_dwordx4 v[168:169], off
	s_add_i32 m0, s23, 0x2000
	s_add_u32 s54, s42, 0x80000
	v_lshl_add_u64 v[234:235], s[42:43], 0, v[142:143]
	s_addc_u32 s55, s43, 0
	s_add_i32 s21, s21, s46
	global_load_lds_dwordx4 v[234:235], off
	v_lshl_add_u64 v[236:237], s[54:55], 0, v[162:163]
	s_mov_b32 m0, s21
	v_lshl_add_u64 v[238:239], s[44:45], 0, v[140:141]
	global_load_lds_dwordx4 v[236:237], off
	v_lshl_add_u64 v[236:237], s[54:55], 0, v[142:143]
	s_add_i32 m0, s21, 0x2000
	s_nop 0
	global_load_lds_dwordx4 v[236:237], off
	v_lshl_add_u64 v[236:237], s[44:45], 0, v[138:139]
	s_mov_b32 m0, s47
	s_nop 0
	global_load_lds_dwordx4 v[236:237], off
	s_mov_b32 m0, s48
	s_nop 0
	global_load_lds_dwordx4 v[238:239], off
	s_waitcnt vmcnt(8)
	s_waitcnt lgkmcnt(0)
	s_barrier
	s_setprio 1
	s_waitcnt lgkmcnt(0)
	v_mfma_f32_16x16x32_bf16 v[62:65], v[130:133], v[202:205], v[62:65]
	v_mfma_f32_16x16x32_bf16 v[58:61], v[164:167], v[202:205], v[58:61]
	v_mfma_f32_16x16x32_bf16 v[46:49], v[130:133], v[210:213], v[46:49]
	v_mfma_f32_16x16x32_bf16 v[42:45], v[164:167], v[210:213], v[42:45]
	v_mfma_f32_16x16x32_bf16 v[30:33], v[130:133], v[218:221], v[30:33]
	v_mfma_f32_16x16x32_bf16 v[26:29], v[164:167], v[218:221], v[26:29]
	v_mfma_f32_16x16x32_bf16 v[14:17], v[130:133], v[226:229], v[14:17]
	v_mfma_f32_16x16x32_bf16 v[10:13], v[164:167], v[226:229], v[10:13]
	v_mfma_f32_16x16x32_bf16 v[62:65], v[134:137], v[206:209], v[62:65]
	v_mfma_f32_16x16x32_bf16 v[58:61], v[182:185], v[206:209], v[58:61]
	v_mfma_f32_16x16x32_bf16 v[46:49], v[134:137], v[214:217], v[46:49]
	v_mfma_f32_16x16x32_bf16 v[42:45], v[182:185], v[214:217], v[42:45]
	v_mfma_f32_16x16x32_bf16 v[30:33], v[134:137], v[222:225], v[30:33]
	v_mfma_f32_16x16x32_bf16 v[26:29], v[182:185], v[222:225], v[26:29]
	v_mfma_f32_16x16x32_bf16 v[14:17], v[134:137], v[230:233], v[14:17]
	v_mfma_f32_16x16x32_bf16 v[10:13], v[182:185], v[230:233], v[10:13]
	s_setprio 0
	s_setprio 1
	v_mfma_f32_16x16x32_bf16 v[54:57], v[186:189], v[202:205], v[54:57]
	v_mfma_f32_16x16x32_bf16 v[50:53], v[194:197], v[202:205], v[50:53]
	v_mfma_f32_16x16x32_bf16 v[38:41], v[186:189], v[210:213], v[38:41]
	v_mfma_f32_16x16x32_bf16 v[34:37], v[194:197], v[210:213], v[34:37]
	v_mfma_f32_16x16x32_bf16 v[22:25], v[186:189], v[218:221], v[22:25]
	v_mfma_f32_16x16x32_bf16 v[18:21], v[194:197], v[218:221], v[18:21]
	v_mfma_f32_16x16x32_bf16 v[6:9], v[186:189], v[226:229], v[6:9]
	v_mfma_f32_16x16x32_bf16 v[2:5], v[194:197], v[226:229], v[2:5]
	v_mfma_f32_16x16x32_bf16 v[54:57], v[190:193], v[206:209], v[54:57]
	v_mfma_f32_16x16x32_bf16 v[50:53], v[198:201], v[206:209], v[50:53]
	v_mfma_f32_16x16x32_bf16 v[38:41], v[190:193], v[214:217], v[38:41]
	v_mfma_f32_16x16x32_bf16 v[34:37], v[198:201], v[214:217], v[34:37]
	v_mfma_f32_16x16x32_bf16 v[22:25], v[190:193], v[222:225], v[22:25]
	v_mfma_f32_16x16x32_bf16 v[18:21], v[198:201], v[222:225], v[18:21]
	s_setprio 2
	s_barrier
	v_mfma_f32_16x16x32_bf16 v[6:9], v[190:193], v[230:233], v[6:9]
	v_mfma_f32_16x16x32_bf16 v[2:5], v[198:201], v[230:233], v[2:5]
	s_setprio 0
	s_add_i32 s21, 0, 0x18000
	v_add_u32_e32 v153, s21, v147
	s_add_i32 s23, 0, 0x1c000
	ds_read_b128 v[130:133], v153
	ds_read_b128 v[134:137], v153 offset:1024
	ds_read_b128 v[164:167], v153 offset:2048
	ds_read_b128 v[182:185], v153 offset:3072
	v_add_u32_e32 v153, s23, v147
	ds_read_b128 v[186:189], v153
	ds_read_b128 v[190:193], v153 offset:1024
	ds_read_b128 v[194:197], v153 offset:2048
	ds_read_b128 v[198:201], v153 offset:3072
	s_add_u32 s44, s44, 0x80000
	s_addc_u32 s45, s45, 0
	s_mov_b32 m0, s49
	v_lshl_add_u64 v[240:241], s[44:45], 0, v[138:139]
	ds_read_b128 v[202:205], v180 offset:32768
	ds_read_b128 v[206:209], v180 offset:33792
	ds_read_b128 v[210:213], v180 offset:34816
	ds_read_b128 v[214:217], v180 offset:35840
	ds_read_b128 v[218:221], v180 offset:36864
	ds_read_b128 v[222:225], v180 offset:37888
	ds_read_b128 v[226:229], v180 offset:38912
	ds_read_b128 v[230:233], v180 offset:39936
	global_load_lds_dwordx4 v[240:241], off
	v_lshl_add_u64 v[240:241], s[44:45], 0, v[140:141]
	s_mov_b32 m0, s50
	s_nop 0
	global_load_lds_dwordx4 v[240:241], off
	s_waitcnt vmcnt(8)
	s_waitcnt lgkmcnt(0)
	s_barrier
	s_setprio 1
	s_waitcnt lgkmcnt(0)
	v_mfma_f32_16x16x32_bf16 v[126:129], v[130:133], v[202:205], v[126:129]
	v_mfma_f32_16x16x32_bf16 v[122:125], v[164:167], v[202:205], v[122:125]
	v_mfma_f32_16x16x32_bf16 v[110:113], v[130:133], v[210:213], v[110:113]
	v_mfma_f32_16x16x32_bf16 v[106:109], v[164:167], v[210:213], v[106:109]
	v_mfma_f32_16x16x32_bf16 v[94:97], v[130:133], v[218:221], v[94:97]
	v_mfma_f32_16x16x32_bf16 v[90:93], v[164:167], v[218:221], v[90:93]
	v_mfma_f32_16x16x32_bf16 v[78:81], v[130:133], v[226:229], v[78:81]
	v_mfma_f32_16x16x32_bf16 v[74:77], v[164:167], v[226:229], v[74:77]
	v_mfma_f32_16x16x32_bf16 v[126:129], v[134:137], v[206:209], v[126:129]
	v_mfma_f32_16x16x32_bf16 v[122:125], v[182:185], v[206:209], v[122:125]
	v_mfma_f32_16x16x32_bf16 v[110:113], v[134:137], v[214:217], v[110:113]
	v_mfma_f32_16x16x32_bf16 v[106:109], v[182:185], v[214:217], v[106:109]
	v_mfma_f32_16x16x32_bf16 v[94:97], v[134:137], v[222:225], v[94:97]
	v_mfma_f32_16x16x32_bf16 v[90:93], v[182:185], v[222:225], v[90:93]
	v_mfma_f32_16x16x32_bf16 v[78:81], v[134:137], v[230:233], v[78:81]
	v_mfma_f32_16x16x32_bf16 v[74:77], v[182:185], v[230:233], v[74:77]
	s_setprio 0
	s_setprio 1
	v_mfma_f32_16x16x32_bf16 v[118:121], v[186:189], v[202:205], v[118:121]
	v_mfma_f32_16x16x32_bf16 v[114:117], v[194:197], v[202:205], v[114:117]
	v_mfma_f32_16x16x32_bf16 v[102:105], v[186:189], v[210:213], v[102:105]
	v_mfma_f32_16x16x32_bf16 v[98:101], v[194:197], v[210:213], v[98:101]
	v_mfma_f32_16x16x32_bf16 v[86:89], v[186:189], v[218:221], v[86:89]
	v_mfma_f32_16x16x32_bf16 v[82:85], v[194:197], v[218:221], v[82:85]
	v_mfma_f32_16x16x32_bf16 v[70:73], v[186:189], v[226:229], v[70:73]
	v_mfma_f32_16x16x32_bf16 v[66:69], v[194:197], v[226:229], v[66:69]
	v_mfma_f32_16x16x32_bf16 v[118:121], v[190:193], v[206:209], v[118:121]
	v_mfma_f32_16x16x32_bf16 v[114:117], v[198:201], v[206:209], v[114:117]
	v_mfma_f32_16x16x32_bf16 v[102:105], v[190:193], v[214:217], v[102:105]
	v_mfma_f32_16x16x32_bf16 v[98:101], v[198:201], v[214:217], v[98:101]
	v_mfma_f32_16x16x32_bf16 v[86:89], v[190:193], v[222:225], v[86:89]
	v_mfma_f32_16x16x32_bf16 v[82:85], v[198:201], v[222:225], v[82:85]
	s_setprio 2
	s_barrier
	v_mfma_f32_16x16x32_bf16 v[70:73], v[190:193], v[230:233], v[70:73]
	v_mfma_f32_16x16x32_bf16 v[66:69], v[198:201], v[230:233], v[66:69]
	s_setprio 0
	s_add_i32 s21, s21, s46
	v_lshl_add_u64 v[168:169], v[168:169], 0, s[6:7]
	s_mov_b32 m0, s21
	ds_read_b128 v[202:205], v180 offset:49152
	ds_read_b128 v[206:209], v180 offset:50176
	ds_read_b128 v[210:213], v180 offset:51200
	ds_read_b128 v[214:217], v180 offset:52224
	ds_read_b128 v[218:221], v180 offset:53248
	ds_read_b128 v[222:225], v180 offset:54272
	ds_read_b128 v[226:229], v180 offset:55296
	ds_read_b128 v[230:233], v180 offset:56320
	global_load_lds_dwordx4 v[168:169], off
	s_add_i32 m0, s21, 0x2000
	s_add_u32 s42, s42, 0x80080
	v_lshl_add_u64 v[168:169], v[234:235], 0, s[6:7]
	s_addc_u32 s43, s43, 0
	s_add_i32 s21, s23, s46
	global_load_lds_dwordx4 v[168:169], off
	v_lshl_add_u64 v[168:169], s[42:43], 0, v[162:163]
	s_mov_b32 m0, s21
	s_nop 0
	global_load_lds_dwordx4 v[168:169], off
	v_lshl_add_u64 v[168:169], s[42:43], 0, v[142:143]
	s_add_i32 m0, s21, 0x2000
	s_nop 0
	global_load_lds_dwordx4 v[168:169], off
	v_lshl_add_u64 v[168:169], v[236:237], 0, s[6:7]
	s_mov_b32 m0, s51
	s_nop 0
	global_load_lds_dwordx4 v[168:169], off
	v_lshl_add_u64 v[168:169], v[238:239], 0, s[6:7]
	s_mov_b32 m0, s52
	s_nop 0
	global_load_lds_dwordx4 v[168:169], off
	s_waitcnt vmcnt(8)
	s_waitcnt lgkmcnt(0)
	s_barrier
	s_setprio 1
	s_waitcnt lgkmcnt(0)
	v_mfma_f32_16x16x32_bf16 v[62:65], v[130:133], v[202:205], v[62:65]
	v_mfma_f32_16x16x32_bf16 v[58:61], v[164:167], v[202:205], v[58:61]
	v_mfma_f32_16x16x32_bf16 v[46:49], v[130:133], v[210:213], v[46:49]
	v_mfma_f32_16x16x32_bf16 v[42:45], v[164:167], v[210:213], v[42:45]
	v_mfma_f32_16x16x32_bf16 v[30:33], v[130:133], v[218:221], v[30:33]
	v_mfma_f32_16x16x32_bf16 v[26:29], v[164:167], v[218:221], v[26:29]
	v_mfma_f32_16x16x32_bf16 v[14:17], v[130:133], v[226:229], v[14:17]
	v_mfma_f32_16x16x32_bf16 v[10:13], v[164:167], v[226:229], v[10:13]
	v_mfma_f32_16x16x32_bf16 v[62:65], v[134:137], v[206:209], v[62:65]
	v_mfma_f32_16x16x32_bf16 v[58:61], v[182:185], v[206:209], v[58:61]
	v_mfma_f32_16x16x32_bf16 v[46:49], v[134:137], v[214:217], v[46:49]
	v_mfma_f32_16x16x32_bf16 v[42:45], v[182:185], v[214:217], v[42:45]
	v_mfma_f32_16x16x32_bf16 v[30:33], v[134:137], v[222:225], v[30:33]
	v_mfma_f32_16x16x32_bf16 v[26:29], v[182:185], v[222:225], v[26:29]
	v_mfma_f32_16x16x32_bf16 v[14:17], v[134:137], v[230:233], v[14:17]
	v_mfma_f32_16x16x32_bf16 v[10:13], v[182:185], v[230:233], v[10:13]
	s_setprio 0
	s_setprio 1
	v_mfma_f32_16x16x32_bf16 v[54:57], v[186:189], v[202:205], v[54:57]
	v_mfma_f32_16x16x32_bf16 v[50:53], v[194:197], v[202:205], v[50:53]
	v_mfma_f32_16x16x32_bf16 v[38:41], v[186:189], v[210:213], v[38:41]
	v_mfma_f32_16x16x32_bf16 v[34:37], v[194:197], v[210:213], v[34:37]
	v_mfma_f32_16x16x32_bf16 v[22:25], v[186:189], v[218:221], v[22:25]
	v_mfma_f32_16x16x32_bf16 v[18:21], v[194:197], v[218:221], v[18:21]
	v_mfma_f32_16x16x32_bf16 v[6:9], v[186:189], v[226:229], v[6:9]
	v_mfma_f32_16x16x32_bf16 v[2:5], v[194:197], v[226:229], v[2:5]
	v_mfma_f32_16x16x32_bf16 v[54:57], v[190:193], v[206:209], v[54:57]
	v_mfma_f32_16x16x32_bf16 v[50:53], v[198:201], v[206:209], v[50:53]
	v_mfma_f32_16x16x32_bf16 v[38:41], v[190:193], v[214:217], v[38:41]
	v_mfma_f32_16x16x32_bf16 v[34:37], v[198:201], v[214:217], v[34:37]
	v_mfma_f32_16x16x32_bf16 v[22:25], v[190:193], v[222:225], v[22:25]
	v_mfma_f32_16x16x32_bf16 v[18:21], v[198:201], v[222:225], v[18:21]
	s_setprio 2
	s_barrier
	v_mfma_f32_16x16x32_bf16 v[6:9], v[190:193], v[230:233], v[6:9]
	v_mfma_f32_16x16x32_bf16 v[2:5], v[198:201], v[230:233], v[2:5]
	s_setprio 0
	s_add_i32 s20, s20, 2
	s_add_u32 s36, s36, 0x100
	s_addc_u32 s37, s37, 0
	s_add_u32 s13, s13, 0x100
	s_addc_u32 s19, s19, 0
	s_cmp_gt_u32 s20, 29
	s_cbranch_scc0 .LBB0_1294
	s_and_b64 vcc, exec, s[2:3]
	s_cbranch_vccz .LBB0_1297
	s_barrier

.LBB0_1620:
	s_ashr_i32 s19, s18, 31
	s_lshl_b64 s[28:29], s[18:19], 18
	v_readlane_b32 s5, v245, 24
	s_add_u32 s28, s5, s28
	v_readlane_b32 s5, v245, 26
	s_addc_u32 s29, s5, s29
	s_and_b64 s[34:35], s[22:23], exec
	s_cselect_b32 s8, s29, s43
	s_cselect_b32 s19, s28, s42
	s_ashr_i32 s5, s4, 31
	s_lshl_b64 s[34:35], s[4:5], 18
	s_add_u32 s34, s11, s34
	s_addc_u32 s35, s13, s35
	s_and_b64 s[46:47], s[22:23], exec
	s_cselect_b32 s5, s35, s45
	s_cselect_b32 s21, s34, s44
	s_add_u32 s42, s42, 0x20080
	s_addc_u32 s43, s43, 0
	s_add_u32 s39, s44, 0x100
	s_addc_u32 s50, s45, 0
	s_mov_b32 s51, -2
	s_waitcnt vmcnt(0) lgkmcnt(0)
	s_add_u32 s44, s42, 0xfffe0080
	s_addc_u32 s45, s43, -1
	s_add_i32 s52, 0, 0x10000
	s_cmp_eq_u32 s51, 4
	s_cselect_b32 s47, s8, s45
	s_cselect_b32 s46, s19, s44
	v_add_u32_e32 v154, s52, v145
	s_cselect_b32 s45, s5, s50
	s_cselect_b32 s44, s21, s39
	s_add_i32 s54, 0, 0x14000
	ds_read_b128 v[130:133], v154
	ds_read_b128 v[134:137], v154 offset:1024
	ds_read_b128 v[150:153], v154 offset:2048
	ds_read_b128 v[158:161], v154 offset:3072
	v_add_u32_e32 v154, s54, v145
	ds_read_b128 v[164:167], v154
	ds_read_b128 v[180:183], v154 offset:1024
	ds_read_b128 v[184:187], v154 offset:2048
	ds_read_b128 v[188:191], v154 offset:3072
	v_lshl_add_u64 v[154:155], s[42:43], 0, v[146:147]
	s_add_i32 m0, s20, 0xc000
	ds_read_b128 v[192:195], v157
	ds_read_b128 v[196:199], v157 offset:1024
	ds_read_b128 v[200:203], v157 offset:2048
	ds_read_b128 v[204:207], v157 offset:3072
	ds_read_b128 v[208:211], v157 offset:4096
	ds_read_b128 v[212:215], v157 offset:5120
	ds_read_b128 v[216:219], v157 offset:6144
	ds_read_b128 v[220:223], v157 offset:7168
	global_load_lds_dwordx4 v[154:155], off
	v_lshl_add_u64 v[154:155], s[42:43], 0, v[148:149]
	s_add_i32 m0, s20, 0xe000
	s_nop 0
	global_load_lds_dwordx4 v[154:155], off
	s_waitcnt vmcnt(8)
	s_waitcnt lgkmcnt(0)
	s_barrier
	s_setprio 1
	s_waitcnt lgkmcnt(0)
	v_mfma_f32_16x16x32_bf16 v[126:129], v[130:133], v[192:195], 0
	v_mfma_f32_16x16x32_bf16 v[122:125], v[150:153], v[192:195], 0
	v_mfma_f32_16x16x32_bf16 v[110:113], v[130:133], v[200:203], 0
	v_mfma_f32_16x16x32_bf16 v[106:109], v[150:153], v[200:203], 0
	v_mfma_f32_16x16x32_bf16 v[94:97], v[130:133], v[208:211], 0
	v_mfma_f32_16x16x32_bf16 v[90:93], v[150:153], v[208:211], 0
	v_mfma_f32_16x16x32_bf16 v[78:81], v[130:133], v[216:219], 0
	v_mfma_f32_16x16x32_bf16 v[74:77], v[150:153], v[216:219], 0
	v_mfma_f32_16x16x32_bf16 v[126:129], v[134:137], v[196:199], v[126:129]
	v_mfma_f32_16x16x32_bf16 v[122:125], v[158:161], v[196:199], v[122:125]
	v_mfma_f32_16x16x32_bf16 v[110:113], v[134:137], v[204:207], v[110:113]
	v_mfma_f32_16x16x32_bf16 v[106:109], v[158:161], v[204:207], v[106:109]
	v_mfma_f32_16x16x32_bf16 v[94:97], v[134:137], v[212:215], v[94:97]
	v_mfma_f32_16x16x32_bf16 v[90:93], v[158:161], v[212:215], v[90:93]
	v_mfma_f32_16x16x32_bf16 v[78:81], v[134:137], v[220:223], v[78:81]
	v_mfma_f32_16x16x32_bf16 v[74:77], v[158:161], v[220:223], v[74:77]
	s_setprio 0
	s_setprio 1
	v_mfma_f32_16x16x32_bf16 v[118:121], v[164:167], v[192:195], 0
	v_mfma_f32_16x16x32_bf16 v[114:117], v[184:187], v[192:195], 0
	v_mfma_f32_16x16x32_bf16 v[102:105], v[164:167], v[200:203], 0
	v_mfma_f32_16x16x32_bf16 v[98:101], v[184:187], v[200:203], 0
	v_mfma_f32_16x16x32_bf16 v[86:89], v[164:167], v[208:211], 0
	v_mfma_f32_16x16x32_bf16 v[82:85], v[184:187], v[208:211], 0
	v_mfma_f32_16x16x32_bf16 v[70:73], v[164:167], v[216:219], 0
	v_mfma_f32_16x16x32_bf16 v[66:69], v[184:187], v[216:219], 0
	v_mfma_f32_16x16x32_bf16 v[118:121], v[180:183], v[196:199], v[118:121]
	v_mfma_f32_16x16x32_bf16 v[114:117], v[188:191], v[196:199], v[114:117]
	v_mfma_f32_16x16x32_bf16 v[102:105], v[180:183], v[204:207], v[102:105]
	v_mfma_f32_16x16x32_bf16 v[98:101], v[188:191], v[204:207], v[98:101]
	v_mfma_f32_16x16x32_bf16 v[86:89], v[180:183], v[212:215], v[86:89]
	v_mfma_f32_16x16x32_bf16 v[82:85], v[188:191], v[212:215], v[82:85]
	s_setprio 2
	s_barrier
	v_mfma_f32_16x16x32_bf16 v[70:73], v[180:183], v[220:223], v[70:73]
	v_mfma_f32_16x16x32_bf16 v[66:69], v[188:191], v[220:223], v[66:69]
	s_setprio 0
	s_add_i32 s52, s52, s9
	v_lshl_add_u64 v[154:155], s[44:45], 0, v[162:163]
	s_mov_b32 m0, s52
	ds_read_b128 v[192:195], v157 offset:16384
	ds_read_b128 v[196:199], v157 offset:17408
	ds_read_b128 v[200:203], v157 offset:18432
	ds_read_b128 v[204:207], v157 offset:19456
	ds_read_b128 v[208:211], v157 offset:20480
	ds_read_b128 v[212:215], v157 offset:21504
	ds_read_b128 v[216:219], v157 offset:22528
	ds_read_b128 v[220:223], v157 offset:23552
	global_load_lds_dwordx4 v[154:155], off
	s_add_i32 m0, s52, 0x2000
	s_add_u32 s52, s44, 0x20000
	v_lshl_add_u64 v[168:169], s[44:45], 0, v[142:143]
	s_addc_u32 s53, s45, 0
	s_add_i32 s54, s54, s9
	global_load_lds_dwordx4 v[168:169], off
	v_lshl_add_u64 v[224:225], s[52:53], 0, v[162:163]
	s_mov_b32 m0, s54
	v_lshl_add_u64 v[226:227], s[46:47], 0, v[140:141]
	global_load_lds_dwordx4 v[224:225], off
	v_lshl_add_u64 v[224:225], s[52:53], 0, v[142:143]
	s_add_i32 m0, s54, 0x2000
	s_nop 0
	global_load_lds_dwordx4 v[224:225], off
	v_lshl_add_u64 v[224:225], s[46:47], 0, v[138:139]
	s_mov_b32 m0, s20
	s_nop 0
	global_load_lds_dwordx4 v[224:225], off
	s_mov_b32 m0, s25
	s_nop 0
	global_load_lds_dwordx4 v[226:227], off
	s_waitcnt vmcnt(8)
	s_waitcnt lgkmcnt(0)
	s_barrier
	s_setprio 1
	s_waitcnt lgkmcnt(0)
	v_mfma_f32_16x16x32_bf16 v[62:65], v[130:133], v[192:195], 0
	v_mfma_f32_16x16x32_bf16 v[58:61], v[150:153], v[192:195], 0
	v_mfma_f32_16x16x32_bf16 v[46:49], v[130:133], v[200:203], 0
	v_mfma_f32_16x16x32_bf16 v[42:45], v[150:153], v[200:203], 0
	v_mfma_f32_16x16x32_bf16 v[30:33], v[130:133], v[208:211], 0
	v_mfma_f32_16x16x32_bf16 v[26:29], v[150:153], v[208:211], 0
	v_mfma_f32_16x16x32_bf16 v[14:17], v[130:133], v[216:219], 0
	v_mfma_f32_16x16x32_bf16 v[10:13], v[150:153], v[216:219], 0
	v_mfma_f32_16x16x32_bf16 v[62:65], v[134:137], v[196:199], v[62:65]
	v_mfma_f32_16x16x32_bf16 v[58:61], v[158:161], v[196:199], v[58:61]
	v_mfma_f32_16x16x32_bf16 v[46:49], v[134:137], v[204:207], v[46:49]
	v_mfma_f32_16x16x32_bf16 v[42:45], v[158:161], v[204:207], v[42:45]
	v_mfma_f32_16x16x32_bf16 v[30:33], v[134:137], v[212:215], v[30:33]
	v_mfma_f32_16x16x32_bf16 v[26:29], v[158:161], v[212:215], v[26:29]
	v_mfma_f32_16x16x32_bf16 v[14:17], v[134:137], v[220:223], v[14:17]
	v_mfma_f32_16x16x32_bf16 v[10:13], v[158:161], v[220:223], v[10:13]
	s_setprio 0
	s_setprio 1
	v_mfma_f32_16x16x32_bf16 v[54:57], v[164:167], v[192:195], 0
	v_mfma_f32_16x16x32_bf16 v[50:53], v[184:187], v[192:195], 0
	v_mfma_f32_16x16x32_bf16 v[38:41], v[164:167], v[200:203], 0
	v_mfma_f32_16x16x32_bf16 v[34:37], v[184:187], v[200:203], 0
	v_mfma_f32_16x16x32_bf16 v[22:25], v[164:167], v[208:211], 0
	v_mfma_f32_16x16x32_bf16 v[18:21], v[184:187], v[208:211], 0
	v_mfma_f32_16x16x32_bf16 v[6:9], v[164:167], v[216:219], 0
	v_mfma_f32_16x16x32_bf16 v[2:5], v[184:187], v[216:219], 0
	v_mfma_f32_16x16x32_bf16 v[54:57], v[180:183], v[196:199], v[54:57]
	v_mfma_f32_16x16x32_bf16 v[50:53], v[188:191], v[196:199], v[50:53]
	v_mfma_f32_16x16x32_bf16 v[38:41], v[180:183], v[204:207], v[38:41]
	v_mfma_f32_16x16x32_bf16 v[34:37], v[188:191], v[204:207], v[34:37]
	v_mfma_f32_16x16x32_bf16 v[22:25], v[180:183], v[212:215], v[22:25]
	v_mfma_f32_16x16x32_bf16 v[18:21], v[188:191], v[212:215], v[18:21]
	s_setprio 2
	s_barrier
	v_mfma_f32_16x16x32_bf16 v[6:9], v[180:183], v[220:223], v[6:9]
	v_mfma_f32_16x16x32_bf16 v[2:5], v[188:191], v[220:223], v[2:5]
	s_setprio 0
	s_add_i32 s52, 0, 0x18000
	s_add_i32 s53, 0, 0x1c000
	v_add_u32_e32 v158, s52, v145
	v_add_u32_e32 v179, s53, v145
	ds_read_b128 v[130:133], v158
	ds_read_b128 v[134:137], v158 offset:1024
	ds_read_b128 v[150:153], v158 offset:2048
	ds_read_b128 v[158:161], v158 offset:3072
	ds_read_b128 v[164:167], v179
	ds_read_b128 v[180:183], v179 offset:1024
	ds_read_b128 v[184:187], v179 offset:2048
	ds_read_b128 v[188:191], v179 offset:3072
	s_add_u32 s46, s46, 0x20000
	s_addc_u32 s47, s47, 0
	s_mov_b32 m0, s26
	v_lshl_add_u64 v[228:229], s[46:47], 0, v[138:139]
	ds_read_b128 v[192:195], v157 offset:32768
	ds_read_b128 v[196:199], v157 offset:33792
	ds_read_b128 v[200:203], v157 offset:34816
	ds_read_b128 v[204:207], v157 offset:35840
	ds_read_b128 v[208:211], v157 offset:36864
	ds_read_b128 v[212:215], v157 offset:37888
	ds_read_b128 v[216:219], v157 offset:38912
	ds_read_b128 v[220:223], v157 offset:39936
	global_load_lds_dwordx4 v[228:229], off
	v_lshl_add_u64 v[228:229], s[46:47], 0, v[140:141]
	s_mov_b32 m0, s27
	s_nop 0
	global_load_lds_dwordx4 v[228:229], off
	s_waitcnt vmcnt(8)
	s_waitcnt lgkmcnt(0)
	s_barrier
	s_setprio 1
	s_waitcnt lgkmcnt(0)
	v_mfma_f32_16x16x32_bf16 v[126:129], v[130:133], v[192:195], v[126:129]
	v_mfma_f32_16x16x32_bf16 v[122:125], v[150:153], v[192:195], v[122:125]
	v_mfma_f32_16x16x32_bf16 v[110:113], v[130:133], v[200:203], v[110:113]
	v_mfma_f32_16x16x32_bf16 v[106:109], v[150:153], v[200:203], v[106:109]
	v_mfma_f32_16x16x32_bf16 v[94:97], v[130:133], v[208:211], v[94:97]
	v_mfma_f32_16x16x32_bf16 v[90:93], v[150:153], v[208:211], v[90:93]
	v_mfma_f32_16x16x32_bf16 v[78:81], v[130:133], v[216:219], v[78:81]
	v_mfma_f32_16x16x32_bf16 v[74:77], v[150:153], v[216:219], v[74:77]
	v_mfma_f32_16x16x32_bf16 v[126:129], v[134:137], v[196:199], v[126:129]
	v_mfma_f32_16x16x32_bf16 v[122:125], v[158:161], v[196:199], v[122:125]
	v_mfma_f32_16x16x32_bf16 v[110:113], v[134:137], v[204:207], v[110:113]
	v_mfma_f32_16x16x32_bf16 v[106:109], v[158:161], v[204:207], v[106:109]
	v_mfma_f32_16x16x32_bf16 v[94:97], v[134:137], v[212:215], v[94:97]
	v_mfma_f32_16x16x32_bf16 v[90:93], v[158:161], v[212:215], v[90:93]
	v_mfma_f32_16x16x32_bf16 v[78:81], v[134:137], v[220:223], v[78:81]
	v_mfma_f32_16x16x32_bf16 v[74:77], v[158:161], v[220:223], v[74:77]
	s_setprio 0
	s_setprio 1
	v_mfma_f32_16x16x32_bf16 v[118:121], v[164:167], v[192:195], v[118:121]
	v_mfma_f32_16x16x32_bf16 v[114:117], v[184:187], v[192:195], v[114:117]
	v_mfma_f32_16x16x32_bf16 v[102:105], v[164:167], v[200:203], v[102:105]
	v_mfma_f32_16x16x32_bf16 v[98:101], v[184:187], v[200:203], v[98:101]
	v_mfma_f32_16x16x32_bf16 v[86:89], v[164:167], v[208:211], v[86:89]
	v_mfma_f32_16x16x32_bf16 v[82:85], v[184:187], v[208:211], v[82:85]
	v_mfma_f32_16x16x32_bf16 v[70:73], v[164:167], v[216:219], v[70:73]
	v_mfma_f32_16x16x32_bf16 v[66:69], v[184:187], v[216:219], v[66:69]
	v_mfma_f32_16x16x32_bf16 v[118:121], v[180:183], v[196:199], v[118:121]
	v_mfma_f32_16x16x32_bf16 v[114:117], v[188:191], v[196:199], v[114:117]
	v_mfma_f32_16x16x32_bf16 v[102:105], v[180:183], v[204:207], v[102:105]
	v_mfma_f32_16x16x32_bf16 v[98:101], v[188:191], v[204:207], v[98:101]
	v_mfma_f32_16x16x32_bf16 v[86:89], v[180:183], v[212:215], v[86:89]
	v_mfma_f32_16x16x32_bf16 v[82:85], v[188:191], v[212:215], v[82:85]
	s_setprio 2
	s_barrier
	v_mfma_f32_16x16x32_bf16 v[70:73], v[180:183], v[220:223], v[70:73]
	v_mfma_f32_16x16x32_bf16 v[66:69], v[188:191], v[220:223], v[66:69]
	s_setprio 0
	s_add_i32 s46, s52, s9
	v_lshl_add_u64 v[154:155], v[154:155], 0, s[6:7]
	s_mov_b32 m0, s46
	ds_read_b128 v[192:195], v157 offset:49152
	ds_read_b128 v[196:199], v157 offset:50176
	ds_read_b128 v[200:203], v157 offset:51200
	ds_read_b128 v[204:207], v157 offset:52224
	ds_read_b128 v[208:211], v157 offset:53248
	ds_read_b128 v[212:215], v157 offset:54272
	ds_read_b128 v[216:219], v157 offset:55296
	ds_read_b128 v[220:223], v157 offset:56320
	global_load_lds_dwordx4 v[154:155], off
	s_add_i32 m0, s46, 0x2000
	s_add_u32 s44, s44, 0x20080
	v_lshl_add_u64 v[154:155], v[168:169], 0, s[6:7]
	s_addc_u32 s45, s45, 0
	s_add_i32 s46, s53, s9
	global_load_lds_dwordx4 v[154:155], off
	v_lshl_add_u64 v[154:155], s[44:45], 0, v[162:163]
	s_mov_b32 m0, s46
	s_nop 0
	global_load_lds_dwordx4 v[154:155], off
	v_lshl_add_u64 v[154:155], s[44:45], 0, v[142:143]
	s_add_i32 m0, s46, 0x2000
	s_nop 0
	global_load_lds_dwordx4 v[154:155], off
	v_lshl_add_u64 v[154:155], v[224:225], 0, s[6:7]
	s_mov_b32 m0, s41
	s_nop 0
	global_load_lds_dwordx4 v[154:155], off
	v_lshl_add_u64 v[154:155], v[226:227], 0, s[6:7]
	s_mov_b32 m0, s48
	s_nop 0
	global_load_lds_dwordx4 v[154:155], off
	s_waitcnt vmcnt(8)
	s_waitcnt lgkmcnt(0)
	s_barrier
	s_setprio 1
	s_waitcnt lgkmcnt(0)
	v_mfma_f32_16x16x32_bf16 v[62:65], v[130:133], v[192:195], v[62:65]
	v_mfma_f32_16x16x32_bf16 v[58:61], v[150:153], v[192:195], v[58:61]
	v_mfma_f32_16x16x32_bf16 v[46:49], v[130:133], v[200:203], v[46:49]
	v_mfma_f32_16x16x32_bf16 v[42:45], v[150:153], v[200:203], v[42:45]
	v_mfma_f32_16x16x32_bf16 v[30:33], v[130:133], v[208:211], v[30:33]
	v_mfma_f32_16x16x32_bf16 v[26:29], v[150:153], v[208:211], v[26:29]
	v_mfma_f32_16x16x32_bf16 v[14:17], v[130:133], v[216:219], v[14:17]
	v_mfma_f32_16x16x32_bf16 v[10:13], v[150:153], v[216:219], v[10:13]
	v_mfma_f32_16x16x32_bf16 v[62:65], v[134:137], v[196:199], v[62:65]
	v_mfma_f32_16x16x32_bf16 v[58:61], v[158:161], v[196:199], v[58:61]
	v_mfma_f32_16x16x32_bf16 v[46:49], v[134:137], v[204:207], v[46:49]
	v_mfma_f32_16x16x32_bf16 v[42:45], v[158:161], v[204:207], v[42:45]
	v_mfma_f32_16x16x32_bf16 v[30:33], v[134:137], v[212:215], v[30:33]
	v_mfma_f32_16x16x32_bf16 v[26:29], v[158:161], v[212:215], v[26:29]
	v_mfma_f32_16x16x32_bf16 v[14:17], v[134:137], v[220:223], v[14:17]
	v_mfma_f32_16x16x32_bf16 v[10:13], v[158:161], v[220:223], v[10:13]
	s_setprio 0
	s_setprio 1
	v_mfma_f32_16x16x32_bf16 v[54:57], v[164:167], v[192:195], v[54:57]
	v_mfma_f32_16x16x32_bf16 v[50:53], v[184:187], v[192:195], v[50:53]
	v_mfma_f32_16x16x32_bf16 v[38:41], v[164:167], v[200:203], v[38:41]
	v_mfma_f32_16x16x32_bf16 v[34:37], v[184:187], v[200:203], v[34:37]
	v_mfma_f32_16x16x32_bf16 v[22:25], v[164:167], v[208:211], v[22:25]
	v_mfma_f32_16x16x32_bf16 v[18:21], v[184:187], v[208:211], v[18:21]
	v_mfma_f32_16x16x32_bf16 v[6:9], v[164:167], v[216:219], v[6:9]
	v_mfma_f32_16x16x32_bf16 v[2:5], v[184:187], v[216:219], v[2:5]
	v_mfma_f32_16x16x32_bf16 v[54:57], v[180:183], v[196:199], v[54:57]
	v_mfma_f32_16x16x32_bf16 v[50:53], v[188:191], v[196:199], v[50:53]
	v_mfma_f32_16x16x32_bf16 v[38:41], v[180:183], v[204:207], v[38:41]
	v_mfma_f32_16x16x32_bf16 v[34:37], v[188:191], v[204:207], v[34:37]
	v_mfma_f32_16x16x32_bf16 v[22:25], v[180:183], v[212:215], v[22:25]
	v_mfma_f32_16x16x32_bf16 v[18:21], v[188:191], v[212:215], v[18:21]
	s_setprio 2
	s_barrier
	v_mfma_f32_16x16x32_bf16 v[6:9], v[180:183], v[220:223], v[6:9]
	v_mfma_f32_16x16x32_bf16 v[2:5], v[188:191], v[220:223], v[2:5]
	s_setprio 0
	s_add_i32 s51, s51, 2
	s_add_u32 s42, s42, 0x100
	s_addc_u32 s43, s43, 0
	s_add_u32 s39, s39, 0x100
	s_addc_u32 s50, s50, 0
	s_cmp_gt_u32 s51, 5
.LBB0_1621:
	s_add_u32 s44, s42, 0xfffe0080
	s_addc_u32 s45, s43, -1
	s_add_i32 s52, 0, 0x10000
	s_cmp_eq_u32 s51, 4
	s_cselect_b32 s47, s8, s45
	s_cselect_b32 s46, s19, s44
	v_add_u32_e32 v154, s52, v145
	s_cselect_b32 s45, s5, s50
	s_cselect_b32 s44, s21, s39
	s_add_i32 s54, 0, 0x14000
	ds_read_b128 v[130:133], v154
	ds_read_b128 v[134:137], v154 offset:1024
	ds_read_b128 v[150:153], v154 offset:2048
	ds_read_b128 v[158:161], v154 offset:3072
	v_add_u32_e32 v154, s54, v145
	ds_read_b128 v[164:167], v154
	ds_read_b128 v[180:183], v154 offset:1024
	ds_read_b128 v[184:187], v154 offset:2048
	ds_read_b128 v[188:191], v154 offset:3072
	v_lshl_add_u64 v[154:155], s[42:43], 0, v[146:147]
	s_add_i32 m0, s20, 0xc000
	ds_read_b128 v[192:195], v157
	ds_read_b128 v[196:199], v157 offset:1024
	ds_read_b128 v[200:203], v157 offset:2048
	ds_read_b128 v[204:207], v157 offset:3072
	ds_read_b128 v[208:211], v157 offset:4096
	ds_read_b128 v[212:215], v157 offset:5120
	ds_read_b128 v[216:219], v157 offset:6144
	ds_read_b128 v[220:223], v157 offset:7168
	global_load_lds_dwordx4 v[154:155], off
	v_lshl_add_u64 v[154:155], s[42:43], 0, v[148:149]
	s_add_i32 m0, s20, 0xe000
	s_nop 0
	global_load_lds_dwordx4 v[154:155], off
	s_waitcnt vmcnt(8)
	s_waitcnt lgkmcnt(0)
	s_barrier
	s_setprio 1
	s_waitcnt lgkmcnt(0)
	v_mfma_f32_16x16x32_bf16 v[126:129], v[130:133], v[192:195], v[126:129]
	v_mfma_f32_16x16x32_bf16 v[122:125], v[150:153], v[192:195], v[122:125]
	v_mfma_f32_16x16x32_bf16 v[110:113], v[130:133], v[200:203], v[110:113]
	v_mfma_f32_16x16x32_bf16 v[106:109], v[150:153], v[200:203], v[106:109]
	v_mfma_f32_16x16x32_bf16 v[94:97], v[130:133], v[208:211], v[94:97]
	v_mfma_f32_16x16x32_bf16 v[90:93], v[150:153], v[208:211], v[90:93]
	v_mfma_f32_16x16x32_bf16 v[78:81], v[130:133], v[216:219], v[78:81]
	v_mfma_f32_16x16x32_bf16 v[74:77], v[150:153], v[216:219], v[74:77]
	v_mfma_f32_16x16x32_bf16 v[126:129], v[134:137], v[196:199], v[126:129]
	v_mfma_f32_16x16x32_bf16 v[122:125], v[158:161], v[196:199], v[122:125]
	v_mfma_f32_16x16x32_bf16 v[110:113], v[134:137], v[204:207], v[110:113]
	v_mfma_f32_16x16x32_bf16 v[106:109], v[158:161], v[204:207], v[106:109]
	v_mfma_f32_16x16x32_bf16 v[94:97], v[134:137], v[212:215], v[94:97]
	v_mfma_f32_16x16x32_bf16 v[90:93], v[158:161], v[212:215], v[90:93]
	v_mfma_f32_16x16x32_bf16 v[78:81], v[134:137], v[220:223], v[78:81]
	v_mfma_f32_16x16x32_bf16 v[74:77], v[158:161], v[220:223], v[74:77]
	s_setprio 0
	s_setprio 1
	v_mfma_f32_16x16x32_bf16 v[118:121], v[164:167], v[192:195], v[118:121]
	v_mfma_f32_16x16x32_bf16 v[114:117], v[184:187], v[192:195], v[114:117]
	v_mfma_f32_16x16x32_bf16 v[102:105], v[164:167], v[200:203], v[102:105]
	v_mfma_f32_16x16x32_bf16 v[98:101], v[184:187], v[200:203], v[98:101]
	v_mfma_f32_16x16x32_bf16 v[86:89], v[164:167], v[208:211], v[86:89]
	v_mfma_f32_16x16x32_bf16 v[82:85], v[184:187], v[208:211], v[82:85]
	v_mfma_f32_16x16x32_bf16 v[70:73], v[164:167], v[216:219], v[70:73]
	v_mfma_f32_16x16x32_bf16 v[66:69], v[184:187], v[216:219], v[66:69]
	v_mfma_f32_16x16x32_bf16 v[118:121], v[180:183], v[196:199], v[118:121]
	v_mfma_f32_16x16x32_bf16 v[114:117], v[188:191], v[196:199], v[114:117]
	v_mfma_f32_16x16x32_bf16 v[102:105], v[180:183], v[204:207], v[102:105]
	v_mfma_f32_16x16x32_bf16 v[98:101], v[188:191], v[204:207], v[98:101]
	v_mfma_f32_16x16x32_bf16 v[86:89], v[180:183], v[212:215], v[86:89]
	v_mfma_f32_16x16x32_bf16 v[82:85], v[188:191], v[212:215], v[82:85]
	s_setprio 2
	s_barrier
	v_mfma_f32_16x16x32_bf16 v[70:73], v[180:183], v[220:223], v[70:73]
	v_mfma_f32_16x16x32_bf16 v[66:69], v[188:191], v[220:223], v[66:69]
	s_setprio 0
	s_add_i32 s52, s52, s9
	v_lshl_add_u64 v[154:155], s[44:45], 0, v[162:163]
	s_mov_b32 m0, s52
	ds_read_b128 v[192:195], v157 offset:16384
	ds_read_b128 v[196:199], v157 offset:17408
	ds_read_b128 v[200:203], v157 offset:18432
	ds_read_b128 v[204:207], v157 offset:19456
	ds_read_b128 v[208:211], v157 offset:20480
	ds_read_b128 v[212:215], v157 offset:21504
	ds_read_b128 v[216:219], v157 offset:22528
	ds_read_b128 v[220:223], v157 offset:23552
	global_load_lds_dwordx4 v[154:155], off
	s_add_i32 m0, s52, 0x2000
	s_add_u32 s52, s44, 0x20000
	v_lshl_add_u64 v[168:169], s[44:45], 0, v[142:143]
	s_addc_u32 s53, s45, 0
	s_add_i32 s54, s54, s9
	global_load_lds_dwordx4 v[168:169], off
	v_lshl_add_u64 v[224:225], s[52:53], 0, v[162:163]
	s_mov_b32 m0, s54
	v_lshl_add_u64 v[226:227], s[46:47], 0, v[140:141]
	global_load_lds_dwordx4 v[224:225], off
	v_lshl_add_u64 v[224:225], s[52:53], 0, v[142:143]
	s_add_i32 m0, s54, 0x2000
	s_nop 0
	global_load_lds_dwordx4 v[224:225], off
	v_lshl_add_u64 v[224:225], s[46:47], 0, v[138:139]
	s_mov_b32 m0, s20
	s_nop 0
	global_load_lds_dwordx4 v[224:225], off
	s_mov_b32 m0, s25
	s_nop 0
	global_load_lds_dwordx4 v[226:227], off
	s_waitcnt vmcnt(8)
	s_waitcnt lgkmcnt(0)
	s_barrier
	s_setprio 1
	s_waitcnt lgkmcnt(0)
	v_mfma_f32_16x16x32_bf16 v[62:65], v[130:133], v[192:195], v[62:65]
	v_mfma_f32_16x16x32_bf16 v[58:61], v[150:153], v[192:195], v[58:61]
	v_mfma_f32_16x16x32_bf16 v[46:49], v[130:133], v[200:203], v[46:49]
	v_mfma_f32_16x16x32_bf16 v[42:45], v[150:153], v[200:203], v[42:45]
	v_mfma_f32_16x16x32_bf16 v[30:33], v[130:133], v[208:211], v[30:33]
	v_mfma_f32_16x16x32_bf16 v[26:29], v[150:153], v[208:211], v[26:29]
	v_mfma_f32_16x16x32_bf16 v[14:17], v[130:133], v[216:219], v[14:17]
	v_mfma_f32_16x16x32_bf16 v[10:13], v[150:153], v[216:219], v[10:13]
	v_mfma_f32_16x16x32_bf16 v[62:65], v[134:137], v[196:199], v[62:65]
	v_mfma_f32_16x16x32_bf16 v[58:61], v[158:161], v[196:199], v[58:61]
	v_mfma_f32_16x16x32_bf16 v[46:49], v[134:137], v[204:207], v[46:49]
	v_mfma_f32_16x16x32_bf16 v[42:45], v[158:161], v[204:207], v[42:45]
	v_mfma_f32_16x16x32_bf16 v[30:33], v[134:137], v[212:215], v[30:33]
	v_mfma_f32_16x16x32_bf16 v[26:29], v[158:161], v[212:215], v[26:29]
	v_mfma_f32_16x16x32_bf16 v[14:17], v[134:137], v[220:223], v[14:17]
	v_mfma_f32_16x16x32_bf16 v[10:13], v[158:161], v[220:223], v[10:13]
	s_setprio 0
	s_setprio 1
	v_mfma_f32_16x16x32_bf16 v[54:57], v[164:167], v[192:195], v[54:57]
	v_mfma_f32_16x16x32_bf16 v[50:53], v[184:187], v[192:195], v[50:53]
	v_mfma_f32_16x16x32_bf16 v[38:41], v[164:167], v[200:203], v[38:41]
	v_mfma_f32_16x16x32_bf16 v[34:37], v[184:187], v[200:203], v[34:37]
	v_mfma_f32_16x16x32_bf16 v[22:25], v[164:167], v[208:211], v[22:25]
	v_mfma_f32_16x16x32_bf16 v[18:21], v[184:187], v[208:211], v[18:21]
	v_mfma_f32_16x16x32_bf16 v[6:9], v[164:167], v[216:219], v[6:9]
	v_mfma_f32_16x16x32_bf16 v[2:5], v[184:187], v[216:219], v[2:5]
	v_mfma_f32_16x16x32_bf16 v[54:57], v[180:183], v[196:199], v[54:57]
	v_mfma_f32_16x16x32_bf16 v[50:53], v[188:191], v[196:199], v[50:53]
	v_mfma_f32_16x16x32_bf16 v[38:41], v[180:183], v[204:207], v[38:41]
	v_mfma_f32_16x16x32_bf16 v[34:37], v[188:191], v[204:207], v[34:37]
	v_mfma_f32_16x16x32_bf16 v[22:25], v[180:183], v[212:215], v[22:25]
	v_mfma_f32_16x16x32_bf16 v[18:21], v[188:191], v[212:215], v[18:21]
	s_setprio 2
	s_barrier
	v_mfma_f32_16x16x32_bf16 v[6:9], v[180:183], v[220:223], v[6:9]
	v_mfma_f32_16x16x32_bf16 v[2:5], v[188:191], v[220:223], v[2:5]
	s_setprio 0
	s_add_i32 s52, 0, 0x18000
	s_add_i32 s53, 0, 0x1c000
	v_add_u32_e32 v158, s52, v145
	v_add_u32_e32 v179, s53, v145
	ds_read_b128 v[130:133], v158
	ds_read_b128 v[134:137], v158 offset:1024
	ds_read_b128 v[150:153], v158 offset:2048
	ds_read_b128 v[158:161], v158 offset:3072
	ds_read_b128 v[164:167], v179
	ds_read_b128 v[180:183], v179 offset:1024
	ds_read_b128 v[184:187], v179 offset:2048
	ds_read_b128 v[188:191], v179 offset:3072
	s_add_u32 s46, s46, 0x20000
	s_addc_u32 s47, s47, 0
	s_mov_b32 m0, s26
	v_lshl_add_u64 v[228:229], s[46:47], 0, v[138:139]
	ds_read_b128 v[192:195], v157 offset:32768
	ds_read_b128 v[196:199], v157 offset:33792
	ds_read_b128 v[200:203], v157 offset:34816
	ds_read_b128 v[204:207], v157 offset:35840
	ds_read_b128 v[208:211], v157 offset:36864
	ds_read_b128 v[212:215], v157 offset:37888
	ds_read_b128 v[216:219], v157 offset:38912
	ds_read_b128 v[220:223], v157 offset:39936
	global_load_lds_dwordx4 v[228:229], off
	v_lshl_add_u64 v[228:229], s[46:47], 0, v[140:141]
	s_mov_b32 m0, s27
	s_nop 0
	global_load_lds_dwordx4 v[228:229], off
	s_waitcnt vmcnt(8)
	s_waitcnt lgkmcnt(0)
	s_barrier
	s_setprio 1
	s_waitcnt lgkmcnt(0)
	v_mfma_f32_16x16x32_bf16 v[126:129], v[130:133], v[192:195], v[126:129]
	v_mfma_f32_16x16x32_bf16 v[122:125], v[150:153], v[192:195], v[122:125]
	v_mfma_f32_16x16x32_bf16 v[110:113], v[130:133], v[200:203], v[110:113]
	v_mfma_f32_16x16x32_bf16 v[106:109], v[150:153], v[200:203], v[106:109]
	v_mfma_f32_16x16x32_bf16 v[94:97], v[130:133], v[208:211], v[94:97]
	v_mfma_f32_16x16x32_bf16 v[90:93], v[150:153], v[208:211], v[90:93]
	v_mfma_f32_16x16x32_bf16 v[78:81], v[130:133], v[216:219], v[78:81]
	v_mfma_f32_16x16x32_bf16 v[74:77], v[150:153], v[216:219], v[74:77]
	v_mfma_f32_16x16x32_bf16 v[126:129], v[134:137], v[196:199], v[126:129]
	v_mfma_f32_16x16x32_bf16 v[122:125], v[158:161], v[196:199], v[122:125]
	v_mfma_f32_16x16x32_bf16 v[110:113], v[134:137], v[204:207], v[110:113]
	v_mfma_f32_16x16x32_bf16 v[106:109], v[158:161], v[204:207], v[106:109]
	v_mfma_f32_16x16x32_bf16 v[94:97], v[134:137], v[212:215], v[94:97]
	v_mfma_f32_16x16x32_bf16 v[90:93], v[158:161], v[212:215], v[90:93]
	v_mfma_f32_16x16x32_bf16 v[78:81], v[134:137], v[220:223], v[78:81]
	v_mfma_f32_16x16x32_bf16 v[74:77], v[158:161], v[220:223], v[74:77]
	s_setprio 0
	s_setprio 1
	v_mfma_f32_16x16x32_bf16 v[118:121], v[164:167], v[192:195], v[118:121]
	v_mfma_f32_16x16x32_bf16 v[114:117], v[184:187], v[192:195], v[114:117]
	v_mfma_f32_16x16x32_bf16 v[102:105], v[164:167], v[200:203], v[102:105]
	v_mfma_f32_16x16x32_bf16 v[98:101], v[184:187], v[200:203], v[98:101]
	v_mfma_f32_16x16x32_bf16 v[86:89], v[164:167], v[208:211], v[86:89]
	v_mfma_f32_16x16x32_bf16 v[82:85], v[184:187], v[208:211], v[82:85]
	v_mfma_f32_16x16x32_bf16 v[70:73], v[164:167], v[216:219], v[70:73]
	v_mfma_f32_16x16x32_bf16 v[66:69], v[184:187], v[216:219], v[66:69]
	v_mfma_f32_16x16x32_bf16 v[118:121], v[180:183], v[196:199], v[118:121]
	v_mfma_f32_16x16x32_bf16 v[114:117], v[188:191], v[196:199], v[114:117]
	v_mfma_f32_16x16x32_bf16 v[102:105], v[180:183], v[204:207], v[102:105]
	v_mfma_f32_16x16x32_bf16 v[98:101], v[188:191], v[204:207], v[98:101]
	v_mfma_f32_16x16x32_bf16 v[86:89], v[180:183], v[212:215], v[86:89]
	v_mfma_f32_16x16x32_bf16 v[82:85], v[188:191], v[212:215], v[82:85]
	s_setprio 2
	s_barrier
	v_mfma_f32_16x16x32_bf16 v[70:73], v[180:183], v[220:223], v[70:73]
	v_mfma_f32_16x16x32_bf16 v[66:69], v[188:191], v[220:223], v[66:69]
	s_setprio 0
	s_add_i32 s46, s52, s9
	v_lshl_add_u64 v[154:155], v[154:155], 0, s[6:7]
	s_mov_b32 m0, s46
	ds_read_b128 v[192:195], v157 offset:49152
	ds_read_b128 v[196:199], v157 offset:50176
	ds_read_b128 v[200:203], v157 offset:51200
	ds_read_b128 v[204:207], v157 offset:52224
	ds_read_b128 v[208:211], v157 offset:53248
	ds_read_b128 v[212:215], v157 offset:54272
	ds_read_b128 v[216:219], v157 offset:55296
	ds_read_b128 v[220:223], v157 offset:56320
	global_load_lds_dwordx4 v[154:155], off
	s_add_i32 m0, s46, 0x2000
	s_add_u32 s44, s44, 0x20080
	v_lshl_add_u64 v[154:155], v[168:169], 0, s[6:7]
	s_addc_u32 s45, s45, 0
	s_add_i32 s46, s53, s9
	global_load_lds_dwordx4 v[154:155], off
	v_lshl_add_u64 v[154:155], s[44:45], 0, v[162:163]
	s_mov_b32 m0, s46
	s_nop 0
	global_load_lds_dwordx4 v[154:155], off
	v_lshl_add_u64 v[154:155], s[44:45], 0, v[142:143]
	s_add_i32 m0, s46, 0x2000
	s_nop 0
	global_load_lds_dwordx4 v[154:155], off
	v_lshl_add_u64 v[154:155], v[224:225], 0, s[6:7]
	s_mov_b32 m0, s41
	s_nop 0
	global_load_lds_dwordx4 v[154:155], off
	v_lshl_add_u64 v[154:155], v[226:227], 0, s[6:7]
	s_mov_b32 m0, s48
	s_nop 0
	global_load_lds_dwordx4 v[154:155], off
	s_waitcnt vmcnt(8)
	s_waitcnt lgkmcnt(0)
	s_barrier
	s_setprio 1
	s_waitcnt lgkmcnt(0)
	v_mfma_f32_16x16x32_bf16 v[62:65], v[130:133], v[192:195], v[62:65]
	v_mfma_f32_16x16x32_bf16 v[58:61], v[150:153], v[192:195], v[58:61]
	v_mfma_f32_16x16x32_bf16 v[46:49], v[130:133], v[200:203], v[46:49]
	v_mfma_f32_16x16x32_bf16 v[42:45], v[150:153], v[200:203], v[42:45]
	v_mfma_f32_16x16x32_bf16 v[30:33], v[130:133], v[208:211], v[30:33]
	v_mfma_f32_16x16x32_bf16 v[26:29], v[150:153], v[208:211], v[26:29]
	v_mfma_f32_16x16x32_bf16 v[14:17], v[130:133], v[216:219], v[14:17]
	v_mfma_f32_16x16x32_bf16 v[10:13], v[150:153], v[216:219], v[10:13]
	v_mfma_f32_16x16x32_bf16 v[62:65], v[134:137], v[196:199], v[62:65]
	v_mfma_f32_16x16x32_bf16 v[58:61], v[158:161], v[196:199], v[58:61]
	v_mfma_f32_16x16x32_bf16 v[46:49], v[134:137], v[204:207], v[46:49]
	v_mfma_f32_16x16x32_bf16 v[42:45], v[158:161], v[204:207], v[42:45]
	v_mfma_f32_16x16x32_bf16 v[30:33], v[134:137], v[212:215], v[30:33]
	v_mfma_f32_16x16x32_bf16 v[26:29], v[158:161], v[212:215], v[26:29]
	v_mfma_f32_16x16x32_bf16 v[14:17], v[134:137], v[220:223], v[14:17]
	v_mfma_f32_16x16x32_bf16 v[10:13], v[158:161], v[220:223], v[10:13]
	s_setprio 0
	s_setprio 1
	v_mfma_f32_16x16x32_bf16 v[54:57], v[164:167], v[192:195], v[54:57]
	v_mfma_f32_16x16x32_bf16 v[50:53], v[184:187], v[192:195], v[50:53]
	v_mfma_f32_16x16x32_bf16 v[38:41], v[164:167], v[200:203], v[38:41]
	v_mfma_f32_16x16x32_bf16 v[34:37], v[184:187], v[200:203], v[34:37]
	v_mfma_f32_16x16x32_bf16 v[22:25], v[164:167], v[208:211], v[22:25]
	v_mfma_f32_16x16x32_bf16 v[18:21], v[184:187], v[208:211], v[18:21]
	v_mfma_f32_16x16x32_bf16 v[6:9], v[164:167], v[216:219], v[6:9]
	v_mfma_f32_16x16x32_bf16 v[2:5], v[184:187], v[216:219], v[2:5]
	v_mfma_f32_16x16x32_bf16 v[54:57], v[180:183], v[196:199], v[54:57]
	v_mfma_f32_16x16x32_bf16 v[50:53], v[188:191], v[196:199], v[50:53]
	v_mfma_f32_16x16x32_bf16 v[38:41], v[180:183], v[204:207], v[38:41]
	v_mfma_f32_16x16x32_bf16 v[34:37], v[188:191], v[204:207], v[34:37]
	v_mfma_f32_16x16x32_bf16 v[22:25], v[180:183], v[212:215], v[22:25]
	v_mfma_f32_16x16x32_bf16 v[18:21], v[188:191], v[212:215], v[18:21]
	s_setprio 2
	s_barrier
	v_mfma_f32_16x16x32_bf16 v[6:9], v[180:183], v[220:223], v[6:9]
	v_mfma_f32_16x16x32_bf16 v[2:5], v[188:191], v[220:223], v[2:5]
	s_setprio 0
	s_add_i32 s51, s51, 2
	s_add_u32 s42, s42, 0x100
	s_addc_u32 s43, s43, 0
	s_add_u32 s39, s39, 0x100
	s_addc_u32 s50, s50, 0
	s_cmp_gt_u32 s51, 5
	s_cbranch_scc0 .LBB0_1621
	s_and_b64 vcc, exec, s[2:3]
	s_cbranch_vccz .LBB0_1624
	s_barrier

.LBB0_1797:
	s_ashr_i32 s19, s18, 31
	s_lshl_b64 s[20:21], s[18:19], 20
	v_readlane_b32 s5, v243, 17
	s_add_u32 s28, s5, s20
	v_readlane_b32 s5, v243, 18
	s_addc_u32 s29, s5, s21
	s_and_b64 s[20:21], s[34:35], exec
	s_cselect_b32 s11, s29, s23
	s_cselect_b32 s13, s28, s22
	s_ashr_i32 s5, s4, 31
	s_lshl_b64 s[20:21], s[4:5], 20
	s_add_u32 s38, s25, s20
	s_addc_u32 s39, s27, s21
	s_and_b64 s[20:21], s[34:35], exec
	s_cselect_b32 s5, s39, s41
	s_cselect_b32 s19, s38, s40
	s_add_u32 s22, s22, 0x80080
	s_addc_u32 s23, s23, 0
	s_add_u32 s20, s40, 0x100
	s_addc_u32 s21, s41, 0
	s_mov_b32 s26, -2
	s_add_u32 s40, s22, 0xfff80080
	s_addc_u32 s41, s23, -1
	s_add_i32 s52, 0, 0x10000
	s_cmp_eq_u32 s26, 28
	s_cselect_b32 s43, s11, s41
	s_cselect_b32 s42, s13, s40
	v_add_u32_e32 v147, s52, v141
	s_cselect_b32 s41, s5, s21
	s_cselect_b32 s40, s19, s20
	s_add_i32 s54, 0, 0x14000
	ds_read_b128 v[152:155], v147
	ds_read_b128 v[164:167], v147 offset:1024
	ds_read_b128 v[180:183], v147 offset:2048
	ds_read_b128 v[184:187], v147 offset:3072
	v_add_u32_e32 v147, s54, v141
	ds_read_b128 v[188:191], v147
	ds_read_b128 v[192:195], v147 offset:1024
	ds_read_b128 v[196:199], v147 offset:2048
	ds_read_b128 v[200:203], v147 offset:3072
	v_lshl_add_u64 v[160:161], s[22:23], 0, v[136:137]
	s_add_i32 m0, s45, 0xc000
	ds_read_b128 v[204:207], v145
	ds_read_b128 v[208:211], v145 offset:1024
	ds_read_b128 v[212:215], v145 offset:2048
	ds_read_b128 v[216:219], v145 offset:3072
	ds_read_b128 v[220:223], v145 offset:4096
	ds_read_b128 v[224:227], v145 offset:5120
	ds_read_b128 v[228:231], v145 offset:6144
	ds_read_b128 v[232:235], v145 offset:7168
	global_load_lds_dwordx4 v[160:161], off
	v_lshl_add_u64 v[160:161], s[22:23], 0, v[138:139]
	s_add_i32 m0, s45, 0xe000
	s_nop 0
	global_load_lds_dwordx4 v[160:161], off
	s_nop 0
	s_waitcnt lgkmcnt(0)
	s_barrier
	s_setprio 1
	s_waitcnt lgkmcnt(0)
	v_mfma_f32_16x16x32_bf16 v[126:129], v[152:155], v[204:207], 0
	v_mfma_f32_16x16x32_bf16 v[122:125], v[180:183], v[204:207], 0
	v_mfma_f32_16x16x32_bf16 v[110:113], v[152:155], v[212:215], 0
	v_mfma_f32_16x16x32_bf16 v[106:109], v[180:183], v[212:215], 0
	v_mfma_f32_16x16x32_bf16 v[94:97], v[152:155], v[220:223], 0
	v_mfma_f32_16x16x32_bf16 v[90:93], v[180:183], v[220:223], 0
	v_mfma_f32_16x16x32_bf16 v[78:81], v[152:155], v[228:231], 0
	v_mfma_f32_16x16x32_bf16 v[74:77], v[180:183], v[228:231], 0
	v_mfma_f32_16x16x32_bf16 v[126:129], v[164:167], v[208:211], v[126:129]
	v_mfma_f32_16x16x32_bf16 v[122:125], v[184:187], v[208:211], v[122:125]
	v_mfma_f32_16x16x32_bf16 v[110:113], v[164:167], v[216:219], v[110:113]
	v_mfma_f32_16x16x32_bf16 v[106:109], v[184:187], v[216:219], v[106:109]
	v_mfma_f32_16x16x32_bf16 v[94:97], v[164:167], v[224:227], v[94:97]
	v_mfma_f32_16x16x32_bf16 v[90:93], v[184:187], v[224:227], v[90:93]
	v_mfma_f32_16x16x32_bf16 v[78:81], v[164:167], v[232:235], v[78:81]
	v_mfma_f32_16x16x32_bf16 v[74:77], v[184:187], v[232:235], v[74:77]
	s_setprio 0
	s_setprio 1
	v_mfma_f32_16x16x32_bf16 v[118:121], v[188:191], v[204:207], 0
	v_mfma_f32_16x16x32_bf16 v[114:117], v[196:199], v[204:207], 0
	v_mfma_f32_16x16x32_bf16 v[102:105], v[188:191], v[212:215], 0
	v_mfma_f32_16x16x32_bf16 v[98:101], v[196:199], v[212:215], 0
	v_mfma_f32_16x16x32_bf16 v[86:89], v[188:191], v[220:223], 0
	v_mfma_f32_16x16x32_bf16 v[82:85], v[196:199], v[220:223], 0
	v_mfma_f32_16x16x32_bf16 v[70:73], v[188:191], v[228:231], 0
	v_mfma_f32_16x16x32_bf16 v[66:69], v[196:199], v[228:231], 0
	v_mfma_f32_16x16x32_bf16 v[118:121], v[192:195], v[208:211], v[118:121]
	v_mfma_f32_16x16x32_bf16 v[114:117], v[200:203], v[208:211], v[114:117]
	v_mfma_f32_16x16x32_bf16 v[102:105], v[192:195], v[216:219], v[102:105]
	v_mfma_f32_16x16x32_bf16 v[98:101], v[200:203], v[216:219], v[98:101]
	v_mfma_f32_16x16x32_bf16 v[86:89], v[192:195], v[224:227], v[86:89]
	v_mfma_f32_16x16x32_bf16 v[82:85], v[200:203], v[224:227], v[82:85]
	s_setprio 2
	s_barrier
	v_mfma_f32_16x16x32_bf16 v[70:73], v[192:195], v[232:235], v[70:73]
	v_mfma_f32_16x16x32_bf16 v[66:69], v[200:203], v[232:235], v[66:69]
	s_setprio 0
	s_add_i32 s52, s52, s44
	v_lshl_add_u64 v[160:161], s[40:41], 0, v[162:163]
	s_mov_b32 m0, s52
	ds_read_b128 v[204:207], v145 offset:16384
	ds_read_b128 v[208:211], v145 offset:17408
	ds_read_b128 v[212:215], v145 offset:18432
	ds_read_b128 v[216:219], v145 offset:19456
	ds_read_b128 v[220:223], v145 offset:20480
	ds_read_b128 v[224:227], v145 offset:21504
	ds_read_b128 v[228:231], v145 offset:22528
	ds_read_b128 v[232:235], v145 offset:23552
	global_load_lds_dwordx4 v[160:161], off
	s_add_i32 m0, s52, 0x2000
	s_add_u32 s52, s40, 0x80000
	v_lshl_add_u64 v[168:169], s[40:41], 0, v[130:131]
	s_addc_u32 s53, s41, 0
	s_add_i32 s54, s54, s44
	global_load_lds_dwordx4 v[168:169], off
	v_lshl_add_u64 v[236:237], s[52:53], 0, v[162:163]
	s_mov_b32 m0, s54
	v_lshl_add_u64 v[238:239], s[42:43], 0, v[132:133]
	global_load_lds_dwordx4 v[236:237], off
	v_lshl_add_u64 v[236:237], s[52:53], 0, v[130:131]
	s_add_i32 m0, s54, 0x2000
	s_nop 0
	global_load_lds_dwordx4 v[236:237], off
	v_lshl_add_u64 v[236:237], s[42:43], 0, v[134:135]
	s_mov_b32 m0, s45
	s_nop 0
	global_load_lds_dwordx4 v[236:237], off
	s_mov_b32 m0, s46
	s_nop 0
	global_load_lds_dwordx4 v[238:239], off
	s_cmp_eq_u32 s51, 1
	s_cbranch_scc0 .Lg5_later_tile
	s_waitcnt vmcnt(8)
.Lg5_later_tile:
	s_waitcnt lgkmcnt(0)
	s_barrier
	s_setprio 1
	s_waitcnt lgkmcnt(0)
	v_mfma_f32_16x16x32_bf16 v[62:65], v[152:155], v[204:207], 0
	v_mfma_f32_16x16x32_bf16 v[58:61], v[180:183], v[204:207], 0
	v_mfma_f32_16x16x32_bf16 v[46:49], v[152:155], v[212:215], 0
	v_mfma_f32_16x16x32_bf16 v[42:45], v[180:183], v[212:215], 0
	v_mfma_f32_16x16x32_bf16 v[30:33], v[152:155], v[220:223], 0
	v_mfma_f32_16x16x32_bf16 v[26:29], v[180:183], v[220:223], 0
	v_mfma_f32_16x16x32_bf16 v[14:17], v[152:155], v[228:231], 0
	v_mfma_f32_16x16x32_bf16 v[10:13], v[180:183], v[228:231], 0
	v_mfma_f32_16x16x32_bf16 v[62:65], v[164:167], v[208:211], v[62:65]
	v_mfma_f32_16x16x32_bf16 v[58:61], v[184:187], v[208:211], v[58:61]
	v_mfma_f32_16x16x32_bf16 v[46:49], v[164:167], v[216:219], v[46:49]
	v_mfma_f32_16x16x32_bf16 v[42:45], v[184:187], v[216:219], v[42:45]
	v_mfma_f32_16x16x32_bf16 v[30:33], v[164:167], v[224:227], v[30:33]
	v_mfma_f32_16x16x32_bf16 v[26:29], v[184:187], v[224:227], v[26:29]
	v_mfma_f32_16x16x32_bf16 v[14:17], v[164:167], v[232:235], v[14:17]
	v_mfma_f32_16x16x32_bf16 v[10:13], v[184:187], v[232:235], v[10:13]
	s_setprio 0
	s_setprio 1
	v_mfma_f32_16x16x32_bf16 v[54:57], v[188:191], v[204:207], 0
	v_mfma_f32_16x16x32_bf16 v[50:53], v[196:199], v[204:207], 0
	v_mfma_f32_16x16x32_bf16 v[38:41], v[188:191], v[212:215], 0
	v_mfma_f32_16x16x32_bf16 v[34:37], v[196:199], v[212:215], 0
	v_mfma_f32_16x16x32_bf16 v[22:25], v[188:191], v[220:223], 0
	v_mfma_f32_16x16x32_bf16 v[18:21], v[196:199], v[220:223], 0
	v_mfma_f32_16x16x32_bf16 v[6:9], v[188:191], v[228:231], 0
	v_mfma_f32_16x16x32_bf16 v[2:5], v[196:199], v[228:231], 0
	v_mfma_f32_16x16x32_bf16 v[54:57], v[192:195], v[208:211], v[54:57]
	v_mfma_f32_16x16x32_bf16 v[50:53], v[200:203], v[208:211], v[50:53]
	v_mfma_f32_16x16x32_bf16 v[38:41], v[192:195], v[216:219], v[38:41]
	v_mfma_f32_16x16x32_bf16 v[34:37], v[200:203], v[216:219], v[34:37]
	v_mfma_f32_16x16x32_bf16 v[22:25], v[192:195], v[224:227], v[22:25]
	v_mfma_f32_16x16x32_bf16 v[18:21], v[200:203], v[224:227], v[18:21]
	s_setprio 2
	s_barrier
	v_mfma_f32_16x16x32_bf16 v[6:9], v[192:195], v[232:235], v[6:9]
	v_mfma_f32_16x16x32_bf16 v[2:5], v[200:203], v[232:235], v[2:5]
	s_setprio 0
	s_add_i32 s52, 0, 0x18000
	v_add_u32_e32 v147, s52, v141
	s_add_i32 s53, 0, 0x1c000
	ds_read_b128 v[152:155], v147
	ds_read_b128 v[164:167], v147 offset:1024
	ds_read_b128 v[180:183], v147 offset:2048
	ds_read_b128 v[184:187], v147 offset:3072
	v_add_u32_e32 v147, s53, v141
	ds_read_b128 v[188:191], v147
	ds_read_b128 v[192:195], v147 offset:1024
	ds_read_b128 v[196:199], v147 offset:2048
	ds_read_b128 v[200:203], v147 offset:3072
	s_add_u32 s42, s42, 0x80000
	s_addc_u32 s43, s43, 0
	s_mov_b32 m0, s47
	v_lshl_add_u64 v[240:241], s[42:43], 0, v[134:135]
	ds_read_b128 v[204:207], v145 offset:32768
	ds_read_b128 v[208:211], v145 offset:33792
	ds_read_b128 v[212:215], v145 offset:34816
	ds_read_b128 v[216:219], v145 offset:35840
	ds_read_b128 v[220:223], v145 offset:36864
	ds_read_b128 v[224:227], v145 offset:37888
	ds_read_b128 v[228:231], v145 offset:38912
	ds_read_b128 v[232:235], v145 offset:39936
	global_load_lds_dwordx4 v[240:241], off
	v_lshl_add_u64 v[240:241], s[42:43], 0, v[132:133]
	s_mov_b32 m0, s48
	s_nop 0
	global_load_lds_dwordx4 v[240:241], off
	s_waitcnt vmcnt(8)
	s_waitcnt lgkmcnt(0)
	s_barrier
	s_setprio 1
	s_waitcnt lgkmcnt(0)
	v_mfma_f32_16x16x32_bf16 v[126:129], v[152:155], v[204:207], v[126:129]
	v_mfma_f32_16x16x32_bf16 v[122:125], v[180:183], v[204:207], v[122:125]
	v_mfma_f32_16x16x32_bf16 v[110:113], v[152:155], v[212:215], v[110:113]
	v_mfma_f32_16x16x32_bf16 v[106:109], v[180:183], v[212:215], v[106:109]
	v_mfma_f32_16x16x32_bf16 v[94:97], v[152:155], v[220:223], v[94:97]
	v_mfma_f32_16x16x32_bf16 v[90:93], v[180:183], v[220:223], v[90:93]
	v_mfma_f32_16x16x32_bf16 v[78:81], v[152:155], v[228:231], v[78:81]
	v_mfma_f32_16x16x32_bf16 v[74:77], v[180:183], v[228:231], v[74:77]
	v_mfma_f32_16x16x32_bf16 v[126:129], v[164:167], v[208:211], v[126:129]
	v_mfma_f32_16x16x32_bf16 v[122:125], v[184:187], v[208:211], v[122:125]
	v_mfma_f32_16x16x32_bf16 v[110:113], v[164:167], v[216:219], v[110:113]
	v_mfma_f32_16x16x32_bf16 v[106:109], v[184:187], v[216:219], v[106:109]
	v_mfma_f32_16x16x32_bf16 v[94:97], v[164:167], v[224:227], v[94:97]
	v_mfma_f32_16x16x32_bf16 v[90:93], v[184:187], v[224:227], v[90:93]
	v_mfma_f32_16x16x32_bf16 v[78:81], v[164:167], v[232:235], v[78:81]
	v_mfma_f32_16x16x32_bf16 v[74:77], v[184:187], v[232:235], v[74:77]
	s_setprio 0
	s_setprio 1
	v_mfma_f32_16x16x32_bf16 v[118:121], v[188:191], v[204:207], v[118:121]
	v_mfma_f32_16x16x32_bf16 v[114:117], v[196:199], v[204:207], v[114:117]
	v_mfma_f32_16x16x32_bf16 v[102:105], v[188:191], v[212:215], v[102:105]
	v_mfma_f32_16x16x32_bf16 v[98:101], v[196:199], v[212:215], v[98:101]
	v_mfma_f32_16x16x32_bf16 v[86:89], v[188:191], v[220:223], v[86:89]
	v_mfma_f32_16x16x32_bf16 v[82:85], v[196:199], v[220:223], v[82:85]
	v_mfma_f32_16x16x32_bf16 v[70:73], v[188:191], v[228:231], v[70:73]
	v_mfma_f32_16x16x32_bf16 v[66:69], v[196:199], v[228:231], v[66:69]
	v_mfma_f32_16x16x32_bf16 v[118:121], v[192:195], v[208:211], v[118:121]
	v_mfma_f32_16x16x32_bf16 v[114:117], v[200:203], v[208:211], v[114:117]
	v_mfma_f32_16x16x32_bf16 v[102:105], v[192:195], v[216:219], v[102:105]
	v_mfma_f32_16x16x32_bf16 v[98:101], v[200:203], v[216:219], v[98:101]
	v_mfma_f32_16x16x32_bf16 v[86:89], v[192:195], v[224:227], v[86:89]
	v_mfma_f32_16x16x32_bf16 v[82:85], v[200:203], v[224:227], v[82:85]
	s_setprio 2
	s_barrier
	v_mfma_f32_16x16x32_bf16 v[70:73], v[192:195], v[232:235], v[70:73]
	v_mfma_f32_16x16x32_bf16 v[66:69], v[200:203], v[232:235], v[66:69]
	s_setprio 0
	s_add_i32 s42, s52, s44
	v_lshl_add_u64 v[160:161], v[160:161], 0, s[6:7]
	s_mov_b32 m0, s42
	ds_read_b128 v[204:207], v145 offset:49152
	ds_read_b128 v[208:211], v145 offset:50176
	ds_read_b128 v[212:215], v145 offset:51200
	ds_read_b128 v[216:219], v145 offset:52224
	ds_read_b128 v[220:223], v145 offset:53248
	ds_read_b128 v[224:227], v145 offset:54272
	ds_read_b128 v[228:231], v145 offset:55296
	ds_read_b128 v[232:235], v145 offset:56320
	global_load_lds_dwordx4 v[160:161], off
	s_add_i32 m0, s42, 0x2000
	s_add_u32 s40, s40, 0x80080
	v_lshl_add_u64 v[160:161], v[168:169], 0, s[6:7]
	s_addc_u32 s41, s41, 0
	s_add_i32 s42, s53, s44
	global_load_lds_dwordx4 v[160:161], off
	v_lshl_add_u64 v[160:161], s[40:41], 0, v[162:163]
	s_mov_b32 m0, s42
	s_nop 0
	global_load_lds_dwordx4 v[160:161], off
	v_lshl_add_u64 v[160:161], s[40:41], 0, v[130:131]
	s_add_i32 m0, s42, 0x2000
	s_nop 0
	global_load_lds_dwordx4 v[160:161], off
	v_lshl_add_u64 v[160:161], v[236:237], 0, s[6:7]
	s_mov_b32 m0, s49
	s_nop 0
	global_load_lds_dwordx4 v[160:161], off
	v_lshl_add_u64 v[160:161], v[238:239], 0, s[6:7]
	s_mov_b32 m0, s50
	s_nop 0
	global_load_lds_dwordx4 v[160:161], off
	s_waitcnt vmcnt(8)
	s_waitcnt lgkmcnt(0)
	s_barrier
	s_setprio 1
	s_waitcnt lgkmcnt(0)
	v_mfma_f32_16x16x32_bf16 v[62:65], v[152:155], v[204:207], v[62:65]
	v_mfma_f32_16x16x32_bf16 v[58:61], v[180:183], v[204:207], v[58:61]
	v_mfma_f32_16x16x32_bf16 v[46:49], v[152:155], v[212:215], v[46:49]
	v_mfma_f32_16x16x32_bf16 v[42:45], v[180:183], v[212:215], v[42:45]
	v_mfma_f32_16x16x32_bf16 v[30:33], v[152:155], v[220:223], v[30:33]
	v_mfma_f32_16x16x32_bf16 v[26:29], v[180:183], v[220:223], v[26:29]
	v_mfma_f32_16x16x32_bf16 v[14:17], v[152:155], v[228:231], v[14:17]
	v_mfma_f32_16x16x32_bf16 v[10:13], v[180:183], v[228:231], v[10:13]
	v_mfma_f32_16x16x32_bf16 v[62:65], v[164:167], v[208:211], v[62:65]
	v_mfma_f32_16x16x32_bf16 v[58:61], v[184:187], v[208:211], v[58:61]
	v_mfma_f32_16x16x32_bf16 v[46:49], v[164:167], v[216:219], v[46:49]
	v_mfma_f32_16x16x32_bf16 v[42:45], v[184:187], v[216:219], v[42:45]
	v_mfma_f32_16x16x32_bf16 v[30:33], v[164:167], v[224:227], v[30:33]
	v_mfma_f32_16x16x32_bf16 v[26:29], v[184:187], v[224:227], v[26:29]
	v_mfma_f32_16x16x32_bf16 v[14:17], v[164:167], v[232:235], v[14:17]
	v_mfma_f32_16x16x32_bf16 v[10:13], v[184:187], v[232:235], v[10:13]
	s_setprio 0
	s_setprio 1
	v_mfma_f32_16x16x32_bf16 v[54:57], v[188:191], v[204:207], v[54:57]
	v_mfma_f32_16x16x32_bf16 v[50:53], v[196:199], v[204:207], v[50:53]
	v_mfma_f32_16x16x32_bf16 v[38:41], v[188:191], v[212:215], v[38:41]
	v_mfma_f32_16x16x32_bf16 v[34:37], v[196:199], v[212:215], v[34:37]
	v_mfma_f32_16x16x32_bf16 v[22:25], v[188:191], v[220:223], v[22:25]
	v_mfma_f32_16x16x32_bf16 v[18:21], v[196:199], v[220:223], v[18:21]
	v_mfma_f32_16x16x32_bf16 v[6:9], v[188:191], v[228:231], v[6:9]
	v_mfma_f32_16x16x32_bf16 v[2:5], v[196:199], v[228:231], v[2:5]
	v_mfma_f32_16x16x32_bf16 v[54:57], v[192:195], v[208:211], v[54:57]
	v_mfma_f32_16x16x32_bf16 v[50:53], v[200:203], v[208:211], v[50:53]
	v_mfma_f32_16x16x32_bf16 v[38:41], v[192:195], v[216:219], v[38:41]
	v_mfma_f32_16x16x32_bf16 v[34:37], v[200:203], v[216:219], v[34:37]
	v_mfma_f32_16x16x32_bf16 v[22:25], v[192:195], v[224:227], v[22:25]
	v_mfma_f32_16x16x32_bf16 v[18:21], v[200:203], v[224:227], v[18:21]
	s_setprio 2
	s_barrier
	v_mfma_f32_16x16x32_bf16 v[6:9], v[192:195], v[232:235], v[6:9]
	v_mfma_f32_16x16x32_bf16 v[2:5], v[200:203], v[232:235], v[2:5]
	s_setprio 0
	s_add_i32 s26, s26, 2
	s_add_u32 s22, s22, 0x100
	s_addc_u32 s23, s23, 0
	s_add_u32 s20, s20, 0x100
	s_addc_u32 s21, s21, 0
	s_cmp_gt_u32 s26, 29
.LBB0_1798:
	s_add_u32 s40, s22, 0xfff80080
	s_addc_u32 s41, s23, -1
	s_add_i32 s52, 0, 0x10000
	s_cmp_eq_u32 s26, 28
	s_cselect_b32 s43, s11, s41
	s_cselect_b32 s42, s13, s40
	v_add_u32_e32 v147, s52, v141
	s_cselect_b32 s41, s5, s21
	s_cselect_b32 s40, s19, s20
	s_add_i32 s54, 0, 0x14000
	ds_read_b128 v[152:155], v147
	ds_read_b128 v[164:167], v147 offset:1024
	ds_read_b128 v[180:183], v147 offset:2048
	ds_read_b128 v[184:187], v147 offset:3072
	v_add_u32_e32 v147, s54, v141
	ds_read_b128 v[188:191], v147
	ds_read_b128 v[192:195], v147 offset:1024
	ds_read_b128 v[196:199], v147 offset:2048
	ds_read_b128 v[200:203], v147 offset:3072
	v_lshl_add_u64 v[160:161], s[22:23], 0, v[136:137]
	s_add_i32 m0, s45, 0xc000
	ds_read_b128 v[204:207], v145
	ds_read_b128 v[208:211], v145 offset:1024
	ds_read_b128 v[212:215], v145 offset:2048
	ds_read_b128 v[216:219], v145 offset:3072
	ds_read_b128 v[220:223], v145 offset:4096
	ds_read_b128 v[224:227], v145 offset:5120
	ds_read_b128 v[228:231], v145 offset:6144
	ds_read_b128 v[232:235], v145 offset:7168
	global_load_lds_dwordx4 v[160:161], off
	v_lshl_add_u64 v[160:161], s[22:23], 0, v[138:139]
	s_add_i32 m0, s45, 0xe000
	s_nop 0
	global_load_lds_dwordx4 v[160:161], off
	s_waitcnt vmcnt(8)
	s_waitcnt lgkmcnt(0)
	s_barrier
	s_setprio 1
	s_waitcnt lgkmcnt(0)
	v_mfma_f32_16x16x32_bf16 v[126:129], v[152:155], v[204:207], v[126:129]
	v_mfma_f32_16x16x32_bf16 v[122:125], v[180:183], v[204:207], v[122:125]
	v_mfma_f32_16x16x32_bf16 v[110:113], v[152:155], v[212:215], v[110:113]
	v_mfma_f32_16x16x32_bf16 v[106:109], v[180:183], v[212:215], v[106:109]
	v_mfma_f32_16x16x32_bf16 v[94:97], v[152:155], v[220:223], v[94:97]
	v_mfma_f32_16x16x32_bf16 v[90:93], v[180:183], v[220:223], v[90:93]
	v_mfma_f32_16x16x32_bf16 v[78:81], v[152:155], v[228:231], v[78:81]
	v_mfma_f32_16x16x32_bf16 v[74:77], v[180:183], v[228:231], v[74:77]
	v_mfma_f32_16x16x32_bf16 v[126:129], v[164:167], v[208:211], v[126:129]
	v_mfma_f32_16x16x32_bf16 v[122:125], v[184:187], v[208:211], v[122:125]
	v_mfma_f32_16x16x32_bf16 v[110:113], v[164:167], v[216:219], v[110:113]
	v_mfma_f32_16x16x32_bf16 v[106:109], v[184:187], v[216:219], v[106:109]
	v_mfma_f32_16x16x32_bf16 v[94:97], v[164:167], v[224:227], v[94:97]
	v_mfma_f32_16x16x32_bf16 v[90:93], v[184:187], v[224:227], v[90:93]
	v_mfma_f32_16x16x32_bf16 v[78:81], v[164:167], v[232:235], v[78:81]
	v_mfma_f32_16x16x32_bf16 v[74:77], v[184:187], v[232:235], v[74:77]
	s_setprio 0
	s_setprio 1
	v_mfma_f32_16x16x32_bf16 v[118:121], v[188:191], v[204:207], v[118:121]
	v_mfma_f32_16x16x32_bf16 v[114:117], v[196:199], v[204:207], v[114:117]
	v_mfma_f32_16x16x32_bf16 v[102:105], v[188:191], v[212:215], v[102:105]
	v_mfma_f32_16x16x32_bf16 v[98:101], v[196:199], v[212:215], v[98:101]
	v_mfma_f32_16x16x32_bf16 v[86:89], v[188:191], v[220:223], v[86:89]
	v_mfma_f32_16x16x32_bf16 v[82:85], v[196:199], v[220:223], v[82:85]
	v_mfma_f32_16x16x32_bf16 v[70:73], v[188:191], v[228:231], v[70:73]
	v_mfma_f32_16x16x32_bf16 v[66:69], v[196:199], v[228:231], v[66:69]
	v_mfma_f32_16x16x32_bf16 v[118:121], v[192:195], v[208:211], v[118:121]
	v_mfma_f32_16x16x32_bf16 v[114:117], v[200:203], v[208:211], v[114:117]
	v_mfma_f32_16x16x32_bf16 v[102:105], v[192:195], v[216:219], v[102:105]
	v_mfma_f32_16x16x32_bf16 v[98:101], v[200:203], v[216:219], v[98:101]
	v_mfma_f32_16x16x32_bf16 v[86:89], v[192:195], v[224:227], v[86:89]
	v_mfma_f32_16x16x32_bf16 v[82:85], v[200:203], v[224:227], v[82:85]
	s_setprio 2
	s_barrier
	v_mfma_f32_16x16x32_bf16 v[70:73], v[192:195], v[232:235], v[70:73]
	v_mfma_f32_16x16x32_bf16 v[66:69], v[200:203], v[232:235], v[66:69]
	s_setprio 0
	s_add_i32 s52, s52, s44
	v_lshl_add_u64 v[160:161], s[40:41], 0, v[162:163]
	s_mov_b32 m0, s52
	ds_read_b128 v[204:207], v145 offset:16384
	ds_read_b128 v[208:211], v145 offset:17408
	ds_read_b128 v[212:215], v145 offset:18432
	ds_read_b128 v[216:219], v145 offset:19456
	ds_read_b128 v[220:223], v145 offset:20480
	ds_read_b128 v[224:227], v145 offset:21504
	ds_read_b128 v[228:231], v145 offset:22528
	ds_read_b128 v[232:235], v145 offset:23552
	global_load_lds_dwordx4 v[160:161], off
	s_add_i32 m0, s52, 0x2000
	s_add_u32 s52, s40, 0x80000
	v_lshl_add_u64 v[168:169], s[40:41], 0, v[130:131]
	s_addc_u32 s53, s41, 0
	s_add_i32 s54, s54, s44
	global_load_lds_dwordx4 v[168:169], off
	v_lshl_add_u64 v[236:237], s[52:53], 0, v[162:163]
	s_mov_b32 m0, s54
	v_lshl_add_u64 v[238:239], s[42:43], 0, v[132:133]
	global_load_lds_dwordx4 v[236:237], off
	v_lshl_add_u64 v[236:237], s[52:53], 0, v[130:131]
	s_add_i32 m0, s54, 0x2000
	s_nop 0
	global_load_lds_dwordx4 v[236:237], off
	v_lshl_add_u64 v[236:237], s[42:43], 0, v[134:135]
	s_mov_b32 m0, s45
	s_nop 0
	global_load_lds_dwordx4 v[236:237], off
	s_mov_b32 m0, s46
	s_nop 0
	global_load_lds_dwordx4 v[238:239], off
	s_waitcnt vmcnt(8)
	s_waitcnt lgkmcnt(0)
	s_barrier
	s_setprio 1
	s_waitcnt lgkmcnt(0)
	v_mfma_f32_16x16x32_bf16 v[62:65], v[152:155], v[204:207], v[62:65]
	v_mfma_f32_16x16x32_bf16 v[58:61], v[180:183], v[204:207], v[58:61]
	v_mfma_f32_16x16x32_bf16 v[46:49], v[152:155], v[212:215], v[46:49]
	v_mfma_f32_16x16x32_bf16 v[42:45], v[180:183], v[212:215], v[42:45]
	v_mfma_f32_16x16x32_bf16 v[30:33], v[152:155], v[220:223], v[30:33]
	v_mfma_f32_16x16x32_bf16 v[26:29], v[180:183], v[220:223], v[26:29]
	v_mfma_f32_16x16x32_bf16 v[14:17], v[152:155], v[228:231], v[14:17]
	v_mfma_f32_16x16x32_bf16 v[10:13], v[180:183], v[228:231], v[10:13]
	v_mfma_f32_16x16x32_bf16 v[62:65], v[164:167], v[208:211], v[62:65]
	v_mfma_f32_16x16x32_bf16 v[58:61], v[184:187], v[208:211], v[58:61]
	v_mfma_f32_16x16x32_bf16 v[46:49], v[164:167], v[216:219], v[46:49]
	v_mfma_f32_16x16x32_bf16 v[42:45], v[184:187], v[216:219], v[42:45]
	v_mfma_f32_16x16x32_bf16 v[30:33], v[164:167], v[224:227], v[30:33]
	v_mfma_f32_16x16x32_bf16 v[26:29], v[184:187], v[224:227], v[26:29]
	v_mfma_f32_16x16x32_bf16 v[14:17], v[164:167], v[232:235], v[14:17]
	v_mfma_f32_16x16x32_bf16 v[10:13], v[184:187], v[232:235], v[10:13]
	s_setprio 0
	s_setprio 1
	v_mfma_f32_16x16x32_bf16 v[54:57], v[188:191], v[204:207], v[54:57]
	v_mfma_f32_16x16x32_bf16 v[50:53], v[196:199], v[204:207], v[50:53]
	v_mfma_f32_16x16x32_bf16 v[38:41], v[188:191], v[212:215], v[38:41]
	v_mfma_f32_16x16x32_bf16 v[34:37], v[196:199], v[212:215], v[34:37]
	v_mfma_f32_16x16x32_bf16 v[22:25], v[188:191], v[220:223], v[22:25]
	v_mfma_f32_16x16x32_bf16 v[18:21], v[196:199], v[220:223], v[18:21]
	v_mfma_f32_16x16x32_bf16 v[6:9], v[188:191], v[228:231], v[6:9]
	v_mfma_f32_16x16x32_bf16 v[2:5], v[196:199], v[228:231], v[2:5]
	v_mfma_f32_16x16x32_bf16 v[54:57], v[192:195], v[208:211], v[54:57]
	v_mfma_f32_16x16x32_bf16 v[50:53], v[200:203], v[208:211], v[50:53]
	v_mfma_f32_16x16x32_bf16 v[38:41], v[192:195], v[216:219], v[38:41]
	v_mfma_f32_16x16x32_bf16 v[34:37], v[200:203], v[216:219], v[34:37]
	v_mfma_f32_16x16x32_bf16 v[22:25], v[192:195], v[224:227], v[22:25]
	v_mfma_f32_16x16x32_bf16 v[18:21], v[200:203], v[224:227], v[18:21]
	s_setprio 2
	s_barrier
	v_mfma_f32_16x16x32_bf16 v[6:9], v[192:195], v[232:235], v[6:9]
	v_mfma_f32_16x16x32_bf16 v[2:5], v[200:203], v[232:235], v[2:5]
	s_setprio 0
	s_add_i32 s52, 0, 0x18000
	v_add_u32_e32 v147, s52, v141
	s_add_i32 s53, 0, 0x1c000
	ds_read_b128 v[152:155], v147
	ds_read_b128 v[164:167], v147 offset:1024
	ds_read_b128 v[180:183], v147 offset:2048
	ds_read_b128 v[184:187], v147 offset:3072
	v_add_u32_e32 v147, s53, v141
	ds_read_b128 v[188:191], v147
	ds_read_b128 v[192:195], v147 offset:1024
	ds_read_b128 v[196:199], v147 offset:2048
	ds_read_b128 v[200:203], v147 offset:3072
	s_add_u32 s42, s42, 0x80000
	s_addc_u32 s43, s43, 0
	s_mov_b32 m0, s47
	v_lshl_add_u64 v[240:241], s[42:43], 0, v[134:135]
	ds_read_b128 v[204:207], v145 offset:32768
	ds_read_b128 v[208:211], v145 offset:33792
	ds_read_b128 v[212:215], v145 offset:34816
	ds_read_b128 v[216:219], v145 offset:35840
	ds_read_b128 v[220:223], v145 offset:36864
	ds_read_b128 v[224:227], v145 offset:37888
	ds_read_b128 v[228:231], v145 offset:38912
	ds_read_b128 v[232:235], v145 offset:39936
	global_load_lds_dwordx4 v[240:241], off
	v_lshl_add_u64 v[240:241], s[42:43], 0, v[132:133]
	s_mov_b32 m0, s48
	s_nop 0
	global_load_lds_dwordx4 v[240:241], off
	s_waitcnt vmcnt(8)
	s_waitcnt lgkmcnt(0)
	s_barrier
	s_setprio 1
	s_waitcnt lgkmcnt(0)
	v_mfma_f32_16x16x32_bf16 v[126:129], v[152:155], v[204:207], v[126:129]
	v_mfma_f32_16x16x32_bf16 v[122:125], v[180:183], v[204:207], v[122:125]
	v_mfma_f32_16x16x32_bf16 v[110:113], v[152:155], v[212:215], v[110:113]
	v_mfma_f32_16x16x32_bf16 v[106:109], v[180:183], v[212:215], v[106:109]
	v_mfma_f32_16x16x32_bf16 v[94:97], v[152:155], v[220:223], v[94:97]
	v_mfma_f32_16x16x32_bf16 v[90:93], v[180:183], v[220:223], v[90:93]
	v_mfma_f32_16x16x32_bf16 v[78:81], v[152:155], v[228:231], v[78:81]
	v_mfma_f32_16x16x32_bf16 v[74:77], v[180:183], v[228:231], v[74:77]
	v_mfma_f32_16x16x32_bf16 v[126:129], v[164:167], v[208:211], v[126:129]
	v_mfma_f32_16x16x32_bf16 v[122:125], v[184:187], v[208:211], v[122:125]
	v_mfma_f32_16x16x32_bf16 v[110:113], v[164:167], v[216:219], v[110:113]
	v_mfma_f32_16x16x32_bf16 v[106:109], v[184:187], v[216:219], v[106:109]
	v_mfma_f32_16x16x32_bf16 v[94:97], v[164:167], v[224:227], v[94:97]
	v_mfma_f32_16x16x32_bf16 v[90:93], v[184:187], v[224:227], v[90:93]
	v_mfma_f32_16x16x32_bf16 v[78:81], v[164:167], v[232:235], v[78:81]
	v_mfma_f32_16x16x32_bf16 v[74:77], v[184:187], v[232:235], v[74:77]
	s_setprio 0
	s_setprio 1
	v_mfma_f32_16x16x32_bf16 v[118:121], v[188:191], v[204:207], v[118:121]
	v_mfma_f32_16x16x32_bf16 v[114:117], v[196:199], v[204:207], v[114:117]
	v_mfma_f32_16x16x32_bf16 v[102:105], v[188:191], v[212:215], v[102:105]
	v_mfma_f32_16x16x32_bf16 v[98:101], v[196:199], v[212:215], v[98:101]
	v_mfma_f32_16x16x32_bf16 v[86:89], v[188:191], v[220:223], v[86:89]
	v_mfma_f32_16x16x32_bf16 v[82:85], v[196:199], v[220:223], v[82:85]
	v_mfma_f32_16x16x32_bf16 v[70:73], v[188:191], v[228:231], v[70:73]
	v_mfma_f32_16x16x32_bf16 v[66:69], v[196:199], v[228:231], v[66:69]
	v_mfma_f32_16x16x32_bf16 v[118:121], v[192:195], v[208:211], v[118:121]
	v_mfma_f32_16x16x32_bf16 v[114:117], v[200:203], v[208:211], v[114:117]
	v_mfma_f32_16x16x32_bf16 v[102:105], v[192:195], v[216:219], v[102:105]
	v_mfma_f32_16x16x32_bf16 v[98:101], v[200:203], v[216:219], v[98:101]
	v_mfma_f32_16x16x32_bf16 v[86:89], v[192:195], v[224:227], v[86:89]
	v_mfma_f32_16x16x32_bf16 v[82:85], v[200:203], v[224:227], v[82:85]
	s_setprio 2
	s_barrier
	v_mfma_f32_16x16x32_bf16 v[70:73], v[192:195], v[232:235], v[70:73]
	v_mfma_f32_16x16x32_bf16 v[66:69], v[200:203], v[232:235], v[66:69]
	s_setprio 0
	s_add_i32 s42, s52, s44
	v_lshl_add_u64 v[160:161], v[160:161], 0, s[6:7]
	s_mov_b32 m0, s42
	ds_read_b128 v[204:207], v145 offset:49152
	ds_read_b128 v[208:211], v145 offset:50176
	ds_read_b128 v[212:215], v145 offset:51200
	ds_read_b128 v[216:219], v145 offset:52224
	ds_read_b128 v[220:223], v145 offset:53248
	ds_read_b128 v[224:227], v145 offset:54272
	ds_read_b128 v[228:231], v145 offset:55296
	ds_read_b128 v[232:235], v145 offset:56320
	global_load_lds_dwordx4 v[160:161], off
	s_add_i32 m0, s42, 0x2000
	s_add_u32 s40, s40, 0x80080
	v_lshl_add_u64 v[160:161], v[168:169], 0, s[6:7]
	s_addc_u32 s41, s41, 0
	s_add_i32 s42, s53, s44
	global_load_lds_dwordx4 v[160:161], off
	v_lshl_add_u64 v[160:161], s[40:41], 0, v[162:163]
	s_mov_b32 m0, s42
	s_nop 0
	global_load_lds_dwordx4 v[160:161], off
	v_lshl_add_u64 v[160:161], s[40:41], 0, v[130:131]
	s_add_i32 m0, s42, 0x2000
	s_nop 0
	global_load_lds_dwordx4 v[160:161], off
	v_lshl_add_u64 v[160:161], v[236:237], 0, s[6:7]
	s_mov_b32 m0, s49
	s_nop 0
	global_load_lds_dwordx4 v[160:161], off
	v_lshl_add_u64 v[160:161], v[238:239], 0, s[6:7]
	s_mov_b32 m0, s50
	s_nop 0
	global_load_lds_dwordx4 v[160:161], off
	s_waitcnt vmcnt(8)
	s_waitcnt lgkmcnt(0)
	s_barrier
	s_setprio 1
	s_waitcnt lgkmcnt(0)
	v_mfma_f32_16x16x32_bf16 v[62:65], v[152:155], v[204:207], v[62:65]
	v_mfma_f32_16x16x32_bf16 v[58:61], v[180:183], v[204:207], v[58:61]
	v_mfma_f32_16x16x32_bf16 v[46:49], v[152:155], v[212:215], v[46:49]
	v_mfma_f32_16x16x32_bf16 v[42:45], v[180:183], v[212:215], v[42:45]
	v_mfma_f32_16x16x32_bf16 v[30:33], v[152:155], v[220:223], v[30:33]
	v_mfma_f32_16x16x32_bf16 v[26:29], v[180:183], v[220:223], v[26:29]
	v_mfma_f32_16x16x32_bf16 v[14:17], v[152:155], v[228:231], v[14:17]
	v_mfma_f32_16x16x32_bf16 v[10:13], v[180:183], v[228:231], v[10:13]
	v_mfma_f32_16x16x32_bf16 v[62:65], v[164:167], v[208:211], v[62:65]
	v_mfma_f32_16x16x32_bf16 v[58:61], v[184:187], v[208:211], v[58:61]
	v_mfma_f32_16x16x32_bf16 v[46:49], v[164:167], v[216:219], v[46:49]
	v_mfma_f32_16x16x32_bf16 v[42:45], v[184:187], v[216:219], v[42:45]
	v_mfma_f32_16x16x32_bf16 v[30:33], v[164:167], v[224:227], v[30:33]
	v_mfma_f32_16x16x32_bf16 v[26:29], v[184:187], v[224:227], v[26:29]
	v_mfma_f32_16x16x32_bf16 v[14:17], v[164:167], v[232:235], v[14:17]
	v_mfma_f32_16x16x32_bf16 v[10:13], v[184:187], v[232:235], v[10:13]
	s_setprio 0
	s_setprio 1
	v_mfma_f32_16x16x32_bf16 v[54:57], v[188:191], v[204:207], v[54:57]
	v_mfma_f32_16x16x32_bf16 v[50:53], v[196:199], v[204:207], v[50:53]
	v_mfma_f32_16x16x32_bf16 v[38:41], v[188:191], v[212:215], v[38:41]
	v_mfma_f32_16x16x32_bf16 v[34:37], v[196:199], v[212:215], v[34:37]
	v_mfma_f32_16x16x32_bf16 v[22:25], v[188:191], v[220:223], v[22:25]
	v_mfma_f32_16x16x32_bf16 v[18:21], v[196:199], v[220:223], v[18:21]
	v_mfma_f32_16x16x32_bf16 v[6:9], v[188:191], v[228:231], v[6:9]
	v_mfma_f32_16x16x32_bf16 v[2:5], v[196:199], v[228:231], v[2:5]
	v_mfma_f32_16x16x32_bf16 v[54:57], v[192:195], v[208:211], v[54:57]
	v_mfma_f32_16x16x32_bf16 v[50:53], v[200:203], v[208:211], v[50:53]
	v_mfma_f32_16x16x32_bf16 v[38:41], v[192:195], v[216:219], v[38:41]
	v_mfma_f32_16x16x32_bf16 v[34:37], v[200:203], v[216:219], v[34:37]
	v_mfma_f32_16x16x32_bf16 v[22:25], v[192:195], v[224:227], v[22:25]
	v_mfma_f32_16x16x32_bf16 v[18:21], v[200:203], v[224:227], v[18:21]
	s_setprio 2
	s_barrier
	v_mfma_f32_16x16x32_bf16 v[6:9], v[192:195], v[232:235], v[6:9]
	v_mfma_f32_16x16x32_bf16 v[2:5], v[200:203], v[232:235], v[2:5]
	s_setprio 0
	s_add_i32 s26, s26, 2
	s_add_u32 s22, s22, 0x100
	s_addc_u32 s23, s23, 0
	s_add_u32 s20, s20, 0x100
	s_addc_u32 s21, s21, 0
	s_cmp_gt_u32 s26, 29
	s_cbranch_scc0 .LBB0_1798
	s_and_b64 vcc, exec, s[2:3]
	s_cbranch_vccz .LBB0_1801
	s_barrier

.LBB0_1873:
	s_add_u32 s45, s28, 0x100
	s_addc_u32 s46, s29, 0
	s_mov_b32 s47, -2
	s_waitcnt vmcnt(0) lgkmcnt(0)
	s_add_u32 s28, s22, 0x100
	s_addc_u32 s29, s23, 0
	s_add_i32 s48, 0, 0x10000
	s_cmpk_eq_i32 s47, 0x54
	s_cselect_b32 s39, s5, s29
	s_cselect_b32 s38, s4, s28
	v_add_u32_e32 v154, s48, v145
	s_cselect_b32 s35, s19, s46
	s_cselect_b32 s34, s18, s45
	s_add_i32 s49, 0, 0x14000
	ds_read_b128 v[130:133], v154
	ds_read_b128 v[134:137], v154 offset:1024
	ds_read_b128 v[150:153], v154 offset:2048
	ds_read_b128 v[158:161], v154 offset:3072
	v_add_u32_e32 v154, s49, v145
	ds_read_b128 v[164:167], v154
	ds_read_b128 v[180:183], v154 offset:1024
	ds_read_b128 v[184:187], v154 offset:2048
	ds_read_b128 v[188:191], v154 offset:3072
	v_lshl_add_u64 v[154:155], s[22:23], 0, v[146:147]
	s_add_i32 m0, s20, 0xc000
	ds_read_b128 v[192:195], v157
	ds_read_b128 v[196:199], v157 offset:1024
	ds_read_b128 v[200:203], v157 offset:2048
	ds_read_b128 v[204:207], v157 offset:3072
	ds_read_b128 v[208:211], v157 offset:4096
	ds_read_b128 v[212:215], v157 offset:5120
	ds_read_b128 v[216:219], v157 offset:6144
	ds_read_b128 v[220:223], v157 offset:7168
	global_load_lds_dwordx4 v[154:155], off
	v_lshl_add_u64 v[154:155], s[22:23], 0, v[148:149]
	s_add_i32 m0, s20, 0xe000
	s_nop 0
	global_load_lds_dwordx4 v[154:155], off
	s_waitcnt vmcnt(8)
	s_waitcnt lgkmcnt(0)
	s_barrier
	s_setprio 1
	s_waitcnt lgkmcnt(0)
	v_mfma_f32_16x16x32_bf16 v[126:129], v[130:133], v[192:195], 0
	v_mfma_f32_16x16x32_bf16 v[122:125], v[150:153], v[192:195], 0
	v_mfma_f32_16x16x32_bf16 v[110:113], v[130:133], v[200:203], 0
	v_mfma_f32_16x16x32_bf16 v[106:109], v[150:153], v[200:203], 0
	v_mfma_f32_16x16x32_bf16 v[94:97], v[130:133], v[208:211], 0
	v_mfma_f32_16x16x32_bf16 v[90:93], v[150:153], v[208:211], 0
	v_mfma_f32_16x16x32_bf16 v[78:81], v[130:133], v[216:219], 0
	v_mfma_f32_16x16x32_bf16 v[74:77], v[150:153], v[216:219], 0
	v_mfma_f32_16x16x32_bf16 v[126:129], v[134:137], v[196:199], v[126:129]
	v_mfma_f32_16x16x32_bf16 v[122:125], v[158:161], v[196:199], v[122:125]
	v_mfma_f32_16x16x32_bf16 v[110:113], v[134:137], v[204:207], v[110:113]
	v_mfma_f32_16x16x32_bf16 v[106:109], v[158:161], v[204:207], v[106:109]
	v_mfma_f32_16x16x32_bf16 v[94:97], v[134:137], v[212:215], v[94:97]
	v_mfma_f32_16x16x32_bf16 v[90:93], v[158:161], v[212:215], v[90:93]
	v_mfma_f32_16x16x32_bf16 v[78:81], v[134:137], v[220:223], v[78:81]
	v_mfma_f32_16x16x32_bf16 v[74:77], v[158:161], v[220:223], v[74:77]
	s_setprio 0
	s_setprio 1
	v_mfma_f32_16x16x32_bf16 v[118:121], v[164:167], v[192:195], 0
	v_mfma_f32_16x16x32_bf16 v[114:117], v[184:187], v[192:195], 0
	v_mfma_f32_16x16x32_bf16 v[102:105], v[164:167], v[200:203], 0
	v_mfma_f32_16x16x32_bf16 v[98:101], v[184:187], v[200:203], 0
	v_mfma_f32_16x16x32_bf16 v[86:89], v[164:167], v[208:211], 0
	v_mfma_f32_16x16x32_bf16 v[82:85], v[184:187], v[208:211], 0
	v_mfma_f32_16x16x32_bf16 v[70:73], v[164:167], v[216:219], 0
	v_mfma_f32_16x16x32_bf16 v[66:69], v[184:187], v[216:219], 0
	v_mfma_f32_16x16x32_bf16 v[118:121], v[180:183], v[196:199], v[118:121]
	v_mfma_f32_16x16x32_bf16 v[114:117], v[188:191], v[196:199], v[114:117]
	v_mfma_f32_16x16x32_bf16 v[102:105], v[180:183], v[204:207], v[102:105]
	v_mfma_f32_16x16x32_bf16 v[98:101], v[188:191], v[204:207], v[98:101]
	v_mfma_f32_16x16x32_bf16 v[86:89], v[180:183], v[212:215], v[86:89]
	v_mfma_f32_16x16x32_bf16 v[82:85], v[188:191], v[212:215], v[82:85]
	s_setprio 2
	s_barrier
	v_mfma_f32_16x16x32_bf16 v[70:73], v[180:183], v[220:223], v[70:73]
	v_mfma_f32_16x16x32_bf16 v[66:69], v[188:191], v[220:223], v[66:69]
	s_setprio 0
	s_add_i32 s22, s48, s9
	v_lshl_add_u64 v[154:155], s[34:35], 0, v[162:163]
	s_mov_b32 m0, s22
	ds_read_b128 v[192:195], v157 offset:16384
	ds_read_b128 v[196:199], v157 offset:17408
	ds_read_b128 v[200:203], v157 offset:18432
	ds_read_b128 v[204:207], v157 offset:19456
	ds_read_b128 v[208:211], v157 offset:20480
	ds_read_b128 v[212:215], v157 offset:21504
	ds_read_b128 v[216:219], v157 offset:22528
	ds_read_b128 v[220:223], v157 offset:23552
	global_load_lds_dwordx4 v[154:155], off
	s_add_i32 m0, s22, 0x2000
	s_add_u32 s22, s34, 0x160000
	v_lshl_add_u64 v[168:169], s[34:35], 0, v[142:143]
	s_addc_u32 s23, s35, 0
	s_add_i32 s48, s49, s9
	global_load_lds_dwordx4 v[168:169], off
	v_lshl_add_u64 v[224:225], s[22:23], 0, v[162:163]
	s_mov_b32 m0, s48
	v_lshl_add_u64 v[226:227], s[38:39], 0, v[140:141]
	global_load_lds_dwordx4 v[224:225], off
	v_lshl_add_u64 v[224:225], s[22:23], 0, v[142:143]
	s_add_i32 m0, s48, 0x2000
	s_nop 0
	global_load_lds_dwordx4 v[224:225], off
	v_lshl_add_u64 v[224:225], s[38:39], 0, v[138:139]
	s_mov_b32 m0, s20
	s_nop 0
	global_load_lds_dwordx4 v[224:225], off
	s_mov_b32 m0, s25
	s_nop 0
	global_load_lds_dwordx4 v[226:227], off
	s_waitcnt vmcnt(8)
	s_waitcnt lgkmcnt(0)
	s_barrier
	s_setprio 1
	s_waitcnt lgkmcnt(0)
	v_mfma_f32_16x16x32_bf16 v[62:65], v[130:133], v[192:195], 0
	v_mfma_f32_16x16x32_bf16 v[58:61], v[150:153], v[192:195], 0
	v_mfma_f32_16x16x32_bf16 v[46:49], v[130:133], v[200:203], 0
	v_mfma_f32_16x16x32_bf16 v[42:45], v[150:153], v[200:203], 0
	v_mfma_f32_16x16x32_bf16 v[30:33], v[130:133], v[208:211], 0
	v_mfma_f32_16x16x32_bf16 v[26:29], v[150:153], v[208:211], 0
	v_mfma_f32_16x16x32_bf16 v[14:17], v[130:133], v[216:219], 0
	v_mfma_f32_16x16x32_bf16 v[10:13], v[150:153], v[216:219], 0
	v_mfma_f32_16x16x32_bf16 v[62:65], v[134:137], v[196:199], v[62:65]
	v_mfma_f32_16x16x32_bf16 v[58:61], v[158:161], v[196:199], v[58:61]
	v_mfma_f32_16x16x32_bf16 v[46:49], v[134:137], v[204:207], v[46:49]
	v_mfma_f32_16x16x32_bf16 v[42:45], v[158:161], v[204:207], v[42:45]
	v_mfma_f32_16x16x32_bf16 v[30:33], v[134:137], v[212:215], v[30:33]
	v_mfma_f32_16x16x32_bf16 v[26:29], v[158:161], v[212:215], v[26:29]
	v_mfma_f32_16x16x32_bf16 v[14:17], v[134:137], v[220:223], v[14:17]
	v_mfma_f32_16x16x32_bf16 v[10:13], v[158:161], v[220:223], v[10:13]
	s_setprio 0
	s_setprio 1
	v_mfma_f32_16x16x32_bf16 v[54:57], v[164:167], v[192:195], 0
	v_mfma_f32_16x16x32_bf16 v[50:53], v[184:187], v[192:195], 0
	v_mfma_f32_16x16x32_bf16 v[38:41], v[164:167], v[200:203], 0
	v_mfma_f32_16x16x32_bf16 v[34:37], v[184:187], v[200:203], 0
	v_mfma_f32_16x16x32_bf16 v[22:25], v[164:167], v[208:211], 0
	v_mfma_f32_16x16x32_bf16 v[18:21], v[184:187], v[208:211], 0
	v_mfma_f32_16x16x32_bf16 v[6:9], v[164:167], v[216:219], 0
	v_mfma_f32_16x16x32_bf16 v[2:5], v[184:187], v[216:219], 0
	v_mfma_f32_16x16x32_bf16 v[54:57], v[180:183], v[196:199], v[54:57]
	v_mfma_f32_16x16x32_bf16 v[50:53], v[188:191], v[196:199], v[50:53]
	v_mfma_f32_16x16x32_bf16 v[38:41], v[180:183], v[204:207], v[38:41]
	v_mfma_f32_16x16x32_bf16 v[34:37], v[188:191], v[204:207], v[34:37]
	v_mfma_f32_16x16x32_bf16 v[22:25], v[180:183], v[212:215], v[22:25]
	v_mfma_f32_16x16x32_bf16 v[18:21], v[188:191], v[212:215], v[18:21]
	s_setprio 2
	s_barrier
	v_mfma_f32_16x16x32_bf16 v[6:9], v[180:183], v[220:223], v[6:9]
	v_mfma_f32_16x16x32_bf16 v[2:5], v[188:191], v[220:223], v[2:5]
	s_setprio 0
	s_add_i32 s48, 0, 0x18000
	s_add_i32 s49, 0, 0x1c000
	v_add_u32_e32 v158, s48, v145
	v_add_u32_e32 v179, s49, v145
	ds_read_b128 v[130:133], v158
	ds_read_b128 v[134:137], v158 offset:1024
	ds_read_b128 v[150:153], v158 offset:2048
	ds_read_b128 v[158:161], v158 offset:3072
	ds_read_b128 v[164:167], v179
	ds_read_b128 v[180:183], v179 offset:1024
	ds_read_b128 v[184:187], v179 offset:2048
	ds_read_b128 v[188:191], v179 offset:3072
	s_add_u32 s22, s38, 0x160000
	s_addc_u32 s23, s39, 0
	s_mov_b32 m0, s26
	v_lshl_add_u64 v[228:229], s[22:23], 0, v[138:139]
	ds_read_b128 v[192:195], v157 offset:32768
	ds_read_b128 v[196:199], v157 offset:33792
	ds_read_b128 v[200:203], v157 offset:34816
	ds_read_b128 v[204:207], v157 offset:35840
	ds_read_b128 v[208:211], v157 offset:36864
	ds_read_b128 v[212:215], v157 offset:37888
	ds_read_b128 v[216:219], v157 offset:38912
	ds_read_b128 v[220:223], v157 offset:39936
	global_load_lds_dwordx4 v[228:229], off
	v_lshl_add_u64 v[228:229], s[22:23], 0, v[140:141]
	s_mov_b32 m0, s27
	s_nop 0
	global_load_lds_dwordx4 v[228:229], off
	s_waitcnt vmcnt(8)
	s_waitcnt lgkmcnt(0)
	s_barrier
	s_setprio 1
	s_waitcnt lgkmcnt(0)
	v_mfma_f32_16x16x32_bf16 v[126:129], v[130:133], v[192:195], v[126:129]
	v_mfma_f32_16x16x32_bf16 v[122:125], v[150:153], v[192:195], v[122:125]
	v_mfma_f32_16x16x32_bf16 v[110:113], v[130:133], v[200:203], v[110:113]
	v_mfma_f32_16x16x32_bf16 v[106:109], v[150:153], v[200:203], v[106:109]
	v_mfma_f32_16x16x32_bf16 v[94:97], v[130:133], v[208:211], v[94:97]
	v_mfma_f32_16x16x32_bf16 v[90:93], v[150:153], v[208:211], v[90:93]
	v_mfma_f32_16x16x32_bf16 v[78:81], v[130:133], v[216:219], v[78:81]
	v_mfma_f32_16x16x32_bf16 v[74:77], v[150:153], v[216:219], v[74:77]
	v_mfma_f32_16x16x32_bf16 v[126:129], v[134:137], v[196:199], v[126:129]
	v_mfma_f32_16x16x32_bf16 v[122:125], v[158:161], v[196:199], v[122:125]
	v_mfma_f32_16x16x32_bf16 v[110:113], v[134:137], v[204:207], v[110:113]
	v_mfma_f32_16x16x32_bf16 v[106:109], v[158:161], v[204:207], v[106:109]
	v_mfma_f32_16x16x32_bf16 v[94:97], v[134:137], v[212:215], v[94:97]
	v_mfma_f32_16x16x32_bf16 v[90:93], v[158:161], v[212:215], v[90:93]
	v_mfma_f32_16x16x32_bf16 v[78:81], v[134:137], v[220:223], v[78:81]
	v_mfma_f32_16x16x32_bf16 v[74:77], v[158:161], v[220:223], v[74:77]
	s_setprio 0
	s_setprio 1
	v_mfma_f32_16x16x32_bf16 v[118:121], v[164:167], v[192:195], v[118:121]
	v_mfma_f32_16x16x32_bf16 v[114:117], v[184:187], v[192:195], v[114:117]
	v_mfma_f32_16x16x32_bf16 v[102:105], v[164:167], v[200:203], v[102:105]
	v_mfma_f32_16x16x32_bf16 v[98:101], v[184:187], v[200:203], v[98:101]
	v_mfma_f32_16x16x32_bf16 v[86:89], v[164:167], v[208:211], v[86:89]
	v_mfma_f32_16x16x32_bf16 v[82:85], v[184:187], v[208:211], v[82:85]
	v_mfma_f32_16x16x32_bf16 v[70:73], v[164:167], v[216:219], v[70:73]
	v_mfma_f32_16x16x32_bf16 v[66:69], v[184:187], v[216:219], v[66:69]
	v_mfma_f32_16x16x32_bf16 v[118:121], v[180:183], v[196:199], v[118:121]
	v_mfma_f32_16x16x32_bf16 v[114:117], v[188:191], v[196:199], v[114:117]
	v_mfma_f32_16x16x32_bf16 v[102:105], v[180:183], v[204:207], v[102:105]
	v_mfma_f32_16x16x32_bf16 v[98:101], v[188:191], v[204:207], v[98:101]
	v_mfma_f32_16x16x32_bf16 v[86:89], v[180:183], v[212:215], v[86:89]
	v_mfma_f32_16x16x32_bf16 v[82:85], v[188:191], v[212:215], v[82:85]
	s_setprio 2
	s_barrier
	v_mfma_f32_16x16x32_bf16 v[70:73], v[180:183], v[220:223], v[70:73]
	v_mfma_f32_16x16x32_bf16 v[66:69], v[188:191], v[220:223], v[66:69]
	s_setprio 0
	s_add_i32 s22, s48, s9
	v_lshl_add_u64 v[154:155], v[154:155], 0, s[6:7]
	s_mov_b32 m0, s22
	ds_read_b128 v[192:195], v157 offset:49152
	ds_read_b128 v[196:199], v157 offset:50176
	ds_read_b128 v[200:203], v157 offset:51200
	ds_read_b128 v[204:207], v157 offset:52224
	ds_read_b128 v[208:211], v157 offset:53248
	ds_read_b128 v[212:215], v157 offset:54272
	ds_read_b128 v[216:219], v157 offset:55296
	ds_read_b128 v[220:223], v157 offset:56320
	global_load_lds_dwordx4 v[154:155], off
	s_add_i32 m0, s22, 0x2000
	s_add_u32 s22, s34, 0x160080
	v_lshl_add_u64 v[154:155], v[168:169], 0, s[6:7]
	s_addc_u32 s23, s35, 0
	s_add_i32 s34, s49, s9
	global_load_lds_dwordx4 v[154:155], off
	v_lshl_add_u64 v[154:155], s[22:23], 0, v[162:163]
	s_mov_b32 m0, s34
	s_nop 0
	global_load_lds_dwordx4 v[154:155], off
	v_lshl_add_u64 v[154:155], s[22:23], 0, v[142:143]
	s_add_i32 m0, s34, 0x2000
	s_nop 0
	global_load_lds_dwordx4 v[154:155], off
	v_lshl_add_u64 v[154:155], v[224:225], 0, s[6:7]
	s_mov_b32 m0, s40
	s_nop 0
	global_load_lds_dwordx4 v[154:155], off
	v_lshl_add_u64 v[154:155], v[226:227], 0, s[6:7]
	s_mov_b32 m0, s41
	s_nop 0
	global_load_lds_dwordx4 v[154:155], off
	s_waitcnt vmcnt(8)
	s_waitcnt lgkmcnt(0)
	s_barrier
	s_setprio 1
	s_waitcnt lgkmcnt(0)
	v_mfma_f32_16x16x32_bf16 v[62:65], v[130:133], v[192:195], v[62:65]
	v_mfma_f32_16x16x32_bf16 v[58:61], v[150:153], v[192:195], v[58:61]
	v_mfma_f32_16x16x32_bf16 v[46:49], v[130:133], v[200:203], v[46:49]
	v_mfma_f32_16x16x32_bf16 v[42:45], v[150:153], v[200:203], v[42:45]
	v_mfma_f32_16x16x32_bf16 v[30:33], v[130:133], v[208:211], v[30:33]
	v_mfma_f32_16x16x32_bf16 v[26:29], v[150:153], v[208:211], v[26:29]
	v_mfma_f32_16x16x32_bf16 v[14:17], v[130:133], v[216:219], v[14:17]
	v_mfma_f32_16x16x32_bf16 v[10:13], v[150:153], v[216:219], v[10:13]
	v_mfma_f32_16x16x32_bf16 v[62:65], v[134:137], v[196:199], v[62:65]
	v_mfma_f32_16x16x32_bf16 v[58:61], v[158:161], v[196:199], v[58:61]
	v_mfma_f32_16x16x32_bf16 v[46:49], v[134:137], v[204:207], v[46:49]
	v_mfma_f32_16x16x32_bf16 v[42:45], v[158:161], v[204:207], v[42:45]
	v_mfma_f32_16x16x32_bf16 v[30:33], v[134:137], v[212:215], v[30:33]
	v_mfma_f32_16x16x32_bf16 v[26:29], v[158:161], v[212:215], v[26:29]
	v_mfma_f32_16x16x32_bf16 v[14:17], v[134:137], v[220:223], v[14:17]
	v_mfma_f32_16x16x32_bf16 v[10:13], v[158:161], v[220:223], v[10:13]
	s_setprio 0
	s_setprio 1
	v_mfma_f32_16x16x32_bf16 v[54:57], v[164:167], v[192:195], v[54:57]
	v_mfma_f32_16x16x32_bf16 v[50:53], v[184:187], v[192:195], v[50:53]
	v_mfma_f32_16x16x32_bf16 v[38:41], v[164:167], v[200:203], v[38:41]
	v_mfma_f32_16x16x32_bf16 v[34:37], v[184:187], v[200:203], v[34:37]
	v_mfma_f32_16x16x32_bf16 v[22:25], v[164:167], v[208:211], v[22:25]
	v_mfma_f32_16x16x32_bf16 v[18:21], v[184:187], v[208:211], v[18:21]
	v_mfma_f32_16x16x32_bf16 v[6:9], v[164:167], v[216:219], v[6:9]
	v_mfma_f32_16x16x32_bf16 v[2:5], v[184:187], v[216:219], v[2:5]
	v_mfma_f32_16x16x32_bf16 v[54:57], v[180:183], v[196:199], v[54:57]
	v_mfma_f32_16x16x32_bf16 v[50:53], v[188:191], v[196:199], v[50:53]
	v_mfma_f32_16x16x32_bf16 v[38:41], v[180:183], v[204:207], v[38:41]
	v_mfma_f32_16x16x32_bf16 v[34:37], v[188:191], v[204:207], v[34:37]
	v_mfma_f32_16x16x32_bf16 v[22:25], v[180:183], v[212:215], v[22:25]
	v_mfma_f32_16x16x32_bf16 v[18:21], v[188:191], v[212:215], v[18:21]
	s_setprio 2
	s_barrier
	v_mfma_f32_16x16x32_bf16 v[6:9], v[180:183], v[220:223], v[6:9]
	v_mfma_f32_16x16x32_bf16 v[2:5], v[188:191], v[220:223], v[2:5]
	s_setprio 0
	s_add_i32 s47, s47, 2
	s_add_u32 s45, s45, 0x100
	s_addc_u32 s46, s46, 0
	s_cmpk_gt_u32 s47, 0x55
	s_mov_b64 s[22:23], s[28:29]
.LBB0_1874:
	s_add_u32 s28, s22, 0x100
	s_addc_u32 s29, s23, 0
	s_add_i32 s48, 0, 0x10000
	s_cmpk_eq_i32 s47, 0x54
	s_cselect_b32 s39, s5, s29
	s_cselect_b32 s38, s4, s28
	v_add_u32_e32 v154, s48, v145
	s_cselect_b32 s35, s19, s46
	s_cselect_b32 s34, s18, s45
	s_add_i32 s49, 0, 0x14000
	ds_read_b128 v[130:133], v154
	ds_read_b128 v[134:137], v154 offset:1024
	ds_read_b128 v[150:153], v154 offset:2048
	ds_read_b128 v[158:161], v154 offset:3072
	v_add_u32_e32 v154, s49, v145
	ds_read_b128 v[164:167], v154
	ds_read_b128 v[180:183], v154 offset:1024
	ds_read_b128 v[184:187], v154 offset:2048
	ds_read_b128 v[188:191], v154 offset:3072
	v_lshl_add_u64 v[154:155], s[22:23], 0, v[146:147]
	s_add_i32 m0, s20, 0xc000
	ds_read_b128 v[192:195], v157
	ds_read_b128 v[196:199], v157 offset:1024
	ds_read_b128 v[200:203], v157 offset:2048
	ds_read_b128 v[204:207], v157 offset:3072
	ds_read_b128 v[208:211], v157 offset:4096
	ds_read_b128 v[212:215], v157 offset:5120
	ds_read_b128 v[216:219], v157 offset:6144
	ds_read_b128 v[220:223], v157 offset:7168
	global_load_lds_dwordx4 v[154:155], off
	v_lshl_add_u64 v[154:155], s[22:23], 0, v[148:149]
	s_add_i32 m0, s20, 0xe000
	s_nop 0
	global_load_lds_dwordx4 v[154:155], off
	s_waitcnt vmcnt(8)
	s_waitcnt lgkmcnt(0)
	s_barrier
	s_setprio 1
	s_waitcnt lgkmcnt(0)
	v_mfma_f32_16x16x32_bf16 v[126:129], v[130:133], v[192:195], v[126:129]
	v_mfma_f32_16x16x32_bf16 v[122:125], v[150:153], v[192:195], v[122:125]
	v_mfma_f32_16x16x32_bf16 v[110:113], v[130:133], v[200:203], v[110:113]
	v_mfma_f32_16x16x32_bf16 v[106:109], v[150:153], v[200:203], v[106:109]
	v_mfma_f32_16x16x32_bf16 v[94:97], v[130:133], v[208:211], v[94:97]
	v_mfma_f32_16x16x32_bf16 v[90:93], v[150:153], v[208:211], v[90:93]
	v_mfma_f32_16x16x32_bf16 v[78:81], v[130:133], v[216:219], v[78:81]
	v_mfma_f32_16x16x32_bf16 v[74:77], v[150:153], v[216:219], v[74:77]
	v_mfma_f32_16x16x32_bf16 v[126:129], v[134:137], v[196:199], v[126:129]
	v_mfma_f32_16x16x32_bf16 v[122:125], v[158:161], v[196:199], v[122:125]
	v_mfma_f32_16x16x32_bf16 v[110:113], v[134:137], v[204:207], v[110:113]
	v_mfma_f32_16x16x32_bf16 v[106:109], v[158:161], v[204:207], v[106:109]
	v_mfma_f32_16x16x32_bf16 v[94:97], v[134:137], v[212:215], v[94:97]
	v_mfma_f32_16x16x32_bf16 v[90:93], v[158:161], v[212:215], v[90:93]
	v_mfma_f32_16x16x32_bf16 v[78:81], v[134:137], v[220:223], v[78:81]
	v_mfma_f32_16x16x32_bf16 v[74:77], v[158:161], v[220:223], v[74:77]
	s_setprio 0
	s_setprio 1
	v_mfma_f32_16x16x32_bf16 v[118:121], v[164:167], v[192:195], v[118:121]
	v_mfma_f32_16x16x32_bf16 v[114:117], v[184:187], v[192:195], v[114:117]
	v_mfma_f32_16x16x32_bf16 v[102:105], v[164:167], v[200:203], v[102:105]
	v_mfma_f32_16x16x32_bf16 v[98:101], v[184:187], v[200:203], v[98:101]
	v_mfma_f32_16x16x32_bf16 v[86:89], v[164:167], v[208:211], v[86:89]
	v_mfma_f32_16x16x32_bf16 v[82:85], v[184:187], v[208:211], v[82:85]
	v_mfma_f32_16x16x32_bf16 v[70:73], v[164:167], v[216:219], v[70:73]
	v_mfma_f32_16x16x32_bf16 v[66:69], v[184:187], v[216:219], v[66:69]
	v_mfma_f32_16x16x32_bf16 v[118:121], v[180:183], v[196:199], v[118:121]
	v_mfma_f32_16x16x32_bf16 v[114:117], v[188:191], v[196:199], v[114:117]
	v_mfma_f32_16x16x32_bf16 v[102:105], v[180:183], v[204:207], v[102:105]
	v_mfma_f32_16x16x32_bf16 v[98:101], v[188:191], v[204:207], v[98:101]
	v_mfma_f32_16x16x32_bf16 v[86:89], v[180:183], v[212:215], v[86:89]
	v_mfma_f32_16x16x32_bf16 v[82:85], v[188:191], v[212:215], v[82:85]
	s_setprio 2
	s_barrier
	v_mfma_f32_16x16x32_bf16 v[70:73], v[180:183], v[220:223], v[70:73]
	v_mfma_f32_16x16x32_bf16 v[66:69], v[188:191], v[220:223], v[66:69]
	s_setprio 0
	s_add_i32 s22, s48, s9
	v_lshl_add_u64 v[154:155], s[34:35], 0, v[162:163]
	s_mov_b32 m0, s22
	ds_read_b128 v[192:195], v157 offset:16384
	ds_read_b128 v[196:199], v157 offset:17408
	ds_read_b128 v[200:203], v157 offset:18432
	ds_read_b128 v[204:207], v157 offset:19456
	ds_read_b128 v[208:211], v157 offset:20480
	ds_read_b128 v[212:215], v157 offset:21504
	ds_read_b128 v[216:219], v157 offset:22528
	ds_read_b128 v[220:223], v157 offset:23552
	global_load_lds_dwordx4 v[154:155], off
	s_add_i32 m0, s22, 0x2000
	s_add_u32 s22, s34, 0x160000
	v_lshl_add_u64 v[168:169], s[34:35], 0, v[142:143]
	s_addc_u32 s23, s35, 0
	s_add_i32 s48, s49, s9
	global_load_lds_dwordx4 v[168:169], off
	v_lshl_add_u64 v[224:225], s[22:23], 0, v[162:163]
	s_mov_b32 m0, s48
	v_lshl_add_u64 v[226:227], s[38:39], 0, v[140:141]
	global_load_lds_dwordx4 v[224:225], off
	v_lshl_add_u64 v[224:225], s[22:23], 0, v[142:143]
	s_add_i32 m0, s48, 0x2000
	s_nop 0
	global_load_lds_dwordx4 v[224:225], off
	v_lshl_add_u64 v[224:225], s[38:39], 0, v[138:139]
	s_mov_b32 m0, s20
	s_nop 0
	global_load_lds_dwordx4 v[224:225], off
	s_mov_b32 m0, s25
	s_nop 0
	global_load_lds_dwordx4 v[226:227], off
	s_waitcnt vmcnt(8)
	s_waitcnt lgkmcnt(0)
	s_barrier
	s_setprio 1
	s_waitcnt lgkmcnt(0)
	v_mfma_f32_16x16x32_bf16 v[62:65], v[130:133], v[192:195], v[62:65]
	v_mfma_f32_16x16x32_bf16 v[58:61], v[150:153], v[192:195], v[58:61]
	v_mfma_f32_16x16x32_bf16 v[46:49], v[130:133], v[200:203], v[46:49]
	v_mfma_f32_16x16x32_bf16 v[42:45], v[150:153], v[200:203], v[42:45]
	v_mfma_f32_16x16x32_bf16 v[30:33], v[130:133], v[208:211], v[30:33]
	v_mfma_f32_16x16x32_bf16 v[26:29], v[150:153], v[208:211], v[26:29]
	v_mfma_f32_16x16x32_bf16 v[14:17], v[130:133], v[216:219], v[14:17]
	v_mfma_f32_16x16x32_bf16 v[10:13], v[150:153], v[216:219], v[10:13]
	v_mfma_f32_16x16x32_bf16 v[62:65], v[134:137], v[196:199], v[62:65]
	v_mfma_f32_16x16x32_bf16 v[58:61], v[158:161], v[196:199], v[58:61]
	v_mfma_f32_16x16x32_bf16 v[46:49], v[134:137], v[204:207], v[46:49]
	v_mfma_f32_16x16x32_bf16 v[42:45], v[158:161], v[204:207], v[42:45]
	v_mfma_f32_16x16x32_bf16 v[30:33], v[134:137], v[212:215], v[30:33]
	v_mfma_f32_16x16x32_bf16 v[26:29], v[158:161], v[212:215], v[26:29]
	v_mfma_f32_16x16x32_bf16 v[14:17], v[134:137], v[220:223], v[14:17]
	v_mfma_f32_16x16x32_bf16 v[10:13], v[158:161], v[220:223], v[10:13]
	s_setprio 0
	s_setprio 1
	v_mfma_f32_16x16x32_bf16 v[54:57], v[164:167], v[192:195], v[54:57]
	v_mfma_f32_16x16x32_bf16 v[50:53], v[184:187], v[192:195], v[50:53]
	v_mfma_f32_16x16x32_bf16 v[38:41], v[164:167], v[200:203], v[38:41]
	v_mfma_f32_16x16x32_bf16 v[34:37], v[184:187], v[200:203], v[34:37]
	v_mfma_f32_16x16x32_bf16 v[22:25], v[164:167], v[208:211], v[22:25]
	v_mfma_f32_16x16x32_bf16 v[18:21], v[184:187], v[208:211], v[18:21]
	v_mfma_f32_16x16x32_bf16 v[6:9], v[164:167], v[216:219], v[6:9]
	v_mfma_f32_16x16x32_bf16 v[2:5], v[184:187], v[216:219], v[2:5]
	v_mfma_f32_16x16x32_bf16 v[54:57], v[180:183], v[196:199], v[54:57]
	v_mfma_f32_16x16x32_bf16 v[50:53], v[188:191], v[196:199], v[50:53]
	v_mfma_f32_16x16x32_bf16 v[38:41], v[180:183], v[204:207], v[38:41]
	v_mfma_f32_16x16x32_bf16 v[34:37], v[188:191], v[204:207], v[34:37]
	v_mfma_f32_16x16x32_bf16 v[22:25], v[180:183], v[212:215], v[22:25]
	v_mfma_f32_16x16x32_bf16 v[18:21], v[188:191], v[212:215], v[18:21]
	s_setprio 2
	s_barrier
	v_mfma_f32_16x16x32_bf16 v[6:9], v[180:183], v[220:223], v[6:9]
	v_mfma_f32_16x16x32_bf16 v[2:5], v[188:191], v[220:223], v[2:5]
	s_setprio 0
	s_add_i32 s48, 0, 0x18000
	s_add_i32 s49, 0, 0x1c000
	v_add_u32_e32 v158, s48, v145
	v_add_u32_e32 v179, s49, v145
	ds_read_b128 v[130:133], v158
	ds_read_b128 v[134:137], v158 offset:1024
	ds_read_b128 v[150:153], v158 offset:2048
	ds_read_b128 v[158:161], v158 offset:3072
	ds_read_b128 v[164:167], v179
	ds_read_b128 v[180:183], v179 offset:1024
	ds_read_b128 v[184:187], v179 offset:2048
	ds_read_b128 v[188:191], v179 offset:3072
	s_add_u32 s22, s38, 0x160000
	s_addc_u32 s23, s39, 0
	s_mov_b32 m0, s26
	v_lshl_add_u64 v[228:229], s[22:23], 0, v[138:139]
	ds_read_b128 v[192:195], v157 offset:32768
	ds_read_b128 v[196:199], v157 offset:33792
	ds_read_b128 v[200:203], v157 offset:34816
	ds_read_b128 v[204:207], v157 offset:35840
	ds_read_b128 v[208:211], v157 offset:36864
	ds_read_b128 v[212:215], v157 offset:37888
	ds_read_b128 v[216:219], v157 offset:38912
	ds_read_b128 v[220:223], v157 offset:39936
	global_load_lds_dwordx4 v[228:229], off
	v_lshl_add_u64 v[228:229], s[22:23], 0, v[140:141]
	s_mov_b32 m0, s27
	s_nop 0
	global_load_lds_dwordx4 v[228:229], off
	s_waitcnt vmcnt(8)
	s_waitcnt lgkmcnt(0)
	s_barrier
	s_setprio 1
	s_waitcnt lgkmcnt(0)
	v_mfma_f32_16x16x32_bf16 v[126:129], v[130:133], v[192:195], v[126:129]
	v_mfma_f32_16x16x32_bf16 v[122:125], v[150:153], v[192:195], v[122:125]
	v_mfma_f32_16x16x32_bf16 v[110:113], v[130:133], v[200:203], v[110:113]
	v_mfma_f32_16x16x32_bf16 v[106:109], v[150:153], v[200:203], v[106:109]
	v_mfma_f32_16x16x32_bf16 v[94:97], v[130:133], v[208:211], v[94:97]
	v_mfma_f32_16x16x32_bf16 v[90:93], v[150:153], v[208:211], v[90:93]
	v_mfma_f32_16x16x32_bf16 v[78:81], v[130:133], v[216:219], v[78:81]
	v_mfma_f32_16x16x32_bf16 v[74:77], v[150:153], v[216:219], v[74:77]
	v_mfma_f32_16x16x32_bf16 v[126:129], v[134:137], v[196:199], v[126:129]
	v_mfma_f32_16x16x32_bf16 v[122:125], v[158:161], v[196:199], v[122:125]
	v_mfma_f32_16x16x32_bf16 v[110:113], v[134:137], v[204:207], v[110:113]
	v_mfma_f32_16x16x32_bf16 v[106:109], v[158:161], v[204:207], v[106:109]
	v_mfma_f32_16x16x32_bf16 v[94:97], v[134:137], v[212:215], v[94:97]
	v_mfma_f32_16x16x32_bf16 v[90:93], v[158:161], v[212:215], v[90:93]
	v_mfma_f32_16x16x32_bf16 v[78:81], v[134:137], v[220:223], v[78:81]
	v_mfma_f32_16x16x32_bf16 v[74:77], v[158:161], v[220:223], v[74:77]
	s_setprio 0
	s_setprio 1
	v_mfma_f32_16x16x32_bf16 v[118:121], v[164:167], v[192:195], v[118:121]
	v_mfma_f32_16x16x32_bf16 v[114:117], v[184:187], v[192:195], v[114:117]
	v_mfma_f32_16x16x32_bf16 v[102:105], v[164:167], v[200:203], v[102:105]
	v_mfma_f32_16x16x32_bf16 v[98:101], v[184:187], v[200:203], v[98:101]
	v_mfma_f32_16x16x32_bf16 v[86:89], v[164:167], v[208:211], v[86:89]
	v_mfma_f32_16x16x32_bf16 v[82:85], v[184:187], v[208:211], v[82:85]
	v_mfma_f32_16x16x32_bf16 v[70:73], v[164:167], v[216:219], v[70:73]
	v_mfma_f32_16x16x32_bf16 v[66:69], v[184:187], v[216:219], v[66:69]
	v_mfma_f32_16x16x32_bf16 v[118:121], v[180:183], v[196:199], v[118:121]
	v_mfma_f32_16x16x32_bf16 v[114:117], v[188:191], v[196:199], v[114:117]
	v_mfma_f32_16x16x32_bf16 v[102:105], v[180:183], v[204:207], v[102:105]
	v_mfma_f32_16x16x32_bf16 v[98:101], v[188:191], v[204:207], v[98:101]
	v_mfma_f32_16x16x32_bf16 v[86:89], v[180:183], v[212:215], v[86:89]
	v_mfma_f32_16x16x32_bf16 v[82:85], v[188:191], v[212:215], v[82:85]
	s_setprio 2
	s_barrier
	v_mfma_f32_16x16x32_bf16 v[70:73], v[180:183], v[220:223], v[70:73]
	v_mfma_f32_16x16x32_bf16 v[66:69], v[188:191], v[220:223], v[66:69]
	s_setprio 0
	s_add_i32 s22, s48, s9
	v_lshl_add_u64 v[154:155], v[154:155], 0, s[6:7]
	s_mov_b32 m0, s22
	ds_read_b128 v[192:195], v157 offset:49152
	ds_read_b128 v[196:199], v157 offset:50176
	ds_read_b128 v[200:203], v157 offset:51200
	ds_read_b128 v[204:207], v157 offset:52224
	ds_read_b128 v[208:211], v157 offset:53248
	ds_read_b128 v[212:215], v157 offset:54272
	ds_read_b128 v[216:219], v157 offset:55296
	ds_read_b128 v[220:223], v157 offset:56320
	global_load_lds_dwordx4 v[154:155], off
	s_add_i32 m0, s22, 0x2000
	s_add_u32 s22, s34, 0x160080
	v_lshl_add_u64 v[154:155], v[168:169], 0, s[6:7]
	s_addc_u32 s23, s35, 0
	s_add_i32 s34, s49, s9
	global_load_lds_dwordx4 v[154:155], off
	v_lshl_add_u64 v[154:155], s[22:23], 0, v[162:163]
	s_mov_b32 m0, s34
	s_nop 0
	global_load_lds_dwordx4 v[154:155], off
	v_lshl_add_u64 v[154:155], s[22:23], 0, v[142:143]
	s_add_i32 m0, s34, 0x2000
	s_nop 0
	global_load_lds_dwordx4 v[154:155], off
	v_lshl_add_u64 v[154:155], v[224:225], 0, s[6:7]
	s_mov_b32 m0, s40
	s_nop 0
	global_load_lds_dwordx4 v[154:155], off
	v_lshl_add_u64 v[154:155], v[226:227], 0, s[6:7]
	s_mov_b32 m0, s41
	s_nop 0
	global_load_lds_dwordx4 v[154:155], off
	s_waitcnt vmcnt(8)
	s_waitcnt lgkmcnt(0)
	s_barrier
	s_setprio 1
	s_waitcnt lgkmcnt(0)
	v_mfma_f32_16x16x32_bf16 v[62:65], v[130:133], v[192:195], v[62:65]
	v_mfma_f32_16x16x32_bf16 v[58:61], v[150:153], v[192:195], v[58:61]
	v_mfma_f32_16x16x32_bf16 v[46:49], v[130:133], v[200:203], v[46:49]
	v_mfma_f32_16x16x32_bf16 v[42:45], v[150:153], v[200:203], v[42:45]
	v_mfma_f32_16x16x32_bf16 v[30:33], v[130:133], v[208:211], v[30:33]
	v_mfma_f32_16x16x32_bf16 v[26:29], v[150:153], v[208:211], v[26:29]
	v_mfma_f32_16x16x32_bf16 v[14:17], v[130:133], v[216:219], v[14:17]
	v_mfma_f32_16x16x32_bf16 v[10:13], v[150:153], v[216:219], v[10:13]
	v_mfma_f32_16x16x32_bf16 v[62:65], v[134:137], v[196:199], v[62:65]
	v_mfma_f32_16x16x32_bf16 v[58:61], v[158:161], v[196:199], v[58:61]
	v_mfma_f32_16x16x32_bf16 v[46:49], v[134:137], v[204:207], v[46:49]
	v_mfma_f32_16x16x32_bf16 v[42:45], v[158:161], v[204:207], v[42:45]
	v_mfma_f32_16x16x32_bf16 v[30:33], v[134:137], v[212:215], v[30:33]
	v_mfma_f32_16x16x32_bf16 v[26:29], v[158:161], v[212:215], v[26:29]
	v_mfma_f32_16x16x32_bf16 v[14:17], v[134:137], v[220:223], v[14:17]
	v_mfma_f32_16x16x32_bf16 v[10:13], v[158:161], v[220:223], v[10:13]
	s_setprio 0
	s_setprio 1
	v_mfma_f32_16x16x32_bf16 v[54:57], v[164:167], v[192:195], v[54:57]
	v_mfma_f32_16x16x32_bf16 v[50:53], v[184:187], v[192:195], v[50:53]
	v_mfma_f32_16x16x32_bf16 v[38:41], v[164:167], v[200:203], v[38:41]
	v_mfma_f32_16x16x32_bf16 v[34:37], v[184:187], v[200:203], v[34:37]
	v_mfma_f32_16x16x32_bf16 v[22:25], v[164:167], v[208:211], v[22:25]
	v_mfma_f32_16x16x32_bf16 v[18:21], v[184:187], v[208:211], v[18:21]
	v_mfma_f32_16x16x32_bf16 v[6:9], v[164:167], v[216:219], v[6:9]
	v_mfma_f32_16x16x32_bf16 v[2:5], v[184:187], v[216:219], v[2:5]
	v_mfma_f32_16x16x32_bf16 v[54:57], v[180:183], v[196:199], v[54:57]
	v_mfma_f32_16x16x32_bf16 v[50:53], v[188:191], v[196:199], v[50:53]
	v_mfma_f32_16x16x32_bf16 v[38:41], v[180:183], v[204:207], v[38:41]
	v_mfma_f32_16x16x32_bf16 v[34:37], v[188:191], v[204:207], v[34:37]
	v_mfma_f32_16x16x32_bf16 v[22:25], v[180:183], v[212:215], v[22:25]
	v_mfma_f32_16x16x32_bf16 v[18:21], v[188:191], v[212:215], v[18:21]
	s_setprio 2
	s_barrier
	v_mfma_f32_16x16x32_bf16 v[6:9], v[180:183], v[220:223], v[6:9]
	v_mfma_f32_16x16x32_bf16 v[2:5], v[188:191], v[220:223], v[2:5]
	s_setprio 0
	s_add_i32 s47, s47, 2
	s_add_u32 s45, s45, 0x100
	s_addc_u32 s46, s46, 0
	s_cmpk_gt_u32 s47, 0x55
	s_mov_b64 s[22:23], s[28:29]
	s_cbranch_scc0 .LBB0_1874
	s_and_b64 vcc, exec, s[2:3]
	s_cbranch_vccz .LBB0_1877
	s_barrier
